# GEMM loops: loader (LDS-read + DMA) phase runs at s_setprio 3, MFMA phase stays at 1
# speedup vs baseline: 1.0039x; 1.0039x over previous
; #define PG8_STAGE(bufoff, gbase, voff) do { _Pragma("unroll") for (int _i = 0; _i < 2; ++_i) \
;         __builtin_amdgcn_global_load_lds((const unsigned*)((const char*)(gbase) + (voff)[_i]), (LAS unsigned*)(lds + (bufoff) + ldsw + _i * 8192), 16, 0, 0); } while (0)
; #define PG8_LDA(dst, b, h) do { _Pragma("unroll") for (int m = 0; m < 4; ++m) _Pragma("unroll") for (int k = 0; k < 2; ++k) dst[m][k] = *(const LAS bf16x8*)(lds + PG8_SA(b, h) + aoff + m * 2048 + k * 1024); } while (0)
; #define PG8_LDB(dst, b, h) do { _Pragma("unroll") for (int n = 0; n < 2; ++n) _Pragma("unroll") for (int k = 0; k < 2; ++k) dst[n][k] = *(const LAS bf16x8*)(lds + PG8_SB(b, h) + boff + n * 2048 + k * 1024); } while (0)
; #define PG8_MMA(ai, bj, At, Bt) do { __builtin_amdgcn_s_setprio(1); _Pragma("unroll") for (int m = 0; m < 4; ++m) _Pragma("unroll") for (int n = 0; n < 2; ++n) _Pragma("unroll") for (int k = 0; k < 2; ++k) \
;         acc[ai][bj][m][n] = __builtin_amdgcn_mfma_f32_16x16x32_bf16(Bt[n][k], At[m][k], acc[ai][bj][m][n], 0, 0, 0); __builtin_amdgcn_s_setprio(0); } while (0)
; #define PG8_WAIT_V(n) asm volatile("s_waitcnt vmcnt(" #n ")" ::: "memory")
; #define PG8_WAIT_L(n) asm volatile("s_waitcnt lgkmcnt(" #n ")" ::: "memory")
; #define PG8_BAR __builtin_amdgcn_s_barrier()
; #define PG8_SCHED __builtin_amdgcn_sched_barrier(0)
; template <class Epi>
; __device__ __forceinline__ void gemm_phase(LAS unsigned char* lds, const Gemm g, const StaticOrder& S, const Epi& E) {
;     ...
;             PG8_LDB(B0, 0, 0); PG8_LDB(B1, 0, 1); PG8_SCHED; PG8_LDA(At, 0, 0); PG8_STAGE(PG8_SA(1, 1), a1 + hsA, voffA);
;             PG8_WAIT_V(8); PG8_WAIT_L(0); PG8_BAR; PG8_MMA(0, 0, At, B0); PG8_MMA(0, 1, At, B1); PG8_BAR; PG8_SCHED;
;             PG8_LDA(At, 0, 1); PG8_STAGE(PG8_SB(0, 0), b2, voffB); PG8_STAGE(PG8_SB(0, 1), b2 + hsB, voffB); PG8_STAGE(PG8_SA(0, 0), a2, voffA);
;             PG8_WAIT_V(8); PG8_WAIT_L(0); PG8_BAR; PG8_MMA(1, 0, At, B0); PG8_MMA(1, 1, At, B1); PG8_BAR; PG8_SCHED;
.LBB0_214:
	ds_read_b128 v[144:147], v155
	ds_read_b128 v[148:151], v155 offset:1024
	ds_read_b128 v[162:165], v155 offset:2048
	ds_read_b128 v[166:169], v155 offset:3072
	ds_read_b128 v[180:183], v156
	ds_read_b128 v[184:187], v156 offset:1024
	ds_read_b128 v[188:191], v156 offset:2048
	ds_read_b128 v[192:195], v156 offset:3072
	s_add_u32 s38, s58, 0xfffc0080
	s_addc_u32 s39, s59, -1
	s_cmp_eq_u32 s37, 12
	s_cselect_b32 s63, s6, s39
	s_cselect_b32 s62, s7, s38
	s_cselect_b32 s61, s11, s36
	s_cselect_b32 s60, s13, s35
	v_lshl_add_u64 v[170:171], s[58:59], 0, v[136:137]
	s_add_i32 m0, s19, 0xc000
	ds_read_b128 v[196:199], v157
	ds_read_b128 v[200:203], v157 offset:1024
	ds_read_b128 v[204:207], v157 offset:2048
	ds_read_b128 v[208:211], v157 offset:3072
	ds_read_b128 v[212:215], v157 offset:4096
	ds_read_b128 v[216:219], v157 offset:5120
	ds_read_b128 v[220:223], v157 offset:6144
	ds_read_b128 v[224:227], v157 offset:7168
	global_load_lds_dwordx4 v[170:171], off
	v_lshl_add_u64 v[170:171], s[58:59], 0, v[138:139]
	s_add_i32 m0, s19, 0xe000
	s_nop 0
	global_load_lds_dwordx4 v[170:171], off
	s_waitcnt vmcnt(8)
	s_waitcnt lgkmcnt(0)
	s_barrier
	s_setprio 1
	s_waitcnt lgkmcnt(0)
	v_mfma_f32_16x16x32_bf16 v[124:127], v[144:147], v[196:199], v[124:127]
	v_mfma_f32_16x16x32_bf16 v[120:123], v[162:165], v[196:199], v[120:123]
	v_mfma_f32_16x16x32_bf16 v[108:111], v[144:147], v[204:207], v[108:111]
	v_mfma_f32_16x16x32_bf16 v[104:107], v[162:165], v[204:207], v[104:107]
	v_mfma_f32_16x16x32_bf16 v[92:95], v[144:147], v[212:215], v[92:95]
	v_mfma_f32_16x16x32_bf16 v[88:91], v[162:165], v[212:215], v[88:91]
	v_mfma_f32_16x16x32_bf16 v[76:79], v[144:147], v[220:223], v[76:79]
	v_mfma_f32_16x16x32_bf16 v[72:75], v[162:165], v[220:223], v[72:75]
	v_mfma_f32_16x16x32_bf16 v[124:127], v[148:151], v[200:203], v[124:127]
	v_mfma_f32_16x16x32_bf16 v[120:123], v[166:169], v[200:203], v[120:123]
	v_mfma_f32_16x16x32_bf16 v[108:111], v[148:151], v[208:211], v[108:111]
	v_mfma_f32_16x16x32_bf16 v[104:107], v[166:169], v[208:211], v[104:107]
	v_mfma_f32_16x16x32_bf16 v[92:95], v[148:151], v[216:219], v[92:95]
	v_mfma_f32_16x16x32_bf16 v[88:91], v[166:169], v[216:219], v[88:91]
	v_mfma_f32_16x16x32_bf16 v[76:79], v[148:151], v[224:227], v[76:79]
	v_mfma_f32_16x16x32_bf16 v[72:75], v[166:169], v[224:227], v[72:75]
	s_setprio 0
	s_setprio 1
	v_mfma_f32_16x16x32_bf16 v[116:119], v[180:183], v[196:199], v[116:119]
	v_mfma_f32_16x16x32_bf16 v[112:115], v[188:191], v[196:199], v[112:115]
	v_mfma_f32_16x16x32_bf16 v[100:103], v[180:183], v[204:207], v[100:103]
	v_mfma_f32_16x16x32_bf16 v[96:99], v[188:191], v[204:207], v[96:99]
	v_mfma_f32_16x16x32_bf16 v[84:87], v[180:183], v[212:215], v[84:87]
	v_mfma_f32_16x16x32_bf16 v[80:83], v[188:191], v[212:215], v[80:83]
	v_mfma_f32_16x16x32_bf16 v[68:71], v[180:183], v[220:223], v[68:71]
	v_mfma_f32_16x16x32_bf16 v[64:67], v[188:191], v[220:223], v[64:67]
	v_mfma_f32_16x16x32_bf16 v[116:119], v[184:187], v[200:203], v[116:119]
	v_mfma_f32_16x16x32_bf16 v[112:115], v[192:195], v[200:203], v[112:115]
	v_mfma_f32_16x16x32_bf16 v[100:103], v[184:187], v[208:211], v[100:103]
	v_mfma_f32_16x16x32_bf16 v[96:99], v[192:195], v[208:211], v[96:99]
	v_mfma_f32_16x16x32_bf16 v[84:87], v[184:187], v[216:219], v[84:87]
	v_mfma_f32_16x16x32_bf16 v[80:83], v[192:195], v[216:219], v[80:83]
	v_mfma_f32_16x16x32_bf16 v[68:71], v[184:187], v[224:227], v[68:71]
	v_mfma_f32_16x16x32_bf16 v[64:67], v[192:195], v[224:227], v[64:67]
	s_setprio 3
	s_barrier
	s_add_i32 s38, s30, s16
	v_lshl_add_u64 v[170:171], s[60:61], 0, v[132:133]
	s_mov_b32 m0, s38
	ds_read_b128 v[196:199], v157 offset:16384
	ds_read_b128 v[200:203], v157 offset:17408
	ds_read_b128 v[204:207], v157 offset:18432
	ds_read_b128 v[208:211], v157 offset:19456
	ds_read_b128 v[212:215], v157 offset:20480
	ds_read_b128 v[216:219], v157 offset:21504
	ds_read_b128 v[220:223], v157 offset:22528
	ds_read_b128 v[224:227], v157 offset:23552
	global_load_lds_dwordx4 v[170:171], off
	s_add_i32 m0, s38, 0x2000
	s_add_u32 s38, s60, 0x40000
	v_lshl_add_u64 v[228:229], s[60:61], 0, v[128:129]
	s_addc_u32 s39, s61, 0
	s_add_i32 s40, s31, s16
	global_load_lds_dwordx4 v[228:229], off
	v_lshl_add_u64 v[230:231], s[38:39], 0, v[132:133]
	s_mov_b32 m0, s40
	v_lshl_add_u64 v[232:233], s[62:63], 0, v[130:131]
	global_load_lds_dwordx4 v[230:231], off
	v_lshl_add_u64 v[230:231], s[38:39], 0, v[128:129]
	s_add_i32 m0, s40, 0x2000
	s_nop 0
	global_load_lds_dwordx4 v[230:231], off
	v_lshl_add_u64 v[230:231], s[62:63], 0, v[134:135]
	s_mov_b32 m0, s19
	s_nop 0
	global_load_lds_dwordx4 v[230:231], off
	s_mov_b32 m0, s22
	s_nop 0
	global_load_lds_dwordx4 v[232:233], off
	s_waitcnt vmcnt(8)
	s_waitcnt lgkmcnt(0)
	s_barrier
; #define PG8_STAGE(bufoff, gbase, voff) do { _Pragma("unroll") for (int _i = 0; _i < 2; ++_i) \
;         __builtin_amdgcn_global_load_lds((const unsigned*)((const char*)(gbase) + (voff)[_i]), (LAS unsigned*)(lds + (bufoff) + ldsw + _i * 8192), 16, 0, 0); } while (0)
; #define PG8_LDA(dst, b, h) do { _Pragma("unroll") for (int m = 0; m < 4; ++m) _Pragma("unroll") for (int k = 0; k < 2; ++k) dst[m][k] = *(const LAS bf16x8*)(lds + PG8_SA(b, h) + aoff + m * 2048 + k * 1024); } while (0)
; #define PG8_LDB(dst, b, h) do { _Pragma("unroll") for (int n = 0; n < 2; ++n) _Pragma("unroll") for (int k = 0; k < 2; ++k) dst[n][k] = *(const LAS bf16x8*)(lds + PG8_SB(b, h) + boff + n * 2048 + k * 1024); } while (0)
; #define PG8_MMA(ai, bj, At, Bt) do { __builtin_amdgcn_s_setprio(1); _Pragma("unroll") for (int m = 0; m < 4; ++m) _Pragma("unroll") for (int n = 0; n < 2; ++n) _Pragma("unroll") for (int k = 0; k < 2; ++k) \
;         acc[ai][bj][m][n] = __builtin_amdgcn_mfma_f32_16x16x32_bf16(Bt[n][k], At[m][k], acc[ai][bj][m][n], 0, 0, 0); __builtin_amdgcn_s_setprio(0); } while (0)
; #define PG8_WAIT_V(n) asm volatile("s_waitcnt vmcnt(" #n ")" ::: "memory")
; #define PG8_WAIT_L(n) asm volatile("s_waitcnt lgkmcnt(" #n ")" ::: "memory")
; #define PG8_BAR __builtin_amdgcn_s_barrier()
; #define PG8_SCHED __builtin_amdgcn_sched_barrier(0)
; template <class Epi>
; __device__ __forceinline__ void gemm_phase(LAS unsigned char* lds, const Gemm g, const StaticOrder& S, const Epi& E) {
;     ...
;             PG8_WAIT_V(8); PG8_WAIT_L(0); PG8_BAR; PG8_MMA(1, 0, At, B0); PG8_MMA(1, 1, At, B1); PG8_BAR; PG8_SCHED;
;             PG8_LDB(B0, 1, 0); PG8_LDB(B1, 1, 1); PG8_SCHED; PG8_LDA(At, 1, 0); PG8_STAGE(PG8_SA(0, 1), a2 + hsA, voffA);
;             PG8_WAIT_V(8); PG8_WAIT_L(0); PG8_BAR; PG8_MMA(0, 0, At, B0); PG8_MMA(0, 1, At, B1); PG8_BAR; PG8_SCHED;
	s_setprio 1
	s_waitcnt lgkmcnt(0)
	v_mfma_f32_16x16x32_bf16 v[60:63], v[144:147], v[196:199], v[60:63]
	v_mfma_f32_16x16x32_bf16 v[56:59], v[162:165], v[196:199], v[56:59]
	v_mfma_f32_16x16x32_bf16 v[44:47], v[144:147], v[204:207], v[44:47]
	v_mfma_f32_16x16x32_bf16 v[40:43], v[162:165], v[204:207], v[40:43]
	v_mfma_f32_16x16x32_bf16 v[28:31], v[144:147], v[212:215], v[28:31]
	v_mfma_f32_16x16x32_bf16 v[24:27], v[162:165], v[212:215], v[24:27]
	v_mfma_f32_16x16x32_bf16 v[12:15], v[144:147], v[220:223], v[12:15]
	v_mfma_f32_16x16x32_bf16 v[8:11], v[162:165], v[220:223], v[8:11]
	v_mfma_f32_16x16x32_bf16 v[60:63], v[148:151], v[200:203], v[60:63]
	v_mfma_f32_16x16x32_bf16 v[56:59], v[166:169], v[200:203], v[56:59]
	v_mfma_f32_16x16x32_bf16 v[44:47], v[148:151], v[208:211], v[44:47]
	v_mfma_f32_16x16x32_bf16 v[40:43], v[166:169], v[208:211], v[40:43]
	v_mfma_f32_16x16x32_bf16 v[28:31], v[148:151], v[216:219], v[28:31]
	v_mfma_f32_16x16x32_bf16 v[24:27], v[166:169], v[216:219], v[24:27]
	v_mfma_f32_16x16x32_bf16 v[12:15], v[148:151], v[224:227], v[12:15]
	v_mfma_f32_16x16x32_bf16 v[8:11], v[166:169], v[224:227], v[8:11]
	s_setprio 0
	s_setprio 1
	v_mfma_f32_16x16x32_bf16 v[52:55], v[180:183], v[196:199], v[52:55]
	v_mfma_f32_16x16x32_bf16 v[48:51], v[188:191], v[196:199], v[48:51]
	v_mfma_f32_16x16x32_bf16 v[36:39], v[180:183], v[204:207], v[36:39]
	v_mfma_f32_16x16x32_bf16 v[32:35], v[188:191], v[204:207], v[32:35]
	v_mfma_f32_16x16x32_bf16 v[20:23], v[180:183], v[212:215], v[20:23]
	v_mfma_f32_16x16x32_bf16 v[16:19], v[188:191], v[212:215], v[16:19]
	v_mfma_f32_16x16x32_bf16 v[4:7], v[180:183], v[220:223], v[4:7]
	v_mfma_f32_16x16x32_bf16 v[0:3], v[188:191], v[220:223], v[0:3]
	v_mfma_f32_16x16x32_bf16 v[52:55], v[184:187], v[200:203], v[52:55]
	v_mfma_f32_16x16x32_bf16 v[48:51], v[192:195], v[200:203], v[48:51]
	v_mfma_f32_16x16x32_bf16 v[36:39], v[184:187], v[208:211], v[36:39]
	v_mfma_f32_16x16x32_bf16 v[32:35], v[192:195], v[208:211], v[32:35]
	v_mfma_f32_16x16x32_bf16 v[20:23], v[184:187], v[216:219], v[20:23]
	v_mfma_f32_16x16x32_bf16 v[16:19], v[192:195], v[216:219], v[16:19]
	v_mfma_f32_16x16x32_bf16 v[4:7], v[184:187], v[224:227], v[4:7]
	v_mfma_f32_16x16x32_bf16 v[0:3], v[192:195], v[224:227], v[0:3]
	s_setprio 3
	s_barrier
	s_add_i32 s40, 0, 0x18000
	v_add_u32_e32 v159, s40, v153
	s_add_i32 s41, 0, 0x1c000
	ds_read_b128 v[144:147], v159
	ds_read_b128 v[148:151], v159 offset:1024
	ds_read_b128 v[162:165], v159 offset:2048
	ds_read_b128 v[166:169], v159 offset:3072
	v_add_u32_e32 v159, s41, v153
	ds_read_b128 v[180:183], v159
	ds_read_b128 v[184:187], v159 offset:1024
	ds_read_b128 v[188:191], v159 offset:2048
	ds_read_b128 v[192:195], v159 offset:3072
	s_add_u32 s38, s62, 0x40000
	s_addc_u32 s39, s63, 0
	s_mov_b32 m0, s23
	v_lshl_add_u64 v[234:235], s[38:39], 0, v[134:135]
	ds_read_b128 v[196:199], v157 offset:32768
	ds_read_b128 v[200:203], v157 offset:33792
	ds_read_b128 v[204:207], v157 offset:34816
	ds_read_b128 v[208:211], v157 offset:35840
	ds_read_b128 v[212:215], v157 offset:36864
	ds_read_b128 v[216:219], v157 offset:37888
	ds_read_b128 v[220:223], v157 offset:38912
	ds_read_b128 v[224:227], v157 offset:39936
	global_load_lds_dwordx4 v[234:235], off
	v_lshl_add_u64 v[234:235], s[38:39], 0, v[130:131]
	s_mov_b32 m0, s24
	s_nop 0
	global_load_lds_dwordx4 v[234:235], off
	s_waitcnt vmcnt(8)
	s_waitcnt lgkmcnt(0)
	s_barrier
	s_setprio 1
	s_waitcnt lgkmcnt(0)
	v_mfma_f32_16x16x32_bf16 v[124:127], v[144:147], v[196:199], v[124:127]
	v_mfma_f32_16x16x32_bf16 v[120:123], v[162:165], v[196:199], v[120:123]
	v_mfma_f32_16x16x32_bf16 v[108:111], v[144:147], v[204:207], v[108:111]
	v_mfma_f32_16x16x32_bf16 v[104:107], v[162:165], v[204:207], v[104:107]
	v_mfma_f32_16x16x32_bf16 v[92:95], v[144:147], v[212:215], v[92:95]
	v_mfma_f32_16x16x32_bf16 v[88:91], v[162:165], v[212:215], v[88:91]
	v_mfma_f32_16x16x32_bf16 v[76:79], v[144:147], v[220:223], v[76:79]
	v_mfma_f32_16x16x32_bf16 v[72:75], v[162:165], v[220:223], v[72:75]
	v_mfma_f32_16x16x32_bf16 v[124:127], v[148:151], v[200:203], v[124:127]
	v_mfma_f32_16x16x32_bf16 v[120:123], v[166:169], v[200:203], v[120:123]
	v_mfma_f32_16x16x32_bf16 v[108:111], v[148:151], v[208:211], v[108:111]
	v_mfma_f32_16x16x32_bf16 v[104:107], v[166:169], v[208:211], v[104:107]
	v_mfma_f32_16x16x32_bf16 v[92:95], v[148:151], v[216:219], v[92:95]
	v_mfma_f32_16x16x32_bf16 v[88:91], v[166:169], v[216:219], v[88:91]
	v_mfma_f32_16x16x32_bf16 v[76:79], v[148:151], v[224:227], v[76:79]
	v_mfma_f32_16x16x32_bf16 v[72:75], v[166:169], v[224:227], v[72:75]
	s_setprio 0
	s_setprio 1
	v_mfma_f32_16x16x32_bf16 v[116:119], v[180:183], v[196:199], v[116:119]
	v_mfma_f32_16x16x32_bf16 v[112:115], v[188:191], v[196:199], v[112:115]
	v_mfma_f32_16x16x32_bf16 v[100:103], v[180:183], v[204:207], v[100:103]
	v_mfma_f32_16x16x32_bf16 v[96:99], v[188:191], v[204:207], v[96:99]
	v_mfma_f32_16x16x32_bf16 v[84:87], v[180:183], v[212:215], v[84:87]
	v_mfma_f32_16x16x32_bf16 v[80:83], v[188:191], v[212:215], v[80:83]
	v_mfma_f32_16x16x32_bf16 v[68:71], v[180:183], v[220:223], v[68:71]
	v_mfma_f32_16x16x32_bf16 v[64:67], v[188:191], v[220:223], v[64:67]
	v_mfma_f32_16x16x32_bf16 v[116:119], v[184:187], v[200:203], v[116:119]
	v_mfma_f32_16x16x32_bf16 v[112:115], v[192:195], v[200:203], v[112:115]
	v_mfma_f32_16x16x32_bf16 v[100:103], v[184:187], v[208:211], v[100:103]
	v_mfma_f32_16x16x32_bf16 v[96:99], v[192:195], v[208:211], v[96:99]
	v_mfma_f32_16x16x32_bf16 v[84:87], v[184:187], v[216:219], v[84:87]
	v_mfma_f32_16x16x32_bf16 v[80:83], v[192:195], v[216:219], v[80:83]
	v_mfma_f32_16x16x32_bf16 v[68:71], v[184:187], v[224:227], v[68:71]
	v_mfma_f32_16x16x32_bf16 v[64:67], v[192:195], v[224:227], v[64:67]
	s_setprio 3
	s_barrier
; #define PG8_STAGE(bufoff, gbase, voff) do { _Pragma("unroll") for (int _i = 0; _i < 2; ++_i) \
;         __builtin_amdgcn_global_load_lds((const unsigned*)((const char*)(gbase) + (voff)[_i]), (LAS unsigned*)(lds + (bufoff) + ldsw + _i * 8192), 16, 0, 0); } while (0)
; #define PG8_LDA(dst, b, h) do { _Pragma("unroll") for (int m = 0; m < 4; ++m) _Pragma("unroll") for (int k = 0; k < 2; ++k) dst[m][k] = *(const LAS bf16x8*)(lds + PG8_SA(b, h) + aoff + m * 2048 + k * 1024); } while (0)
; #define PG8_MMA(ai, bj, At, Bt) do { __builtin_amdgcn_s_setprio(1); _Pragma("unroll") for (int m = 0; m < 4; ++m) _Pragma("unroll") for (int n = 0; n < 2; ++n) _Pragma("unroll") for (int k = 0; k < 2; ++k) \
;         acc[ai][bj][m][n] = __builtin_amdgcn_mfma_f32_16x16x32_bf16(Bt[n][k], At[m][k], acc[ai][bj][m][n], 0, 0, 0); __builtin_amdgcn_s_setprio(0); } while (0)
; #define PG8_WAIT_V(n) asm volatile("s_waitcnt vmcnt(" #n ")" ::: "memory")
; #define PG8_WAIT_L(n) asm volatile("s_waitcnt lgkmcnt(" #n ")" ::: "memory")
; #define PG8_BAR __builtin_amdgcn_s_barrier()
; #define PG8_SCHED __builtin_amdgcn_sched_barrier(0)
; template <class Epi>
; __device__ __forceinline__ void gemm_phase(LAS unsigned char* lds, const Gemm g, const StaticOrder& S, const Epi& E) {
;     ...
;             PG8_LDA(At, 1, 1); PG8_STAGE(PG8_SB(1, 0), b3, voffB); PG8_STAGE(PG8_SB(1, 1), b3 + hsB, voffB); PG8_STAGE(PG8_SA(1, 0), a3, voffA);
;             PG8_WAIT_V(8); PG8_WAIT_L(0); PG8_BAR; PG8_MMA(1, 0, At, B0); PG8_MMA(1, 1, At, B1); PG8_BAR; PG8_SCHED;
;         }
	s_add_i32 s38, s40, s16
	v_lshl_add_u64 v[170:171], v[170:171], 0, s[2:3]
	s_mov_b32 m0, s38
	ds_read_b128 v[196:199], v157 offset:49152
	ds_read_b128 v[200:203], v157 offset:50176
	ds_read_b128 v[204:207], v157 offset:51200
	ds_read_b128 v[208:211], v157 offset:52224
	ds_read_b128 v[212:215], v157 offset:53248
	ds_read_b128 v[216:219], v157 offset:54272
	ds_read_b128 v[220:223], v157 offset:55296
	ds_read_b128 v[224:227], v157 offset:56320
	global_load_lds_dwordx4 v[170:171], off
	s_add_i32 m0, s38, 0x2000
	s_add_u32 s38, s60, 0x40080
	v_lshl_add_u64 v[170:171], v[228:229], 0, s[2:3]
	s_addc_u32 s39, s61, 0
	s_add_i32 s40, s41, s16
	global_load_lds_dwordx4 v[170:171], off
	v_lshl_add_u64 v[170:171], s[38:39], 0, v[132:133]
	s_mov_b32 m0, s40
	s_nop 0
	global_load_lds_dwordx4 v[170:171], off
	v_lshl_add_u64 v[170:171], s[38:39], 0, v[128:129]
	s_add_i32 m0, s40, 0x2000
	s_nop 0
	global_load_lds_dwordx4 v[170:171], off
	v_lshl_add_u64 v[170:171], v[230:231], 0, s[2:3]
	s_mov_b32 m0, s25
	s_nop 0
	global_load_lds_dwordx4 v[170:171], off
	v_lshl_add_u64 v[170:171], v[232:233], 0, s[2:3]
	s_mov_b32 m0, s26
	s_nop 0
	global_load_lds_dwordx4 v[170:171], off
	s_waitcnt vmcnt(8)
	s_waitcnt lgkmcnt(0)
	s_barrier
	s_setprio 1
	s_waitcnt lgkmcnt(0)
	v_mfma_f32_16x16x32_bf16 v[60:63], v[144:147], v[196:199], v[60:63]
	v_mfma_f32_16x16x32_bf16 v[56:59], v[162:165], v[196:199], v[56:59]
	v_mfma_f32_16x16x32_bf16 v[44:47], v[144:147], v[204:207], v[44:47]
	v_mfma_f32_16x16x32_bf16 v[40:43], v[162:165], v[204:207], v[40:43]
	v_mfma_f32_16x16x32_bf16 v[28:31], v[144:147], v[212:215], v[28:31]
	v_mfma_f32_16x16x32_bf16 v[24:27], v[162:165], v[212:215], v[24:27]
	v_mfma_f32_16x16x32_bf16 v[12:15], v[144:147], v[220:223], v[12:15]
	v_mfma_f32_16x16x32_bf16 v[8:11], v[162:165], v[220:223], v[8:11]
	v_mfma_f32_16x16x32_bf16 v[60:63], v[148:151], v[200:203], v[60:63]
	v_mfma_f32_16x16x32_bf16 v[56:59], v[166:169], v[200:203], v[56:59]
	v_mfma_f32_16x16x32_bf16 v[44:47], v[148:151], v[208:211], v[44:47]
	v_mfma_f32_16x16x32_bf16 v[40:43], v[166:169], v[208:211], v[40:43]
	v_mfma_f32_16x16x32_bf16 v[28:31], v[148:151], v[216:219], v[28:31]
	v_mfma_f32_16x16x32_bf16 v[24:27], v[166:169], v[216:219], v[24:27]
	v_mfma_f32_16x16x32_bf16 v[12:15], v[148:151], v[224:227], v[12:15]
	v_mfma_f32_16x16x32_bf16 v[8:11], v[166:169], v[224:227], v[8:11]
	s_setprio 0
	s_setprio 1
	v_mfma_f32_16x16x32_bf16 v[52:55], v[180:183], v[196:199], v[52:55]
	v_mfma_f32_16x16x32_bf16 v[48:51], v[188:191], v[196:199], v[48:51]
	v_mfma_f32_16x16x32_bf16 v[36:39], v[180:183], v[204:207], v[36:39]
	v_mfma_f32_16x16x32_bf16 v[32:35], v[188:191], v[204:207], v[32:35]
	v_mfma_f32_16x16x32_bf16 v[20:23], v[180:183], v[212:215], v[20:23]
	v_mfma_f32_16x16x32_bf16 v[16:19], v[188:191], v[212:215], v[16:19]
	v_mfma_f32_16x16x32_bf16 v[4:7], v[180:183], v[220:223], v[4:7]
	v_mfma_f32_16x16x32_bf16 v[0:3], v[188:191], v[220:223], v[0:3]
	v_mfma_f32_16x16x32_bf16 v[52:55], v[184:187], v[200:203], v[52:55]
	v_mfma_f32_16x16x32_bf16 v[48:51], v[192:195], v[200:203], v[48:51]
	v_mfma_f32_16x16x32_bf16 v[36:39], v[184:187], v[208:211], v[36:39]
	v_mfma_f32_16x16x32_bf16 v[32:35], v[192:195], v[208:211], v[32:35]
	v_mfma_f32_16x16x32_bf16 v[20:23], v[184:187], v[216:219], v[20:23]
	v_mfma_f32_16x16x32_bf16 v[16:19], v[192:195], v[216:219], v[16:19]
	v_mfma_f32_16x16x32_bf16 v[4:7], v[184:187], v[224:227], v[4:7]
	v_mfma_f32_16x16x32_bf16 v[0:3], v[192:195], v[224:227], v[0:3]
	s_setprio 3
	s_barrier
	s_add_i32 s37, s37, 2
	s_add_u32 s58, s58, 0x100
	s_addc_u32 s59, s59, 0
	s_add_u32 s35, s35, 0x100
	s_addc_u32 s36, s36, 0
	s_cmp_gt_u32 s37, 13
	s_cbranch_scc0 .LBB0_214
	s_and_b64 vcc, exec, s[8:9]
	s_cbranch_vccz .LBB0_217
	s_barrier

; #define PG8_STAGE(bufoff, gbase, voff) do { _Pragma("unroll") for (int _i = 0; _i < 2; ++_i) \
;         __builtin_amdgcn_global_load_lds((const unsigned*)((const char*)(gbase) + (voff)[_i]), (LAS unsigned*)(lds + (bufoff) + ldsw + _i * 8192), 16, 0, 0); } while (0)
; #define PG8_LDA(dst, b, h) do { _Pragma("unroll") for (int m = 0; m < 4; ++m) _Pragma("unroll") for (int k = 0; k < 2; ++k) dst[m][k] = *(const LAS bf16x8*)(lds + PG8_SA(b, h) + aoff + m * 2048 + k * 1024); } while (0)
; #define PG8_LDB(dst, b, h) do { _Pragma("unroll") for (int n = 0; n < 2; ++n) _Pragma("unroll") for (int k = 0; k < 2; ++k) dst[n][k] = *(const LAS bf16x8*)(lds + PG8_SB(b, h) + boff + n * 2048 + k * 1024); } while (0)
; #define PG8_MMA(ai, bj, At, Bt) do { __builtin_amdgcn_s_setprio(1); _Pragma("unroll") for (int m = 0; m < 4; ++m) _Pragma("unroll") for (int n = 0; n < 2; ++n) _Pragma("unroll") for (int k = 0; k < 2; ++k) \
;         acc[ai][bj][m][n] = __builtin_amdgcn_mfma_f32_16x16x32_bf16(Bt[n][k], At[m][k], acc[ai][bj][m][n], 0, 0, 0); __builtin_amdgcn_s_setprio(0); } while (0)
; #define PG8_WAIT_V(n) asm volatile("s_waitcnt vmcnt(" #n ")" ::: "memory")
; #define PG8_WAIT_L(n) asm volatile("s_waitcnt lgkmcnt(" #n ")" ::: "memory")
; #define PG8_BAR __builtin_amdgcn_s_barrier()
; #define PG8_SCHED __builtin_amdgcn_sched_barrier(0)
; template <class Epi>
; __device__ __forceinline__ void gemm_phase(LAS unsigned char* lds, const Gemm g, const StaticOrder& S, const Epi& E) {
;     ...
;             PG8_LDB(B0, 0, 0); PG8_LDB(B1, 0, 1); PG8_SCHED; PG8_LDA(At, 0, 0); PG8_STAGE(PG8_SA(1, 1), a1 + hsA, voffA);
;             PG8_WAIT_V(8); PG8_WAIT_L(0); PG8_BAR; PG8_MMA(0, 0, At, B0); PG8_MMA(0, 1, At, B1); PG8_BAR; PG8_SCHED;
;             PG8_LDA(At, 0, 1); PG8_STAGE(PG8_SB(0, 0), b2, voffB); PG8_STAGE(PG8_SB(0, 1), b2 + hsB, voffB); PG8_STAGE(PG8_SA(0, 0), a2, voffA);
;             PG8_WAIT_V(8); PG8_WAIT_L(0); PG8_BAR; PG8_MMA(1, 0, At, B0); PG8_MMA(1, 1, At, B1); PG8_BAR; PG8_SCHED;
.LBB0_296:
	ds_read_b128 v[144:147], v157
	ds_read_b128 v[148:151], v157 offset:1024
	ds_read_b128 v[164:167], v157 offset:2048
	ds_read_b128 v[168:171], v157 offset:3072
	ds_read_b128 v[180:183], v158
	ds_read_b128 v[184:187], v158 offset:1024
	ds_read_b128 v[188:191], v158 offset:2048
	ds_read_b128 v[192:195], v158 offset:3072
	s_add_u32 s60, s12, 0x100
	s_addc_u32 s61, s13, 0
	s_cmp_eq_u32 s34, 40
	s_cselect_b32 s65, s1, s61
	s_cselect_b32 s64, s0, s60
	s_cselect_b32 s63, s59, s7
	s_cselect_b32 s62, s58, s6
	v_lshl_add_u64 v[152:153], s[12:13], 0, v[136:137]
	s_add_i32 m0, s5, 0xc000
	ds_read_b128 v[196:199], v159
	ds_read_b128 v[200:203], v159 offset:1024
	ds_read_b128 v[204:207], v159 offset:2048
	ds_read_b128 v[208:211], v159 offset:3072
	ds_read_b128 v[212:215], v159 offset:4096
	ds_read_b128 v[216:219], v159 offset:5120
	ds_read_b128 v[220:223], v159 offset:6144
	ds_read_b128 v[224:227], v159 offset:7168
	global_load_lds_dwordx4 v[152:153], off
	v_lshl_add_u64 v[152:153], s[12:13], 0, v[138:139]
	s_add_i32 m0, s5, 0xe000
	s_nop 0
	global_load_lds_dwordx4 v[152:153], off
	s_waitcnt vmcnt(8)
	s_waitcnt lgkmcnt(0)
	s_barrier
	s_setprio 1
	s_waitcnt lgkmcnt(0)
	v_mfma_f32_16x16x32_bf16 v[124:127], v[144:147], v[196:199], v[124:127]
	v_mfma_f32_16x16x32_bf16 v[120:123], v[164:167], v[196:199], v[120:123]
	v_mfma_f32_16x16x32_bf16 v[108:111], v[144:147], v[204:207], v[108:111]
	v_mfma_f32_16x16x32_bf16 v[104:107], v[164:167], v[204:207], v[104:107]
	v_mfma_f32_16x16x32_bf16 v[92:95], v[144:147], v[212:215], v[92:95]
	v_mfma_f32_16x16x32_bf16 v[88:91], v[164:167], v[212:215], v[88:91]
	v_mfma_f32_16x16x32_bf16 v[76:79], v[144:147], v[220:223], v[76:79]
	v_mfma_f32_16x16x32_bf16 v[72:75], v[164:167], v[220:223], v[72:75]
	v_mfma_f32_16x16x32_bf16 v[124:127], v[148:151], v[200:203], v[124:127]
	v_mfma_f32_16x16x32_bf16 v[120:123], v[168:171], v[200:203], v[120:123]
	v_mfma_f32_16x16x32_bf16 v[108:111], v[148:151], v[208:211], v[108:111]
	v_mfma_f32_16x16x32_bf16 v[104:107], v[168:171], v[208:211], v[104:107]
	v_mfma_f32_16x16x32_bf16 v[92:95], v[148:151], v[216:219], v[92:95]
	v_mfma_f32_16x16x32_bf16 v[88:91], v[168:171], v[216:219], v[88:91]
	v_mfma_f32_16x16x32_bf16 v[76:79], v[148:151], v[224:227], v[76:79]
	v_mfma_f32_16x16x32_bf16 v[72:75], v[168:171], v[224:227], v[72:75]
	s_setprio 0
	s_setprio 1
	v_mfma_f32_16x16x32_bf16 v[116:119], v[180:183], v[196:199], v[116:119]
	v_mfma_f32_16x16x32_bf16 v[112:115], v[188:191], v[196:199], v[112:115]
	v_mfma_f32_16x16x32_bf16 v[100:103], v[180:183], v[204:207], v[100:103]
	v_mfma_f32_16x16x32_bf16 v[96:99], v[188:191], v[204:207], v[96:99]
	v_mfma_f32_16x16x32_bf16 v[84:87], v[180:183], v[212:215], v[84:87]
	v_mfma_f32_16x16x32_bf16 v[80:83], v[188:191], v[212:215], v[80:83]
	v_mfma_f32_16x16x32_bf16 v[68:71], v[180:183], v[220:223], v[68:71]
	v_mfma_f32_16x16x32_bf16 v[64:67], v[188:191], v[220:223], v[64:67]
	v_mfma_f32_16x16x32_bf16 v[116:119], v[184:187], v[200:203], v[116:119]
	v_mfma_f32_16x16x32_bf16 v[112:115], v[192:195], v[200:203], v[112:115]
	v_mfma_f32_16x16x32_bf16 v[100:103], v[184:187], v[208:211], v[100:103]
	v_mfma_f32_16x16x32_bf16 v[96:99], v[192:195], v[208:211], v[96:99]
	v_mfma_f32_16x16x32_bf16 v[84:87], v[184:187], v[216:219], v[84:87]
	v_mfma_f32_16x16x32_bf16 v[80:83], v[192:195], v[216:219], v[80:83]
	v_mfma_f32_16x16x32_bf16 v[68:71], v[184:187], v[224:227], v[68:71]
	v_mfma_f32_16x16x32_bf16 v[64:67], v[192:195], v[224:227], v[64:67]
	s_setprio 3
	s_barrier
	s_add_i32 s12, s27, s4
	v_lshl_add_u64 v[152:153], s[62:63], 0, v[130:131]
	s_mov_b32 m0, s12
	ds_read_b128 v[196:199], v159 offset:16384
	ds_read_b128 v[200:203], v159 offset:17408
	ds_read_b128 v[204:207], v159 offset:18432
	ds_read_b128 v[208:211], v159 offset:19456
	ds_read_b128 v[212:215], v159 offset:20480
	ds_read_b128 v[216:219], v159 offset:21504
	ds_read_b128 v[220:223], v159 offset:22528
	ds_read_b128 v[224:227], v159 offset:23552
	global_load_lds_dwordx4 v[152:153], off
	s_add_i32 m0, s12, 0x2000
	s_add_u32 s12, s62, 0xb0000
	v_lshl_add_u64 v[228:229], s[62:63], 0, v[134:135]
	s_addc_u32 s13, s63, 0
	s_add_i32 s35, s28, s4
	global_load_lds_dwordx4 v[228:229], off
	v_lshl_add_u64 v[230:231], s[12:13], 0, v[130:131]
	s_mov_b32 m0, s35
	v_lshl_add_u64 v[232:233], s[64:65], 0, v[132:133]
	global_load_lds_dwordx4 v[230:231], off
	v_lshl_add_u64 v[230:231], s[12:13], 0, v[134:135]
	s_add_i32 m0, s35, 0x2000
	s_nop 0
	global_load_lds_dwordx4 v[230:231], off
	v_lshl_add_u64 v[230:231], s[64:65], 0, v[128:129]
	s_mov_b32 m0, s5
	s_nop 0
	global_load_lds_dwordx4 v[230:231], off
	s_mov_b32 m0, s16
	s_nop 0
	global_load_lds_dwordx4 v[232:233], off
	s_waitcnt vmcnt(8)
	s_waitcnt lgkmcnt(0)
	s_barrier
; #define PG8_STAGE(bufoff, gbase, voff) do { _Pragma("unroll") for (int _i = 0; _i < 2; ++_i) \
;         __builtin_amdgcn_global_load_lds((const unsigned*)((const char*)(gbase) + (voff)[_i]), (LAS unsigned*)(lds + (bufoff) + ldsw + _i * 8192), 16, 0, 0); } while (0)
; #define PG8_LDA(dst, b, h) do { _Pragma("unroll") for (int m = 0; m < 4; ++m) _Pragma("unroll") for (int k = 0; k < 2; ++k) dst[m][k] = *(const LAS bf16x8*)(lds + PG8_SA(b, h) + aoff + m * 2048 + k * 1024); } while (0)
; #define PG8_LDB(dst, b, h) do { _Pragma("unroll") for (int n = 0; n < 2; ++n) _Pragma("unroll") for (int k = 0; k < 2; ++k) dst[n][k] = *(const LAS bf16x8*)(lds + PG8_SB(b, h) + boff + n * 2048 + k * 1024); } while (0)
; #define PG8_MMA(ai, bj, At, Bt) do { __builtin_amdgcn_s_setprio(1); _Pragma("unroll") for (int m = 0; m < 4; ++m) _Pragma("unroll") for (int n = 0; n < 2; ++n) _Pragma("unroll") for (int k = 0; k < 2; ++k) \
;         acc[ai][bj][m][n] = __builtin_amdgcn_mfma_f32_16x16x32_bf16(Bt[n][k], At[m][k], acc[ai][bj][m][n], 0, 0, 0); __builtin_amdgcn_s_setprio(0); } while (0)
; #define PG8_WAIT_V(n) asm volatile("s_waitcnt vmcnt(" #n ")" ::: "memory")
; #define PG8_WAIT_L(n) asm volatile("s_waitcnt lgkmcnt(" #n ")" ::: "memory")
; #define PG8_BAR __builtin_amdgcn_s_barrier()
; #define PG8_SCHED __builtin_amdgcn_sched_barrier(0)
; template <class Epi>
; __device__ __forceinline__ void gemm_phase(LAS unsigned char* lds, const Gemm g, const StaticOrder& S, const Epi& E) {
;     ...
;             PG8_WAIT_V(8); PG8_WAIT_L(0); PG8_BAR; PG8_MMA(1, 0, At, B0); PG8_MMA(1, 1, At, B1); PG8_BAR; PG8_SCHED;
;             PG8_LDB(B0, 1, 0); PG8_LDB(B1, 1, 1); PG8_SCHED; PG8_LDA(At, 1, 0); PG8_STAGE(PG8_SA(0, 1), a2 + hsA, voffA);
;             PG8_WAIT_V(8); PG8_WAIT_L(0); PG8_BAR; PG8_MMA(0, 0, At, B0); PG8_MMA(0, 1, At, B1); PG8_BAR; PG8_SCHED;
	s_setprio 1
	s_waitcnt lgkmcnt(0)
	v_mfma_f32_16x16x32_bf16 v[60:63], v[144:147], v[196:199], v[60:63]
	v_mfma_f32_16x16x32_bf16 v[56:59], v[164:167], v[196:199], v[56:59]
	v_mfma_f32_16x16x32_bf16 v[44:47], v[144:147], v[204:207], v[44:47]
	v_mfma_f32_16x16x32_bf16 v[40:43], v[164:167], v[204:207], v[40:43]
	v_mfma_f32_16x16x32_bf16 v[28:31], v[144:147], v[212:215], v[28:31]
	v_mfma_f32_16x16x32_bf16 v[24:27], v[164:167], v[212:215], v[24:27]
	v_mfma_f32_16x16x32_bf16 v[12:15], v[144:147], v[220:223], v[12:15]
	v_mfma_f32_16x16x32_bf16 v[8:11], v[164:167], v[220:223], v[8:11]
	v_mfma_f32_16x16x32_bf16 v[60:63], v[148:151], v[200:203], v[60:63]
	v_mfma_f32_16x16x32_bf16 v[56:59], v[168:171], v[200:203], v[56:59]
	v_mfma_f32_16x16x32_bf16 v[44:47], v[148:151], v[208:211], v[44:47]
	v_mfma_f32_16x16x32_bf16 v[40:43], v[168:171], v[208:211], v[40:43]
	v_mfma_f32_16x16x32_bf16 v[28:31], v[148:151], v[216:219], v[28:31]
	v_mfma_f32_16x16x32_bf16 v[24:27], v[168:171], v[216:219], v[24:27]
	v_mfma_f32_16x16x32_bf16 v[12:15], v[148:151], v[224:227], v[12:15]
	v_mfma_f32_16x16x32_bf16 v[8:11], v[168:171], v[224:227], v[8:11]
	s_setprio 0
	s_setprio 1
	v_mfma_f32_16x16x32_bf16 v[52:55], v[180:183], v[196:199], v[52:55]
	v_mfma_f32_16x16x32_bf16 v[48:51], v[188:191], v[196:199], v[48:51]
	v_mfma_f32_16x16x32_bf16 v[36:39], v[180:183], v[204:207], v[36:39]
	v_mfma_f32_16x16x32_bf16 v[32:35], v[188:191], v[204:207], v[32:35]
	v_mfma_f32_16x16x32_bf16 v[20:23], v[180:183], v[212:215], v[20:23]
	v_mfma_f32_16x16x32_bf16 v[16:19], v[188:191], v[212:215], v[16:19]
	v_mfma_f32_16x16x32_bf16 v[4:7], v[180:183], v[220:223], v[4:7]
	v_mfma_f32_16x16x32_bf16 v[0:3], v[188:191], v[220:223], v[0:3]
	v_mfma_f32_16x16x32_bf16 v[52:55], v[184:187], v[200:203], v[52:55]
	v_mfma_f32_16x16x32_bf16 v[48:51], v[192:195], v[200:203], v[48:51]
	v_mfma_f32_16x16x32_bf16 v[36:39], v[184:187], v[208:211], v[36:39]
	v_mfma_f32_16x16x32_bf16 v[32:35], v[192:195], v[208:211], v[32:35]
	v_mfma_f32_16x16x32_bf16 v[20:23], v[184:187], v[216:219], v[20:23]
	v_mfma_f32_16x16x32_bf16 v[16:19], v[192:195], v[216:219], v[16:19]
	v_mfma_f32_16x16x32_bf16 v[4:7], v[184:187], v[224:227], v[4:7]
	v_mfma_f32_16x16x32_bf16 v[0:3], v[192:195], v[224:227], v[0:3]
	s_setprio 3
	s_barrier
	s_add_i32 s35, 0, 0x18000
	v_add_u32_e32 v163, s35, v155
	s_add_i32 s36, 0, 0x1c000
	ds_read_b128 v[144:147], v163
	ds_read_b128 v[148:151], v163 offset:1024
	ds_read_b128 v[164:167], v163 offset:2048
	ds_read_b128 v[168:171], v163 offset:3072
	v_add_u32_e32 v163, s36, v155
	ds_read_b128 v[180:183], v163
	ds_read_b128 v[184:187], v163 offset:1024
	ds_read_b128 v[188:191], v163 offset:2048
	ds_read_b128 v[192:195], v163 offset:3072
	s_add_u32 s12, s64, 0xb0000
	s_addc_u32 s13, s65, 0
	s_mov_b32 m0, s17
	v_lshl_add_u64 v[234:235], s[12:13], 0, v[128:129]
	ds_read_b128 v[196:199], v159 offset:32768
	ds_read_b128 v[200:203], v159 offset:33792
	ds_read_b128 v[204:207], v159 offset:34816
	ds_read_b128 v[208:211], v159 offset:35840
	ds_read_b128 v[212:215], v159 offset:36864
	ds_read_b128 v[216:219], v159 offset:37888
	ds_read_b128 v[220:223], v159 offset:38912
	ds_read_b128 v[224:227], v159 offset:39936
	global_load_lds_dwordx4 v[234:235], off
	v_lshl_add_u64 v[234:235], s[12:13], 0, v[132:133]
	s_mov_b32 m0, s18
	s_nop 0
	global_load_lds_dwordx4 v[234:235], off
	s_waitcnt vmcnt(8)
	s_waitcnt lgkmcnt(0)
	s_barrier
	s_setprio 1
	s_waitcnt lgkmcnt(0)
	v_mfma_f32_16x16x32_bf16 v[124:127], v[144:147], v[196:199], v[124:127]
	v_mfma_f32_16x16x32_bf16 v[120:123], v[164:167], v[196:199], v[120:123]
	v_mfma_f32_16x16x32_bf16 v[108:111], v[144:147], v[204:207], v[108:111]
	v_mfma_f32_16x16x32_bf16 v[104:107], v[164:167], v[204:207], v[104:107]
	v_mfma_f32_16x16x32_bf16 v[92:95], v[144:147], v[212:215], v[92:95]
	v_mfma_f32_16x16x32_bf16 v[88:91], v[164:167], v[212:215], v[88:91]
	v_mfma_f32_16x16x32_bf16 v[76:79], v[144:147], v[220:223], v[76:79]
	v_mfma_f32_16x16x32_bf16 v[72:75], v[164:167], v[220:223], v[72:75]
	v_mfma_f32_16x16x32_bf16 v[124:127], v[148:151], v[200:203], v[124:127]
	v_mfma_f32_16x16x32_bf16 v[120:123], v[168:171], v[200:203], v[120:123]
	v_mfma_f32_16x16x32_bf16 v[108:111], v[148:151], v[208:211], v[108:111]
	v_mfma_f32_16x16x32_bf16 v[104:107], v[168:171], v[208:211], v[104:107]
	v_mfma_f32_16x16x32_bf16 v[92:95], v[148:151], v[216:219], v[92:95]
	v_mfma_f32_16x16x32_bf16 v[88:91], v[168:171], v[216:219], v[88:91]
	v_mfma_f32_16x16x32_bf16 v[76:79], v[148:151], v[224:227], v[76:79]
	v_mfma_f32_16x16x32_bf16 v[72:75], v[168:171], v[224:227], v[72:75]
	s_setprio 0
	s_setprio 1
	v_mfma_f32_16x16x32_bf16 v[116:119], v[180:183], v[196:199], v[116:119]
	v_mfma_f32_16x16x32_bf16 v[112:115], v[188:191], v[196:199], v[112:115]
	v_mfma_f32_16x16x32_bf16 v[100:103], v[180:183], v[204:207], v[100:103]
	v_mfma_f32_16x16x32_bf16 v[96:99], v[188:191], v[204:207], v[96:99]
	v_mfma_f32_16x16x32_bf16 v[84:87], v[180:183], v[212:215], v[84:87]
	v_mfma_f32_16x16x32_bf16 v[80:83], v[188:191], v[212:215], v[80:83]
	v_mfma_f32_16x16x32_bf16 v[68:71], v[180:183], v[220:223], v[68:71]
	v_mfma_f32_16x16x32_bf16 v[64:67], v[188:191], v[220:223], v[64:67]
	v_mfma_f32_16x16x32_bf16 v[116:119], v[184:187], v[200:203], v[116:119]
	v_mfma_f32_16x16x32_bf16 v[112:115], v[192:195], v[200:203], v[112:115]
	v_mfma_f32_16x16x32_bf16 v[100:103], v[184:187], v[208:211], v[100:103]
	v_mfma_f32_16x16x32_bf16 v[96:99], v[192:195], v[208:211], v[96:99]
	v_mfma_f32_16x16x32_bf16 v[84:87], v[184:187], v[216:219], v[84:87]
	v_mfma_f32_16x16x32_bf16 v[80:83], v[192:195], v[216:219], v[80:83]
	v_mfma_f32_16x16x32_bf16 v[68:71], v[184:187], v[224:227], v[68:71]
	v_mfma_f32_16x16x32_bf16 v[64:67], v[192:195], v[224:227], v[64:67]
	s_setprio 3
	s_barrier
; #define PG8_STAGE(bufoff, gbase, voff) do { _Pragma("unroll") for (int _i = 0; _i < 2; ++_i) \
;         __builtin_amdgcn_global_load_lds((const unsigned*)((const char*)(gbase) + (voff)[_i]), (LAS unsigned*)(lds + (bufoff) + ldsw + _i * 8192), 16, 0, 0); } while (0)
; #define PG8_LDA(dst, b, h) do { _Pragma("unroll") for (int m = 0; m < 4; ++m) _Pragma("unroll") for (int k = 0; k < 2; ++k) dst[m][k] = *(const LAS bf16x8*)(lds + PG8_SA(b, h) + aoff + m * 2048 + k * 1024); } while (0)
; #define PG8_MMA(ai, bj, At, Bt) do { __builtin_amdgcn_s_setprio(1); _Pragma("unroll") for (int m = 0; m < 4; ++m) _Pragma("unroll") for (int n = 0; n < 2; ++n) _Pragma("unroll") for (int k = 0; k < 2; ++k) \
;         acc[ai][bj][m][n] = __builtin_amdgcn_mfma_f32_16x16x32_bf16(Bt[n][k], At[m][k], acc[ai][bj][m][n], 0, 0, 0); __builtin_amdgcn_s_setprio(0); } while (0)
; #define PG8_WAIT_V(n) asm volatile("s_waitcnt vmcnt(" #n ")" ::: "memory")
; #define PG8_WAIT_L(n) asm volatile("s_waitcnt lgkmcnt(" #n ")" ::: "memory")
; #define PG8_BAR __builtin_amdgcn_s_barrier()
; #define PG8_SCHED __builtin_amdgcn_sched_barrier(0)
; template <class Epi>
; __device__ __forceinline__ void gemm_phase(LAS unsigned char* lds, const Gemm g, const StaticOrder& S, const Epi& E) {
;     ...
;             PG8_LDA(At, 1, 1); PG8_STAGE(PG8_SB(1, 0), b3, voffB); PG8_STAGE(PG8_SB(1, 1), b3 + hsB, voffB); PG8_STAGE(PG8_SA(1, 0), a3, voffA);
;             PG8_WAIT_V(8); PG8_WAIT_L(0); PG8_BAR; PG8_MMA(1, 0, At, B0); PG8_MMA(1, 1, At, B1); PG8_BAR; PG8_SCHED;
;         }
	s_add_i32 s12, s35, s4
	v_lshl_add_u64 v[152:153], v[152:153], 0, s[14:15]
	s_mov_b32 m0, s12
	ds_read_b128 v[196:199], v159 offset:49152
	ds_read_b128 v[200:203], v159 offset:50176
	ds_read_b128 v[204:207], v159 offset:51200
	ds_read_b128 v[208:211], v159 offset:52224
	ds_read_b128 v[212:215], v159 offset:53248
	ds_read_b128 v[216:219], v159 offset:54272
	ds_read_b128 v[220:223], v159 offset:55296
	ds_read_b128 v[224:227], v159 offset:56320
	global_load_lds_dwordx4 v[152:153], off
	s_add_i32 m0, s12, 0x2000
	s_add_u32 s12, s62, 0xb0080
	v_lshl_add_u64 v[152:153], v[228:229], 0, s[14:15]
	s_addc_u32 s13, s63, 0
	s_add_i32 s35, s36, s4
	global_load_lds_dwordx4 v[152:153], off
	v_lshl_add_u64 v[152:153], s[12:13], 0, v[130:131]
	s_mov_b32 m0, s35
	s_nop 0
	global_load_lds_dwordx4 v[152:153], off
	v_lshl_add_u64 v[152:153], s[12:13], 0, v[134:135]
	s_add_i32 m0, s35, 0x2000
	s_nop 0
	global_load_lds_dwordx4 v[152:153], off
	v_lshl_add_u64 v[152:153], v[230:231], 0, s[14:15]
	s_mov_b32 m0, s22
	s_nop 0
	global_load_lds_dwordx4 v[152:153], off
	v_lshl_add_u64 v[152:153], v[232:233], 0, s[14:15]
	s_mov_b32 m0, s23
	s_nop 0
	global_load_lds_dwordx4 v[152:153], off
	s_waitcnt vmcnt(8)
	s_waitcnt lgkmcnt(0)
	s_barrier
	s_setprio 1
	s_waitcnt lgkmcnt(0)
	v_mfma_f32_16x16x32_bf16 v[60:63], v[144:147], v[196:199], v[60:63]
	v_mfma_f32_16x16x32_bf16 v[56:59], v[164:167], v[196:199], v[56:59]
	v_mfma_f32_16x16x32_bf16 v[44:47], v[144:147], v[204:207], v[44:47]
	v_mfma_f32_16x16x32_bf16 v[40:43], v[164:167], v[204:207], v[40:43]
	v_mfma_f32_16x16x32_bf16 v[28:31], v[144:147], v[212:215], v[28:31]
	v_mfma_f32_16x16x32_bf16 v[24:27], v[164:167], v[212:215], v[24:27]
	v_mfma_f32_16x16x32_bf16 v[12:15], v[144:147], v[220:223], v[12:15]
	v_mfma_f32_16x16x32_bf16 v[8:11], v[164:167], v[220:223], v[8:11]
	v_mfma_f32_16x16x32_bf16 v[60:63], v[148:151], v[200:203], v[60:63]
	v_mfma_f32_16x16x32_bf16 v[56:59], v[168:171], v[200:203], v[56:59]
	v_mfma_f32_16x16x32_bf16 v[44:47], v[148:151], v[208:211], v[44:47]
	v_mfma_f32_16x16x32_bf16 v[40:43], v[168:171], v[208:211], v[40:43]
	v_mfma_f32_16x16x32_bf16 v[28:31], v[148:151], v[216:219], v[28:31]
	v_mfma_f32_16x16x32_bf16 v[24:27], v[168:171], v[216:219], v[24:27]
	v_mfma_f32_16x16x32_bf16 v[12:15], v[148:151], v[224:227], v[12:15]
	v_mfma_f32_16x16x32_bf16 v[8:11], v[168:171], v[224:227], v[8:11]
	s_setprio 0
	s_setprio 1
	v_mfma_f32_16x16x32_bf16 v[52:55], v[180:183], v[196:199], v[52:55]
	v_mfma_f32_16x16x32_bf16 v[48:51], v[188:191], v[196:199], v[48:51]
	v_mfma_f32_16x16x32_bf16 v[36:39], v[180:183], v[204:207], v[36:39]
	v_mfma_f32_16x16x32_bf16 v[32:35], v[188:191], v[204:207], v[32:35]
	v_mfma_f32_16x16x32_bf16 v[20:23], v[180:183], v[212:215], v[20:23]
	v_mfma_f32_16x16x32_bf16 v[16:19], v[188:191], v[212:215], v[16:19]
	v_mfma_f32_16x16x32_bf16 v[4:7], v[180:183], v[220:223], v[4:7]
	v_mfma_f32_16x16x32_bf16 v[0:3], v[188:191], v[220:223], v[0:3]
	v_mfma_f32_16x16x32_bf16 v[52:55], v[184:187], v[200:203], v[52:55]
	v_mfma_f32_16x16x32_bf16 v[48:51], v[192:195], v[200:203], v[48:51]
	v_mfma_f32_16x16x32_bf16 v[36:39], v[184:187], v[208:211], v[36:39]
	v_mfma_f32_16x16x32_bf16 v[32:35], v[192:195], v[208:211], v[32:35]
	v_mfma_f32_16x16x32_bf16 v[20:23], v[184:187], v[216:219], v[20:23]
	v_mfma_f32_16x16x32_bf16 v[16:19], v[192:195], v[216:219], v[16:19]
	v_mfma_f32_16x16x32_bf16 v[4:7], v[184:187], v[224:227], v[4:7]
	v_mfma_f32_16x16x32_bf16 v[0:3], v[192:195], v[224:227], v[0:3]
	s_setprio 3
	s_barrier
	s_add_i32 s34, s34, 2
	s_add_u32 s6, s6, 0x100
	s_addc_u32 s7, s7, 0
	s_cmp_gt_u32 s34, 41
	s_mov_b64 s[12:13], s[60:61]
	s_cbranch_scc0 .LBB0_296
	s_and_b64 vcc, exec, s[42:43]
	s_cbranch_vccz .LBB0_299
	s_barrier

; #define PG8_STAGE(bufoff, gbase, voff) do { _Pragma("unroll") for (int _i = 0; _i < 2; ++_i) \
;         __builtin_amdgcn_global_load_lds((const unsigned*)((const char*)(gbase) + (voff)[_i]), (LAS unsigned*)(lds + (bufoff) + ldsw + _i * 8192), 16, 0, 0); } while (0)
; #define PG8_LDA(dst, b, h) do { _Pragma("unroll") for (int m = 0; m < 4; ++m) _Pragma("unroll") for (int k = 0; k < 2; ++k) dst[m][k] = *(const LAS bf16x8*)(lds + PG8_SA(b, h) + aoff + m * 2048 + k * 1024); } while (0)
; #define PG8_LDB(dst, b, h) do { _Pragma("unroll") for (int n = 0; n < 2; ++n) _Pragma("unroll") for (int k = 0; k < 2; ++k) dst[n][k] = *(const LAS bf16x8*)(lds + PG8_SB(b, h) + boff + n * 2048 + k * 1024); } while (0)
; #define PG8_MMA(ai, bj, At, Bt) do { __builtin_amdgcn_s_setprio(1); _Pragma("unroll") for (int m = 0; m < 4; ++m) _Pragma("unroll") for (int n = 0; n < 2; ++n) _Pragma("unroll") for (int k = 0; k < 2; ++k) \
;         acc[ai][bj][m][n] = __builtin_amdgcn_mfma_f32_16x16x32_bf16(Bt[n][k], At[m][k], acc[ai][bj][m][n], 0, 0, 0); __builtin_amdgcn_s_setprio(0); } while (0)
; #define PG8_WAIT_V(n) asm volatile("s_waitcnt vmcnt(" #n ")" ::: "memory")
; #define PG8_WAIT_L(n) asm volatile("s_waitcnt lgkmcnt(" #n ")" ::: "memory")
; #define PG8_BAR __builtin_amdgcn_s_barrier()
; #define PG8_SCHED __builtin_amdgcn_sched_barrier(0)
; template <class Epi>
; __device__ __forceinline__ void gemm_phase(LAS unsigned char* lds, const Gemm g, const StaticOrder& S, const Epi& E) {
;     ...
;             PG8_LDB(B0, 0, 0); PG8_LDB(B1, 0, 1); PG8_SCHED; PG8_LDA(At, 0, 0); PG8_STAGE(PG8_SA(1, 1), a1 + hsA, voffA);
;             PG8_WAIT_V(8); PG8_WAIT_L(0); PG8_BAR; PG8_MMA(0, 0, At, B0); PG8_MMA(0, 1, At, B1); PG8_BAR; PG8_SCHED;
;             PG8_LDA(At, 0, 1); PG8_STAGE(PG8_SB(0, 0), b2, voffB); PG8_STAGE(PG8_SB(0, 1), b2 + hsB, voffB); PG8_STAGE(PG8_SA(0, 0), a2, voffA);
;             PG8_WAIT_V(8); PG8_WAIT_L(0); PG8_BAR; PG8_MMA(1, 0, At, B0); PG8_MMA(1, 1, At, B1); PG8_BAR; PG8_SCHED;
.LBB0_414:
	ds_read_b128 v[152:155], v167
	ds_read_b128 v[156:159], v167 offset:1024
	ds_read_b128 v[162:165], v167 offset:2048
	ds_read_b128 v[180:183], v167 offset:3072
	ds_read_b128 v[184:187], v168
	ds_read_b128 v[188:191], v168 offset:1024
	ds_read_b128 v[192:195], v168 offset:2048
	ds_read_b128 v[196:199], v168 offset:3072
	s_add_u32 s12, s10, 0xfffc0080
	s_addc_u32 s13, s11, -1
	s_cmp_eq_u32 s17, 12
	s_cselect_b32 s87, s0, s13
	s_cselect_b32 s86, s2, s12
	s_cselect_b32 s13, s3, s15
	s_cselect_b32 s12, s6, s7
	v_lshl_add_u64 v[232:233], s[10:11], 0, v[144:145]
	s_add_i32 m0, s5, 0xc000
	ds_read_b128 v[200:203], v169
	ds_read_b128 v[204:207], v169 offset:1024
	ds_read_b128 v[208:211], v169 offset:2048
	ds_read_b128 v[212:215], v169 offset:3072
	ds_read_b128 v[216:219], v169 offset:4096
	ds_read_b128 v[220:223], v169 offset:5120
	ds_read_b128 v[224:227], v169 offset:6144
	ds_read_b128 v[228:231], v169 offset:7168
	global_load_lds_dwordx4 v[232:233], off
	v_lshl_add_u64 v[232:233], s[10:11], 0, v[146:147]
	s_add_i32 m0, s5, 0xe000
	s_nop 0
	global_load_lds_dwordx4 v[232:233], off
	s_waitcnt vmcnt(8)
	s_waitcnt lgkmcnt(0)
	s_barrier
	s_setprio 1
	s_waitcnt lgkmcnt(0)
	v_mfma_f32_16x16x32_bf16 v[124:127], v[152:155], v[200:203], v[124:127]
	v_mfma_f32_16x16x32_bf16 v[120:123], v[162:165], v[200:203], v[120:123]
	v_mfma_f32_16x16x32_bf16 v[108:111], v[152:155], v[208:211], v[108:111]
	v_mfma_f32_16x16x32_bf16 v[104:107], v[162:165], v[208:211], v[104:107]
	v_mfma_f32_16x16x32_bf16 v[92:95], v[152:155], v[216:219], v[92:95]
	v_mfma_f32_16x16x32_bf16 v[88:91], v[162:165], v[216:219], v[88:91]
	v_mfma_f32_16x16x32_bf16 v[76:79], v[152:155], v[224:227], v[76:79]
	v_mfma_f32_16x16x32_bf16 v[72:75], v[162:165], v[224:227], v[72:75]
	v_mfma_f32_16x16x32_bf16 v[124:127], v[156:159], v[204:207], v[124:127]
	v_mfma_f32_16x16x32_bf16 v[120:123], v[180:183], v[204:207], v[120:123]
	v_mfma_f32_16x16x32_bf16 v[108:111], v[156:159], v[212:215], v[108:111]
	v_mfma_f32_16x16x32_bf16 v[104:107], v[180:183], v[212:215], v[104:107]
	v_mfma_f32_16x16x32_bf16 v[92:95], v[156:159], v[220:223], v[92:95]
	v_mfma_f32_16x16x32_bf16 v[88:91], v[180:183], v[220:223], v[88:91]
	v_mfma_f32_16x16x32_bf16 v[76:79], v[156:159], v[228:231], v[76:79]
	v_mfma_f32_16x16x32_bf16 v[72:75], v[180:183], v[228:231], v[72:75]
	s_setprio 0
	s_setprio 1
	v_mfma_f32_16x16x32_bf16 v[116:119], v[184:187], v[200:203], v[116:119]
	v_mfma_f32_16x16x32_bf16 v[112:115], v[192:195], v[200:203], v[112:115]
	v_mfma_f32_16x16x32_bf16 v[100:103], v[184:187], v[208:211], v[100:103]
	v_mfma_f32_16x16x32_bf16 v[96:99], v[192:195], v[208:211], v[96:99]
	v_mfma_f32_16x16x32_bf16 v[84:87], v[184:187], v[216:219], v[84:87]
	v_mfma_f32_16x16x32_bf16 v[80:83], v[192:195], v[216:219], v[80:83]
	v_mfma_f32_16x16x32_bf16 v[68:71], v[184:187], v[224:227], v[68:71]
	v_mfma_f32_16x16x32_bf16 v[64:67], v[192:195], v[224:227], v[64:67]
	v_mfma_f32_16x16x32_bf16 v[116:119], v[188:191], v[204:207], v[116:119]
	v_mfma_f32_16x16x32_bf16 v[112:115], v[196:199], v[204:207], v[112:115]
	v_mfma_f32_16x16x32_bf16 v[100:103], v[188:191], v[212:215], v[100:103]
	v_mfma_f32_16x16x32_bf16 v[96:99], v[196:199], v[212:215], v[96:99]
	v_mfma_f32_16x16x32_bf16 v[84:87], v[188:191], v[220:223], v[84:87]
	v_mfma_f32_16x16x32_bf16 v[80:83], v[196:199], v[220:223], v[80:83]
	v_mfma_f32_16x16x32_bf16 v[68:71], v[188:191], v[228:231], v[68:71]
	v_mfma_f32_16x16x32_bf16 v[64:67], v[196:199], v[228:231], v[64:67]
	s_setprio 3
	s_barrier
	s_add_i32 s19, s65, s4
	v_lshl_add_u64 v[232:233], s[12:13], 0, v[130:131]
	s_mov_b32 m0, s19
	ds_read_b128 v[200:203], v169 offset:16384
	ds_read_b128 v[204:207], v169 offset:17408
	ds_read_b128 v[208:211], v169 offset:18432
	ds_read_b128 v[212:215], v169 offset:19456
	ds_read_b128 v[216:219], v169 offset:20480
	ds_read_b128 v[220:223], v169 offset:21504
	ds_read_b128 v[224:227], v169 offset:22528
	ds_read_b128 v[228:231], v169 offset:23552
	global_load_lds_dwordx4 v[232:233], off
	s_add_i32 m0, s19, 0x2000
	s_add_u32 s24, s12, 0x40000
	v_lshl_add_u64 v[234:235], s[12:13], 0, v[134:135]
	s_addc_u32 s25, s13, 0
	s_add_i32 s19, s76, s4
	global_load_lds_dwordx4 v[234:235], off
	v_lshl_add_u64 v[236:237], s[24:25], 0, v[130:131]
	s_mov_b32 m0, s19
	v_lshl_add_u64 v[238:239], s[86:87], 0, v[132:133]
	global_load_lds_dwordx4 v[236:237], off
	v_lshl_add_u64 v[236:237], s[24:25], 0, v[134:135]
	s_add_i32 m0, s19, 0x2000
	s_nop 0
	global_load_lds_dwordx4 v[236:237], off
	v_lshl_add_u64 v[236:237], s[86:87], 0, v[128:129]
	s_mov_b32 m0, s5
	s_nop 0
	global_load_lds_dwordx4 v[236:237], off
	s_mov_b32 m0, s62
	s_nop 0
	global_load_lds_dwordx4 v[238:239], off
	s_waitcnt vmcnt(8)
	s_waitcnt lgkmcnt(0)
	s_barrier
; #define PG8_STAGE(bufoff, gbase, voff) do { _Pragma("unroll") for (int _i = 0; _i < 2; ++_i) \
;         __builtin_amdgcn_global_load_lds((const unsigned*)((const char*)(gbase) + (voff)[_i]), (LAS unsigned*)(lds + (bufoff) + ldsw + _i * 8192), 16, 0, 0); } while (0)
; #define PG8_LDA(dst, b, h) do { _Pragma("unroll") for (int m = 0; m < 4; ++m) _Pragma("unroll") for (int k = 0; k < 2; ++k) dst[m][k] = *(const LAS bf16x8*)(lds + PG8_SA(b, h) + aoff + m * 2048 + k * 1024); } while (0)
; #define PG8_LDB(dst, b, h) do { _Pragma("unroll") for (int n = 0; n < 2; ++n) _Pragma("unroll") for (int k = 0; k < 2; ++k) dst[n][k] = *(const LAS bf16x8*)(lds + PG8_SB(b, h) + boff + n * 2048 + k * 1024); } while (0)
; #define PG8_MMA(ai, bj, At, Bt) do { __builtin_amdgcn_s_setprio(1); _Pragma("unroll") for (int m = 0; m < 4; ++m) _Pragma("unroll") for (int n = 0; n < 2; ++n) _Pragma("unroll") for (int k = 0; k < 2; ++k) \
;         acc[ai][bj][m][n] = __builtin_amdgcn_mfma_f32_16x16x32_bf16(Bt[n][k], At[m][k], acc[ai][bj][m][n], 0, 0, 0); __builtin_amdgcn_s_setprio(0); } while (0)
; #define PG8_WAIT_V(n) asm volatile("s_waitcnt vmcnt(" #n ")" ::: "memory")
; #define PG8_WAIT_L(n) asm volatile("s_waitcnt lgkmcnt(" #n ")" ::: "memory")
; #define PG8_BAR __builtin_amdgcn_s_barrier()
; #define PG8_SCHED __builtin_amdgcn_sched_barrier(0)
; template <class Epi>
; __device__ __forceinline__ void gemm_phase(LAS unsigned char* lds, const Gemm g, const StaticOrder& S, const Epi& E) {
;     ...
;             PG8_WAIT_V(8); PG8_WAIT_L(0); PG8_BAR; PG8_MMA(1, 0, At, B0); PG8_MMA(1, 1, At, B1); PG8_BAR; PG8_SCHED;
;             PG8_LDB(B0, 1, 0); PG8_LDB(B1, 1, 1); PG8_SCHED; PG8_LDA(At, 1, 0); PG8_STAGE(PG8_SA(0, 1), a2 + hsA, voffA);
;             PG8_WAIT_V(8); PG8_WAIT_L(0); PG8_BAR; PG8_MMA(0, 0, At, B0); PG8_MMA(0, 1, At, B1); PG8_BAR; PG8_SCHED;
	s_setprio 1
	s_waitcnt lgkmcnt(0)
	v_mfma_f32_16x16x32_bf16 v[60:63], v[152:155], v[200:203], v[60:63]
	v_mfma_f32_16x16x32_bf16 v[56:59], v[162:165], v[200:203], v[56:59]
	v_mfma_f32_16x16x32_bf16 v[44:47], v[152:155], v[208:211], v[44:47]
	v_mfma_f32_16x16x32_bf16 v[40:43], v[162:165], v[208:211], v[40:43]
	v_mfma_f32_16x16x32_bf16 v[28:31], v[152:155], v[216:219], v[28:31]
	v_mfma_f32_16x16x32_bf16 v[24:27], v[162:165], v[216:219], v[24:27]
	v_mfma_f32_16x16x32_bf16 v[12:15], v[152:155], v[224:227], v[12:15]
	v_mfma_f32_16x16x32_bf16 v[8:11], v[162:165], v[224:227], v[8:11]
	v_mfma_f32_16x16x32_bf16 v[60:63], v[156:159], v[204:207], v[60:63]
	v_mfma_f32_16x16x32_bf16 v[56:59], v[180:183], v[204:207], v[56:59]
	v_mfma_f32_16x16x32_bf16 v[44:47], v[156:159], v[212:215], v[44:47]
	v_mfma_f32_16x16x32_bf16 v[40:43], v[180:183], v[212:215], v[40:43]
	v_mfma_f32_16x16x32_bf16 v[28:31], v[156:159], v[220:223], v[28:31]
	v_mfma_f32_16x16x32_bf16 v[24:27], v[180:183], v[220:223], v[24:27]
	v_mfma_f32_16x16x32_bf16 v[12:15], v[156:159], v[228:231], v[12:15]
	v_mfma_f32_16x16x32_bf16 v[8:11], v[180:183], v[228:231], v[8:11]
	s_setprio 0
	s_setprio 1
	v_mfma_f32_16x16x32_bf16 v[52:55], v[184:187], v[200:203], v[52:55]
	v_mfma_f32_16x16x32_bf16 v[48:51], v[192:195], v[200:203], v[48:51]
	v_mfma_f32_16x16x32_bf16 v[36:39], v[184:187], v[208:211], v[36:39]
	v_mfma_f32_16x16x32_bf16 v[32:35], v[192:195], v[208:211], v[32:35]
	v_mfma_f32_16x16x32_bf16 v[20:23], v[184:187], v[216:219], v[20:23]
	v_mfma_f32_16x16x32_bf16 v[16:19], v[192:195], v[216:219], v[16:19]
	v_mfma_f32_16x16x32_bf16 v[4:7], v[184:187], v[224:227], v[4:7]
	v_mfma_f32_16x16x32_bf16 v[0:3], v[192:195], v[224:227], v[0:3]
	v_mfma_f32_16x16x32_bf16 v[52:55], v[188:191], v[204:207], v[52:55]
	v_mfma_f32_16x16x32_bf16 v[48:51], v[196:199], v[204:207], v[48:51]
	v_mfma_f32_16x16x32_bf16 v[36:39], v[188:191], v[212:215], v[36:39]
	v_mfma_f32_16x16x32_bf16 v[32:35], v[196:199], v[212:215], v[32:35]
	v_mfma_f32_16x16x32_bf16 v[20:23], v[188:191], v[220:223], v[20:23]
	v_mfma_f32_16x16x32_bf16 v[16:19], v[196:199], v[220:223], v[16:19]
	v_mfma_f32_16x16x32_bf16 v[4:7], v[188:191], v[228:231], v[4:7]
	v_mfma_f32_16x16x32_bf16 v[0:3], v[196:199], v[228:231], v[0:3]
	s_setprio 3
	s_barrier
	s_add_i32 s19, 0, 0x18000
	v_add_u32_e32 v136, s19, v166
	s_add_i32 s22, 0, 0x1c000
	ds_read_b128 v[152:155], v136
	ds_read_b128 v[156:159], v136 offset:1024
	ds_read_b128 v[162:165], v136 offset:2048
	ds_read_b128 v[180:183], v136 offset:3072
	v_add_u32_e32 v136, s22, v166
	ds_read_b128 v[184:187], v136
	ds_read_b128 v[188:191], v136 offset:1024
	ds_read_b128 v[192:195], v136 offset:2048
	ds_read_b128 v[196:199], v136 offset:3072
	s_add_u32 s24, s86, 0x40000
	s_addc_u32 s25, s87, 0
	s_mov_b32 m0, s63
	v_lshl_add_u64 v[240:241], s[24:25], 0, v[128:129]
	ds_read_b128 v[200:203], v169 offset:32768
	ds_read_b128 v[204:207], v169 offset:33792
	ds_read_b128 v[208:211], v169 offset:34816
	ds_read_b128 v[212:215], v169 offset:35840
	ds_read_b128 v[216:219], v169 offset:36864
	ds_read_b128 v[220:223], v169 offset:37888
	ds_read_b128 v[224:227], v169 offset:38912
	ds_read_b128 v[228:231], v169 offset:39936
	global_load_lds_dwordx4 v[240:241], off
	v_lshl_add_u64 v[240:241], s[24:25], 0, v[132:133]
	s_mov_b32 m0, s74
	s_nop 0
	global_load_lds_dwordx4 v[240:241], off
	s_waitcnt vmcnt(8)
	s_waitcnt lgkmcnt(0)
	s_barrier
	s_setprio 1
	s_waitcnt lgkmcnt(0)
	v_mfma_f32_16x16x32_bf16 v[124:127], v[152:155], v[200:203], v[124:127]
	v_mfma_f32_16x16x32_bf16 v[120:123], v[162:165], v[200:203], v[120:123]
	v_mfma_f32_16x16x32_bf16 v[108:111], v[152:155], v[208:211], v[108:111]
	v_mfma_f32_16x16x32_bf16 v[104:107], v[162:165], v[208:211], v[104:107]
	v_mfma_f32_16x16x32_bf16 v[92:95], v[152:155], v[216:219], v[92:95]
	v_mfma_f32_16x16x32_bf16 v[88:91], v[162:165], v[216:219], v[88:91]
	v_mfma_f32_16x16x32_bf16 v[76:79], v[152:155], v[224:227], v[76:79]
	v_mfma_f32_16x16x32_bf16 v[72:75], v[162:165], v[224:227], v[72:75]
	v_mfma_f32_16x16x32_bf16 v[124:127], v[156:159], v[204:207], v[124:127]
	v_mfma_f32_16x16x32_bf16 v[120:123], v[180:183], v[204:207], v[120:123]
	v_mfma_f32_16x16x32_bf16 v[108:111], v[156:159], v[212:215], v[108:111]
	v_mfma_f32_16x16x32_bf16 v[104:107], v[180:183], v[212:215], v[104:107]
	v_mfma_f32_16x16x32_bf16 v[92:95], v[156:159], v[220:223], v[92:95]
	v_mfma_f32_16x16x32_bf16 v[88:91], v[180:183], v[220:223], v[88:91]
	v_mfma_f32_16x16x32_bf16 v[76:79], v[156:159], v[228:231], v[76:79]
	v_mfma_f32_16x16x32_bf16 v[72:75], v[180:183], v[228:231], v[72:75]
	s_setprio 0
	s_setprio 1
	v_mfma_f32_16x16x32_bf16 v[116:119], v[184:187], v[200:203], v[116:119]
	v_mfma_f32_16x16x32_bf16 v[112:115], v[192:195], v[200:203], v[112:115]
	v_mfma_f32_16x16x32_bf16 v[100:103], v[184:187], v[208:211], v[100:103]
	v_mfma_f32_16x16x32_bf16 v[96:99], v[192:195], v[208:211], v[96:99]
	v_mfma_f32_16x16x32_bf16 v[84:87], v[184:187], v[216:219], v[84:87]
	v_mfma_f32_16x16x32_bf16 v[80:83], v[192:195], v[216:219], v[80:83]
	v_mfma_f32_16x16x32_bf16 v[68:71], v[184:187], v[224:227], v[68:71]
	v_mfma_f32_16x16x32_bf16 v[64:67], v[192:195], v[224:227], v[64:67]
	v_mfma_f32_16x16x32_bf16 v[116:119], v[188:191], v[204:207], v[116:119]
	v_mfma_f32_16x16x32_bf16 v[112:115], v[196:199], v[204:207], v[112:115]
	v_mfma_f32_16x16x32_bf16 v[100:103], v[188:191], v[212:215], v[100:103]
	v_mfma_f32_16x16x32_bf16 v[96:99], v[196:199], v[212:215], v[96:99]
	v_mfma_f32_16x16x32_bf16 v[84:87], v[188:191], v[220:223], v[84:87]
	v_mfma_f32_16x16x32_bf16 v[80:83], v[196:199], v[220:223], v[80:83]
	v_mfma_f32_16x16x32_bf16 v[68:71], v[188:191], v[228:231], v[68:71]
	v_mfma_f32_16x16x32_bf16 v[64:67], v[196:199], v[228:231], v[64:67]
	s_setprio 3
	s_barrier
; #define PG8_STAGE(bufoff, gbase, voff) do { _Pragma("unroll") for (int _i = 0; _i < 2; ++_i) \
;         __builtin_amdgcn_global_load_lds((const unsigned*)((const char*)(gbase) + (voff)[_i]), (LAS unsigned*)(lds + (bufoff) + ldsw + _i * 8192), 16, 0, 0); } while (0)
; #define PG8_LDA(dst, b, h) do { _Pragma("unroll") for (int m = 0; m < 4; ++m) _Pragma("unroll") for (int k = 0; k < 2; ++k) dst[m][k] = *(const LAS bf16x8*)(lds + PG8_SA(b, h) + aoff + m * 2048 + k * 1024); } while (0)
; #define PG8_MMA(ai, bj, At, Bt) do { __builtin_amdgcn_s_setprio(1); _Pragma("unroll") for (int m = 0; m < 4; ++m) _Pragma("unroll") for (int n = 0; n < 2; ++n) _Pragma("unroll") for (int k = 0; k < 2; ++k) \
;         acc[ai][bj][m][n] = __builtin_amdgcn_mfma_f32_16x16x32_bf16(Bt[n][k], At[m][k], acc[ai][bj][m][n], 0, 0, 0); __builtin_amdgcn_s_setprio(0); } while (0)
; #define PG8_WAIT_V(n) asm volatile("s_waitcnt vmcnt(" #n ")" ::: "memory")
; #define PG8_WAIT_L(n) asm volatile("s_waitcnt lgkmcnt(" #n ")" ::: "memory")
; #define PG8_BAR __builtin_amdgcn_s_barrier()
; #define PG8_SCHED __builtin_amdgcn_sched_barrier(0)
; template <class Epi>
; __device__ __forceinline__ void gemm_phase(LAS unsigned char* lds, const Gemm g, const StaticOrder& S, const Epi& E) {
;     ...
;             PG8_LDA(At, 1, 1); PG8_STAGE(PG8_SB(1, 0), b3, voffB); PG8_STAGE(PG8_SB(1, 1), b3 + hsB, voffB); PG8_STAGE(PG8_SA(1, 0), a3, voffA);
;             PG8_WAIT_V(8); PG8_WAIT_L(0); PG8_BAR; PG8_MMA(1, 0, At, B0); PG8_MMA(1, 1, At, B1); PG8_BAR; PG8_SCHED;
;         }
	s_add_i32 s19, s19, s4
	v_lshl_add_u64 v[232:233], v[232:233], 0, s[52:53]
	s_mov_b32 m0, s19
	ds_read_b128 v[200:203], v169 offset:49152
	ds_read_b128 v[204:207], v169 offset:50176
	ds_read_b128 v[208:211], v169 offset:51200
	ds_read_b128 v[212:215], v169 offset:52224
	ds_read_b128 v[216:219], v169 offset:53248
	ds_read_b128 v[220:223], v169 offset:54272
	ds_read_b128 v[224:227], v169 offset:55296
	ds_read_b128 v[228:231], v169 offset:56320
	global_load_lds_dwordx4 v[232:233], off
	s_add_i32 m0, s19, 0x2000
	s_add_u32 s12, s12, 0x40080
	v_lshl_add_u64 v[232:233], v[234:235], 0, s[52:53]
	s_addc_u32 s13, s13, 0
	s_add_i32 s19, s22, s4
	global_load_lds_dwordx4 v[232:233], off
	v_lshl_add_u64 v[232:233], s[12:13], 0, v[130:131]
	s_mov_b32 m0, s19
	s_nop 0
	global_load_lds_dwordx4 v[232:233], off
	v_lshl_add_u64 v[232:233], s[12:13], 0, v[134:135]
	s_add_i32 m0, s19, 0x2000
	s_nop 0
	global_load_lds_dwordx4 v[232:233], off
	v_lshl_add_u64 v[232:233], v[236:237], 0, s[52:53]
	s_mov_b32 m0, s16
	s_nop 0
	global_load_lds_dwordx4 v[232:233], off
	v_lshl_add_u64 v[232:233], v[238:239], 0, s[52:53]
	s_mov_b32 m0, s33
	s_nop 0
	global_load_lds_dwordx4 v[232:233], off
	s_waitcnt vmcnt(8)
	s_waitcnt lgkmcnt(0)
	s_barrier
	s_setprio 1
	s_waitcnt lgkmcnt(0)
	v_mfma_f32_16x16x32_bf16 v[60:63], v[152:155], v[200:203], v[60:63]
	v_mfma_f32_16x16x32_bf16 v[56:59], v[162:165], v[200:203], v[56:59]
	v_mfma_f32_16x16x32_bf16 v[44:47], v[152:155], v[208:211], v[44:47]
	v_mfma_f32_16x16x32_bf16 v[40:43], v[162:165], v[208:211], v[40:43]
	v_mfma_f32_16x16x32_bf16 v[28:31], v[152:155], v[216:219], v[28:31]
	v_mfma_f32_16x16x32_bf16 v[24:27], v[162:165], v[216:219], v[24:27]
	v_mfma_f32_16x16x32_bf16 v[12:15], v[152:155], v[224:227], v[12:15]
	v_mfma_f32_16x16x32_bf16 v[8:11], v[162:165], v[224:227], v[8:11]
	v_mfma_f32_16x16x32_bf16 v[60:63], v[156:159], v[204:207], v[60:63]
	v_mfma_f32_16x16x32_bf16 v[56:59], v[180:183], v[204:207], v[56:59]
	v_mfma_f32_16x16x32_bf16 v[44:47], v[156:159], v[212:215], v[44:47]
	v_mfma_f32_16x16x32_bf16 v[40:43], v[180:183], v[212:215], v[40:43]
	v_mfma_f32_16x16x32_bf16 v[28:31], v[156:159], v[220:223], v[28:31]
	v_mfma_f32_16x16x32_bf16 v[24:27], v[180:183], v[220:223], v[24:27]
	v_mfma_f32_16x16x32_bf16 v[12:15], v[156:159], v[228:231], v[12:15]
	v_mfma_f32_16x16x32_bf16 v[8:11], v[180:183], v[228:231], v[8:11]
	s_setprio 0
	s_setprio 1
	v_mfma_f32_16x16x32_bf16 v[52:55], v[184:187], v[200:203], v[52:55]
	v_mfma_f32_16x16x32_bf16 v[48:51], v[192:195], v[200:203], v[48:51]
	v_mfma_f32_16x16x32_bf16 v[36:39], v[184:187], v[208:211], v[36:39]
	v_mfma_f32_16x16x32_bf16 v[32:35], v[192:195], v[208:211], v[32:35]
	v_mfma_f32_16x16x32_bf16 v[20:23], v[184:187], v[216:219], v[20:23]
	v_mfma_f32_16x16x32_bf16 v[16:19], v[192:195], v[216:219], v[16:19]
	v_mfma_f32_16x16x32_bf16 v[4:7], v[184:187], v[224:227], v[4:7]
	v_mfma_f32_16x16x32_bf16 v[0:3], v[192:195], v[224:227], v[0:3]
	v_mfma_f32_16x16x32_bf16 v[52:55], v[188:191], v[204:207], v[52:55]
	v_mfma_f32_16x16x32_bf16 v[48:51], v[196:199], v[204:207], v[48:51]
	v_mfma_f32_16x16x32_bf16 v[36:39], v[188:191], v[212:215], v[36:39]
	v_mfma_f32_16x16x32_bf16 v[32:35], v[196:199], v[212:215], v[32:35]
	v_mfma_f32_16x16x32_bf16 v[20:23], v[188:191], v[220:223], v[20:23]
	v_mfma_f32_16x16x32_bf16 v[16:19], v[196:199], v[220:223], v[16:19]
	v_mfma_f32_16x16x32_bf16 v[4:7], v[188:191], v[228:231], v[4:7]
	v_mfma_f32_16x16x32_bf16 v[0:3], v[196:199], v[228:231], v[0:3]
	s_setprio 3
	s_barrier
	s_add_i32 s17, s17, 2
	s_add_u32 s10, s10, 0x100
	s_addc_u32 s11, s11, 0
	s_add_u32 s7, s7, 0x100
	s_addc_u32 s15, s15, 0
	s_cmp_gt_u32 s17, 13
	s_cbranch_scc0 .LBB0_414
	s_and_b64 vcc, exec, s[58:59]
	s_cbranch_vccz .LBB0_417
	s_barrier

; #define PG8_STAGE(bufoff, gbase, voff) do { _Pragma("unroll") for (int _i = 0; _i < 2; ++_i) \
;         __builtin_amdgcn_global_load_lds((const unsigned*)((const char*)(gbase) + (voff)[_i]), (LAS unsigned*)(lds + (bufoff) + ldsw + _i * 8192), 16, 0, 0); } while (0)
; #define PG8_LDA(dst, b, h) do { _Pragma("unroll") for (int m = 0; m < 4; ++m) _Pragma("unroll") for (int k = 0; k < 2; ++k) dst[m][k] = *(const LAS bf16x8*)(lds + PG8_SA(b, h) + aoff + m * 2048 + k * 1024); } while (0)
; #define PG8_LDB(dst, b, h) do { _Pragma("unroll") for (int n = 0; n < 2; ++n) _Pragma("unroll") for (int k = 0; k < 2; ++k) dst[n][k] = *(const LAS bf16x8*)(lds + PG8_SB(b, h) + boff + n * 2048 + k * 1024); } while (0)
; #define PG8_MMA(ai, bj, At, Bt) do { __builtin_amdgcn_s_setprio(1); _Pragma("unroll") for (int m = 0; m < 4; ++m) _Pragma("unroll") for (int n = 0; n < 2; ++n) _Pragma("unroll") for (int k = 0; k < 2; ++k) \
;         acc[ai][bj][m][n] = __builtin_amdgcn_mfma_f32_16x16x32_bf16(Bt[n][k], At[m][k], acc[ai][bj][m][n], 0, 0, 0); __builtin_amdgcn_s_setprio(0); } while (0)
; #define PG8_WAIT_V(n) asm volatile("s_waitcnt vmcnt(" #n ")" ::: "memory")
; #define PG8_WAIT_L(n) asm volatile("s_waitcnt lgkmcnt(" #n ")" ::: "memory")
; #define PG8_BAR __builtin_amdgcn_s_barrier()
; #define PG8_SCHED __builtin_amdgcn_sched_barrier(0)
; template <class Epi>
; __device__ __forceinline__ void gemm_phase(LAS unsigned char* lds, const Gemm g, const StaticOrder& S, const Epi& E) {
;     ...
;             PG8_LDB(B0, 0, 0); PG8_LDB(B1, 0, 1); PG8_SCHED; PG8_LDA(At, 0, 0); PG8_STAGE(PG8_SA(1, 1), a1 + hsA, voffA);
;             PG8_WAIT_V(8); PG8_WAIT_L(0); PG8_BAR; PG8_MMA(0, 0, At, B0); PG8_MMA(0, 1, At, B1); PG8_BAR; PG8_SCHED;
;             PG8_LDA(At, 0, 1); PG8_STAGE(PG8_SB(0, 0), b2, voffB); PG8_STAGE(PG8_SB(0, 1), b2 + hsB, voffB); PG8_STAGE(PG8_SA(0, 0), a2, voffA);
;             PG8_WAIT_V(8); PG8_WAIT_L(0); PG8_BAR; PG8_MMA(1, 0, At, B0); PG8_MMA(1, 1, At, B1); PG8_BAR; PG8_SCHED;
.LBB0_720:
	ds_read_b128 v[128:131], v182
	ds_read_b128 v[132:135], v182 offset:1024
	ds_read_b128 v[136:139], v182 offset:2048
	ds_read_b128 v[140:143], v182 offset:3072
	ds_read_b128 v[166:169], v183
	ds_read_b128 v[188:191], v183 offset:1024
	ds_read_b128 v[192:195], v183 offset:2048
	ds_read_b128 v[196:199], v183 offset:3072
	s_add_u32 s39, s62, 0xfffc0080
	s_addc_u32 s40, s63, -1
	s_cmp_eq_u32 s38, 12
	s_cselect_b32 s67, s6, s40
	s_cselect_b32 s66, s7, s39
	s_cselect_b32 s65, s15, s37
	s_cselect_b32 s64, s35, s36
	v_lshl_add_u64 v[170:171], s[62:63], 0, v[156:157]
	s_add_i32 m0, s4, 0xc000
	ds_read_b128 v[200:203], v184
	ds_read_b128 v[204:207], v184 offset:1024
	ds_read_b128 v[208:211], v184 offset:2048
	ds_read_b128 v[212:215], v184 offset:3072
	ds_read_b128 v[216:219], v184 offset:4096
	ds_read_b128 v[220:223], v184 offset:5120
	ds_read_b128 v[224:227], v184 offset:6144
	ds_read_b128 v[228:231], v184 offset:7168
	global_load_lds_dwordx4 v[170:171], off
	v_lshl_add_u64 v[170:171], s[62:63], 0, v[158:159]
	s_add_i32 m0, s4, 0xe000
	s_nop 0
	global_load_lds_dwordx4 v[170:171], off
	s_waitcnt vmcnt(8)
	s_waitcnt lgkmcnt(0)
	s_barrier
	s_setprio 1
	s_waitcnt lgkmcnt(0)
	v_mfma_f32_16x16x32_bf16 v[124:127], v[128:131], v[200:203], v[124:127]
	v_mfma_f32_16x16x32_bf16 v[120:123], v[136:139], v[200:203], v[120:123]
	v_mfma_f32_16x16x32_bf16 v[108:111], v[128:131], v[208:211], v[108:111]
	v_mfma_f32_16x16x32_bf16 v[104:107], v[136:139], v[208:211], v[104:107]
	v_mfma_f32_16x16x32_bf16 v[92:95], v[128:131], v[216:219], v[92:95]
	v_mfma_f32_16x16x32_bf16 v[88:91], v[136:139], v[216:219], v[88:91]
	v_mfma_f32_16x16x32_bf16 v[76:79], v[128:131], v[224:227], v[76:79]
	v_mfma_f32_16x16x32_bf16 v[72:75], v[136:139], v[224:227], v[72:75]
	v_mfma_f32_16x16x32_bf16 v[124:127], v[132:135], v[204:207], v[124:127]
	v_mfma_f32_16x16x32_bf16 v[120:123], v[140:143], v[204:207], v[120:123]
	v_mfma_f32_16x16x32_bf16 v[108:111], v[132:135], v[212:215], v[108:111]
	v_mfma_f32_16x16x32_bf16 v[104:107], v[140:143], v[212:215], v[104:107]
	v_mfma_f32_16x16x32_bf16 v[92:95], v[132:135], v[220:223], v[92:95]
	v_mfma_f32_16x16x32_bf16 v[88:91], v[140:143], v[220:223], v[88:91]
	v_mfma_f32_16x16x32_bf16 v[76:79], v[132:135], v[228:231], v[76:79]
	v_mfma_f32_16x16x32_bf16 v[72:75], v[140:143], v[228:231], v[72:75]
	s_setprio 0
	s_setprio 1
	v_mfma_f32_16x16x32_bf16 v[116:119], v[166:169], v[200:203], v[116:119]
	v_mfma_f32_16x16x32_bf16 v[112:115], v[192:195], v[200:203], v[112:115]
	v_mfma_f32_16x16x32_bf16 v[100:103], v[166:169], v[208:211], v[100:103]
	v_mfma_f32_16x16x32_bf16 v[96:99], v[192:195], v[208:211], v[96:99]
	v_mfma_f32_16x16x32_bf16 v[84:87], v[166:169], v[216:219], v[84:87]
	v_mfma_f32_16x16x32_bf16 v[80:83], v[192:195], v[216:219], v[80:83]
	v_mfma_f32_16x16x32_bf16 v[68:71], v[166:169], v[224:227], v[68:71]
	v_mfma_f32_16x16x32_bf16 v[64:67], v[192:195], v[224:227], v[64:67]
	v_mfma_f32_16x16x32_bf16 v[116:119], v[188:191], v[204:207], v[116:119]
	v_mfma_f32_16x16x32_bf16 v[112:115], v[196:199], v[204:207], v[112:115]
	v_mfma_f32_16x16x32_bf16 v[100:103], v[188:191], v[212:215], v[100:103]
	v_mfma_f32_16x16x32_bf16 v[96:99], v[196:199], v[212:215], v[96:99]
	v_mfma_f32_16x16x32_bf16 v[84:87], v[188:191], v[220:223], v[84:87]
	v_mfma_f32_16x16x32_bf16 v[80:83], v[196:199], v[220:223], v[80:83]
	v_mfma_f32_16x16x32_bf16 v[68:71], v[188:191], v[228:231], v[68:71]
	v_mfma_f32_16x16x32_bf16 v[64:67], v[196:199], v[228:231], v[64:67]
	s_setprio 3
	s_barrier
	s_add_i32 s39, s27, s3
	v_lshl_add_u64 v[170:171], s[64:65], 0, v[146:147]
	s_mov_b32 m0, s39
	ds_read_b128 v[200:203], v184 offset:16384
	ds_read_b128 v[204:207], v184 offset:17408
	ds_read_b128 v[208:211], v184 offset:18432
	ds_read_b128 v[212:215], v184 offset:19456
	ds_read_b128 v[216:219], v184 offset:20480
	ds_read_b128 v[220:223], v184 offset:21504
	ds_read_b128 v[224:227], v184 offset:22528
	ds_read_b128 v[228:231], v184 offset:23552
	global_load_lds_dwordx4 v[170:171], off
	s_add_i32 m0, s39, 0x2000
	s_add_u32 s40, s64, 0x40000
	v_lshl_add_u64 v[232:233], s[64:65], 0, v[150:151]
	s_addc_u32 s41, s65, 0
	s_add_i32 s39, s28, s3
	global_load_lds_dwordx4 v[232:233], off
	v_lshl_add_u64 v[234:235], s[40:41], 0, v[146:147]
	s_mov_b32 m0, s39
	v_lshl_add_u64 v[236:237], s[66:67], 0, v[148:149]
	global_load_lds_dwordx4 v[234:235], off
	v_lshl_add_u64 v[234:235], s[40:41], 0, v[150:151]
	s_add_i32 m0, s39, 0x2000
	s_nop 0
	global_load_lds_dwordx4 v[234:235], off
	v_lshl_add_u64 v[234:235], s[66:67], 0, v[144:145]
	s_mov_b32 m0, s4
	s_nop 0
	global_load_lds_dwordx4 v[234:235], off
	s_mov_b32 m0, s5
	s_nop 0
	global_load_lds_dwordx4 v[236:237], off
	s_waitcnt vmcnt(8)
	s_waitcnt lgkmcnt(0)
	s_barrier
; #define PG8_STAGE(bufoff, gbase, voff) do { _Pragma("unroll") for (int _i = 0; _i < 2; ++_i) \
;         __builtin_amdgcn_global_load_lds((const unsigned*)((const char*)(gbase) + (voff)[_i]), (LAS unsigned*)(lds + (bufoff) + ldsw + _i * 8192), 16, 0, 0); } while (0)
; #define PG8_LDA(dst, b, h) do { _Pragma("unroll") for (int m = 0; m < 4; ++m) _Pragma("unroll") for (int k = 0; k < 2; ++k) dst[m][k] = *(const LAS bf16x8*)(lds + PG8_SA(b, h) + aoff + m * 2048 + k * 1024); } while (0)
; #define PG8_LDB(dst, b, h) do { _Pragma("unroll") for (int n = 0; n < 2; ++n) _Pragma("unroll") for (int k = 0; k < 2; ++k) dst[n][k] = *(const LAS bf16x8*)(lds + PG8_SB(b, h) + boff + n * 2048 + k * 1024); } while (0)
; #define PG8_MMA(ai, bj, At, Bt) do { __builtin_amdgcn_s_setprio(1); _Pragma("unroll") for (int m = 0; m < 4; ++m) _Pragma("unroll") for (int n = 0; n < 2; ++n) _Pragma("unroll") for (int k = 0; k < 2; ++k) \
;         acc[ai][bj][m][n] = __builtin_amdgcn_mfma_f32_16x16x32_bf16(Bt[n][k], At[m][k], acc[ai][bj][m][n], 0, 0, 0); __builtin_amdgcn_s_setprio(0); } while (0)
; #define PG8_WAIT_V(n) asm volatile("s_waitcnt vmcnt(" #n ")" ::: "memory")
; #define PG8_WAIT_L(n) asm volatile("s_waitcnt lgkmcnt(" #n ")" ::: "memory")
; #define PG8_BAR __builtin_amdgcn_s_barrier()
; #define PG8_SCHED __builtin_amdgcn_sched_barrier(0)
; template <class Epi>
; __device__ __forceinline__ void gemm_phase(LAS unsigned char* lds, const Gemm g, const StaticOrder& S, const Epi& E) {
;     ...
;             PG8_WAIT_V(8); PG8_WAIT_L(0); PG8_BAR; PG8_MMA(1, 0, At, B0); PG8_MMA(1, 1, At, B1); PG8_BAR; PG8_SCHED;
;             PG8_LDB(B0, 1, 0); PG8_LDB(B1, 1, 1); PG8_SCHED; PG8_LDA(At, 1, 0); PG8_STAGE(PG8_SA(0, 1), a2 + hsA, voffA);
;             PG8_WAIT_V(8); PG8_WAIT_L(0); PG8_BAR; PG8_MMA(0, 0, At, B0); PG8_MMA(0, 1, At, B1); PG8_BAR; PG8_SCHED;
	s_setprio 1
	s_waitcnt lgkmcnt(0)
	v_mfma_f32_16x16x32_bf16 v[60:63], v[128:131], v[200:203], v[60:63]
	v_mfma_f32_16x16x32_bf16 v[56:59], v[136:139], v[200:203], v[56:59]
	v_mfma_f32_16x16x32_bf16 v[44:47], v[128:131], v[208:211], v[44:47]
	v_mfma_f32_16x16x32_bf16 v[40:43], v[136:139], v[208:211], v[40:43]
	v_mfma_f32_16x16x32_bf16 v[28:31], v[128:131], v[216:219], v[28:31]
	v_mfma_f32_16x16x32_bf16 v[24:27], v[136:139], v[216:219], v[24:27]
	v_mfma_f32_16x16x32_bf16 v[12:15], v[128:131], v[224:227], v[12:15]
	v_mfma_f32_16x16x32_bf16 v[8:11], v[136:139], v[224:227], v[8:11]
	v_mfma_f32_16x16x32_bf16 v[60:63], v[132:135], v[204:207], v[60:63]
	v_mfma_f32_16x16x32_bf16 v[56:59], v[140:143], v[204:207], v[56:59]
	v_mfma_f32_16x16x32_bf16 v[44:47], v[132:135], v[212:215], v[44:47]
	v_mfma_f32_16x16x32_bf16 v[40:43], v[140:143], v[212:215], v[40:43]
	v_mfma_f32_16x16x32_bf16 v[28:31], v[132:135], v[220:223], v[28:31]
	v_mfma_f32_16x16x32_bf16 v[24:27], v[140:143], v[220:223], v[24:27]
	v_mfma_f32_16x16x32_bf16 v[12:15], v[132:135], v[228:231], v[12:15]
	v_mfma_f32_16x16x32_bf16 v[8:11], v[140:143], v[228:231], v[8:11]
	s_setprio 0
	s_setprio 1
	v_mfma_f32_16x16x32_bf16 v[52:55], v[166:169], v[200:203], v[52:55]
	v_mfma_f32_16x16x32_bf16 v[48:51], v[192:195], v[200:203], v[48:51]
	v_mfma_f32_16x16x32_bf16 v[36:39], v[166:169], v[208:211], v[36:39]
	v_mfma_f32_16x16x32_bf16 v[32:35], v[192:195], v[208:211], v[32:35]
	v_mfma_f32_16x16x32_bf16 v[20:23], v[166:169], v[216:219], v[20:23]
	v_mfma_f32_16x16x32_bf16 v[16:19], v[192:195], v[216:219], v[16:19]
	v_mfma_f32_16x16x32_bf16 v[4:7], v[166:169], v[224:227], v[4:7]
	v_mfma_f32_16x16x32_bf16 v[0:3], v[192:195], v[224:227], v[0:3]
	v_mfma_f32_16x16x32_bf16 v[52:55], v[188:191], v[204:207], v[52:55]
	v_mfma_f32_16x16x32_bf16 v[48:51], v[196:199], v[204:207], v[48:51]
	v_mfma_f32_16x16x32_bf16 v[36:39], v[188:191], v[212:215], v[36:39]
	v_mfma_f32_16x16x32_bf16 v[32:35], v[196:199], v[212:215], v[32:35]
	v_mfma_f32_16x16x32_bf16 v[20:23], v[188:191], v[220:223], v[20:23]
	v_mfma_f32_16x16x32_bf16 v[16:19], v[196:199], v[220:223], v[16:19]
	v_mfma_f32_16x16x32_bf16 v[4:7], v[188:191], v[228:231], v[4:7]
	v_mfma_f32_16x16x32_bf16 v[0:3], v[196:199], v[228:231], v[0:3]
	s_setprio 3
	s_barrier
	s_add_i32 s39, 0, 0x18000
	s_add_i32 s42, 0, 0x1c000
	v_add_u32_e32 v140, s39, v173
	v_add_u32_e32 v152, s42, v173
	ds_read_b128 v[128:131], v140
	ds_read_b128 v[132:135], v140 offset:1024
	ds_read_b128 v[136:139], v140 offset:2048
	ds_read_b128 v[140:143], v140 offset:3072
	ds_read_b128 v[166:169], v152
	ds_read_b128 v[188:191], v152 offset:1024
	ds_read_b128 v[192:195], v152 offset:2048
	ds_read_b128 v[196:199], v152 offset:3072
	s_add_u32 s40, s66, 0x40000
	s_addc_u32 s41, s67, 0
	s_mov_b32 m0, s16
	v_lshl_add_u64 v[238:239], s[40:41], 0, v[144:145]
	ds_read_b128 v[200:203], v184 offset:32768
	ds_read_b128 v[204:207], v184 offset:33792
	ds_read_b128 v[208:211], v184 offset:34816
	ds_read_b128 v[212:215], v184 offset:35840
	ds_read_b128 v[216:219], v184 offset:36864
	ds_read_b128 v[220:223], v184 offset:37888
	ds_read_b128 v[224:227], v184 offset:38912
	ds_read_b128 v[228:231], v184 offset:39936
	global_load_lds_dwordx4 v[238:239], off
	v_lshl_add_u64 v[238:239], s[40:41], 0, v[148:149]
	s_mov_b32 m0, s17
	s_nop 0
	global_load_lds_dwordx4 v[238:239], off
	s_waitcnt vmcnt(8)
	s_waitcnt lgkmcnt(0)
	s_barrier
	s_setprio 1
	s_waitcnt lgkmcnt(0)
	v_mfma_f32_16x16x32_bf16 v[124:127], v[128:131], v[200:203], v[124:127]
	v_mfma_f32_16x16x32_bf16 v[120:123], v[136:139], v[200:203], v[120:123]
	v_mfma_f32_16x16x32_bf16 v[108:111], v[128:131], v[208:211], v[108:111]
	v_mfma_f32_16x16x32_bf16 v[104:107], v[136:139], v[208:211], v[104:107]
	v_mfma_f32_16x16x32_bf16 v[92:95], v[128:131], v[216:219], v[92:95]
	v_mfma_f32_16x16x32_bf16 v[88:91], v[136:139], v[216:219], v[88:91]
	v_mfma_f32_16x16x32_bf16 v[76:79], v[128:131], v[224:227], v[76:79]
	v_mfma_f32_16x16x32_bf16 v[72:75], v[136:139], v[224:227], v[72:75]
	v_mfma_f32_16x16x32_bf16 v[124:127], v[132:135], v[204:207], v[124:127]
	v_mfma_f32_16x16x32_bf16 v[120:123], v[140:143], v[204:207], v[120:123]
	v_mfma_f32_16x16x32_bf16 v[108:111], v[132:135], v[212:215], v[108:111]
	v_mfma_f32_16x16x32_bf16 v[104:107], v[140:143], v[212:215], v[104:107]
	v_mfma_f32_16x16x32_bf16 v[92:95], v[132:135], v[220:223], v[92:95]
	v_mfma_f32_16x16x32_bf16 v[88:91], v[140:143], v[220:223], v[88:91]
	v_mfma_f32_16x16x32_bf16 v[76:79], v[132:135], v[228:231], v[76:79]
	v_mfma_f32_16x16x32_bf16 v[72:75], v[140:143], v[228:231], v[72:75]
	s_setprio 0
	s_setprio 1
	v_mfma_f32_16x16x32_bf16 v[116:119], v[166:169], v[200:203], v[116:119]
	v_mfma_f32_16x16x32_bf16 v[112:115], v[192:195], v[200:203], v[112:115]
	v_mfma_f32_16x16x32_bf16 v[100:103], v[166:169], v[208:211], v[100:103]
	v_mfma_f32_16x16x32_bf16 v[96:99], v[192:195], v[208:211], v[96:99]
	v_mfma_f32_16x16x32_bf16 v[84:87], v[166:169], v[216:219], v[84:87]
	v_mfma_f32_16x16x32_bf16 v[80:83], v[192:195], v[216:219], v[80:83]
	v_mfma_f32_16x16x32_bf16 v[68:71], v[166:169], v[224:227], v[68:71]
	v_mfma_f32_16x16x32_bf16 v[64:67], v[192:195], v[224:227], v[64:67]
	v_mfma_f32_16x16x32_bf16 v[116:119], v[188:191], v[204:207], v[116:119]
	v_mfma_f32_16x16x32_bf16 v[112:115], v[196:199], v[204:207], v[112:115]
	v_mfma_f32_16x16x32_bf16 v[100:103], v[188:191], v[212:215], v[100:103]
	v_mfma_f32_16x16x32_bf16 v[96:99], v[196:199], v[212:215], v[96:99]
	v_mfma_f32_16x16x32_bf16 v[84:87], v[188:191], v[220:223], v[84:87]
	v_mfma_f32_16x16x32_bf16 v[80:83], v[196:199], v[220:223], v[80:83]
	v_mfma_f32_16x16x32_bf16 v[68:71], v[188:191], v[228:231], v[68:71]
	v_mfma_f32_16x16x32_bf16 v[64:67], v[196:199], v[228:231], v[64:67]
	s_setprio 3
	s_barrier
; #define PG8_STAGE(bufoff, gbase, voff) do { _Pragma("unroll") for (int _i = 0; _i < 2; ++_i) \
;         __builtin_amdgcn_global_load_lds((const unsigned*)((const char*)(gbase) + (voff)[_i]), (LAS unsigned*)(lds + (bufoff) + ldsw + _i * 8192), 16, 0, 0); } while (0)
; #define PG8_LDA(dst, b, h) do { _Pragma("unroll") for (int m = 0; m < 4; ++m) _Pragma("unroll") for (int k = 0; k < 2; ++k) dst[m][k] = *(const LAS bf16x8*)(lds + PG8_SA(b, h) + aoff + m * 2048 + k * 1024); } while (0)
; #define PG8_MMA(ai, bj, At, Bt) do { __builtin_amdgcn_s_setprio(1); _Pragma("unroll") for (int m = 0; m < 4; ++m) _Pragma("unroll") for (int n = 0; n < 2; ++n) _Pragma("unroll") for (int k = 0; k < 2; ++k) \
;         acc[ai][bj][m][n] = __builtin_amdgcn_mfma_f32_16x16x32_bf16(Bt[n][k], At[m][k], acc[ai][bj][m][n], 0, 0, 0); __builtin_amdgcn_s_setprio(0); } while (0)
; #define PG8_WAIT_V(n) asm volatile("s_waitcnt vmcnt(" #n ")" ::: "memory")
; #define PG8_WAIT_L(n) asm volatile("s_waitcnt lgkmcnt(" #n ")" ::: "memory")
; #define PG8_BAR __builtin_amdgcn_s_barrier()
; #define PG8_SCHED __builtin_amdgcn_sched_barrier(0)
; template <class Epi>
; __device__ __forceinline__ void gemm_phase(LAS unsigned char* lds, const Gemm g, const StaticOrder& S, const Epi& E) {
;     ...
;             PG8_LDA(At, 1, 1); PG8_STAGE(PG8_SB(1, 0), b3, voffB); PG8_STAGE(PG8_SB(1, 1), b3 + hsB, voffB); PG8_STAGE(PG8_SA(1, 0), a3, voffA);
;             PG8_WAIT_V(8); PG8_WAIT_L(0); PG8_BAR; PG8_MMA(1, 0, At, B0); PG8_MMA(1, 1, At, B1); PG8_BAR; PG8_SCHED;
;         }
	s_add_i32 s39, s39, s3
	v_lshl_add_u64 v[170:171], v[170:171], 0, s[10:11]
	s_mov_b32 m0, s39
	ds_read_b128 v[200:203], v184 offset:49152
	ds_read_b128 v[204:207], v184 offset:50176
	ds_read_b128 v[208:211], v184 offset:51200
	ds_read_b128 v[212:215], v184 offset:52224
	ds_read_b128 v[216:219], v184 offset:53248
	ds_read_b128 v[220:223], v184 offset:54272
	ds_read_b128 v[224:227], v184 offset:55296
	ds_read_b128 v[228:231], v184 offset:56320
	global_load_lds_dwordx4 v[170:171], off
	s_add_i32 m0, s39, 0x2000
	s_add_u32 s40, s64, 0x40080
	v_lshl_add_u64 v[170:171], v[232:233], 0, s[10:11]
	s_addc_u32 s41, s65, 0
	s_add_i32 s39, s42, s3
	global_load_lds_dwordx4 v[170:171], off
	v_lshl_add_u64 v[170:171], s[40:41], 0, v[146:147]
	s_mov_b32 m0, s39
	s_nop 0
	global_load_lds_dwordx4 v[170:171], off
	v_lshl_add_u64 v[170:171], s[40:41], 0, v[150:151]
	s_add_i32 m0, s39, 0x2000
	s_nop 0
	global_load_lds_dwordx4 v[170:171], off
	v_lshl_add_u64 v[170:171], v[234:235], 0, s[10:11]
	s_mov_b32 m0, s22
	s_nop 0
	global_load_lds_dwordx4 v[170:171], off
	v_lshl_add_u64 v[170:171], v[236:237], 0, s[10:11]
	s_mov_b32 m0, s23
	s_nop 0
	global_load_lds_dwordx4 v[170:171], off
	s_waitcnt vmcnt(8)
	s_waitcnt lgkmcnt(0)
	s_barrier
	s_setprio 1
	s_waitcnt lgkmcnt(0)
	v_mfma_f32_16x16x32_bf16 v[60:63], v[128:131], v[200:203], v[60:63]
	v_mfma_f32_16x16x32_bf16 v[56:59], v[136:139], v[200:203], v[56:59]
	v_mfma_f32_16x16x32_bf16 v[44:47], v[128:131], v[208:211], v[44:47]
	v_mfma_f32_16x16x32_bf16 v[40:43], v[136:139], v[208:211], v[40:43]
	v_mfma_f32_16x16x32_bf16 v[28:31], v[128:131], v[216:219], v[28:31]
	v_mfma_f32_16x16x32_bf16 v[24:27], v[136:139], v[216:219], v[24:27]
	v_mfma_f32_16x16x32_bf16 v[12:15], v[128:131], v[224:227], v[12:15]
	v_mfma_f32_16x16x32_bf16 v[8:11], v[136:139], v[224:227], v[8:11]
	v_mfma_f32_16x16x32_bf16 v[60:63], v[132:135], v[204:207], v[60:63]
	v_mfma_f32_16x16x32_bf16 v[56:59], v[140:143], v[204:207], v[56:59]
	v_mfma_f32_16x16x32_bf16 v[44:47], v[132:135], v[212:215], v[44:47]
	v_mfma_f32_16x16x32_bf16 v[40:43], v[140:143], v[212:215], v[40:43]
	v_mfma_f32_16x16x32_bf16 v[28:31], v[132:135], v[220:223], v[28:31]
	v_mfma_f32_16x16x32_bf16 v[24:27], v[140:143], v[220:223], v[24:27]
	v_mfma_f32_16x16x32_bf16 v[12:15], v[132:135], v[228:231], v[12:15]
	v_mfma_f32_16x16x32_bf16 v[8:11], v[140:143], v[228:231], v[8:11]
	s_setprio 0
	s_setprio 1
	v_mfma_f32_16x16x32_bf16 v[52:55], v[166:169], v[200:203], v[52:55]
	v_mfma_f32_16x16x32_bf16 v[48:51], v[192:195], v[200:203], v[48:51]
	v_mfma_f32_16x16x32_bf16 v[36:39], v[166:169], v[208:211], v[36:39]
	v_mfma_f32_16x16x32_bf16 v[32:35], v[192:195], v[208:211], v[32:35]
	v_mfma_f32_16x16x32_bf16 v[20:23], v[166:169], v[216:219], v[20:23]
	v_mfma_f32_16x16x32_bf16 v[16:19], v[192:195], v[216:219], v[16:19]
	v_mfma_f32_16x16x32_bf16 v[4:7], v[166:169], v[224:227], v[4:7]
	v_mfma_f32_16x16x32_bf16 v[0:3], v[192:195], v[224:227], v[0:3]
	v_mfma_f32_16x16x32_bf16 v[52:55], v[188:191], v[204:207], v[52:55]
	v_mfma_f32_16x16x32_bf16 v[48:51], v[196:199], v[204:207], v[48:51]
	v_mfma_f32_16x16x32_bf16 v[36:39], v[188:191], v[212:215], v[36:39]
	v_mfma_f32_16x16x32_bf16 v[32:35], v[196:199], v[212:215], v[32:35]
	v_mfma_f32_16x16x32_bf16 v[20:23], v[188:191], v[220:223], v[20:23]
	v_mfma_f32_16x16x32_bf16 v[16:19], v[196:199], v[220:223], v[16:19]
	v_mfma_f32_16x16x32_bf16 v[4:7], v[188:191], v[228:231], v[4:7]
	v_mfma_f32_16x16x32_bf16 v[0:3], v[196:199], v[228:231], v[0:3]
	s_setprio 3
	s_barrier
	s_add_i32 s38, s38, 2
	s_add_u32 s62, s62, 0x100
	s_addc_u32 s63, s63, 0
	s_add_u32 s36, s36, 0x100
	s_addc_u32 s37, s37, 0
	s_cmp_gt_u32 s38, 13
	s_cbranch_scc0 .LBB0_720
	s_and_b64 vcc, exec, s[12:13]
	s_cbranch_vccz .LBB0_723
	s_barrier

; #define PG8_STAGE(bufoff, gbase, voff) do { _Pragma("unroll") for (int _i = 0; _i < 2; ++_i) \
;         __builtin_amdgcn_global_load_lds((const unsigned*)((const char*)(gbase) + (voff)[_i]), (LAS unsigned*)(lds + (bufoff) + ldsw + _i * 8192), 16, 0, 0); } while (0)
; #define PG8_LDA(dst, b, h) do { _Pragma("unroll") for (int m = 0; m < 4; ++m) _Pragma("unroll") for (int k = 0; k < 2; ++k) dst[m][k] = *(const LAS bf16x8*)(lds + PG8_SA(b, h) + aoff + m * 2048 + k * 1024); } while (0)
; #define PG8_LDB(dst, b, h) do { _Pragma("unroll") for (int n = 0; n < 2; ++n) _Pragma("unroll") for (int k = 0; k < 2; ++k) dst[n][k] = *(const LAS bf16x8*)(lds + PG8_SB(b, h) + boff + n * 2048 + k * 1024); } while (0)
; #define PG8_MMA(ai, bj, At, Bt) do { __builtin_amdgcn_s_setprio(1); _Pragma("unroll") for (int m = 0; m < 4; ++m) _Pragma("unroll") for (int n = 0; n < 2; ++n) _Pragma("unroll") for (int k = 0; k < 2; ++k) \
;         acc[ai][bj][m][n] = __builtin_amdgcn_mfma_f32_16x16x32_bf16(Bt[n][k], At[m][k], acc[ai][bj][m][n], 0, 0, 0); __builtin_amdgcn_s_setprio(0); } while (0)
; #define PG8_WAIT_V(n) asm volatile("s_waitcnt vmcnt(" #n ")" ::: "memory")
; #define PG8_WAIT_L(n) asm volatile("s_waitcnt lgkmcnt(" #n ")" ::: "memory")
; template <class Epi>
; __device__ __forceinline__ void gemm_phase(LAS unsigned char* lds, const Gemm g, const StaticOrder& S, const Epi& E) {
;     ...
;             if constexpr (Epi::HAS_MID) { if (t == nt1) E.mid(acc, cur, wr, wc, fr, fq); }
;             const char* a1 = cA + ((Epi::HAS_MID && t >= nt1) ? dA2 : 0) + (size_t)(t + 1) * kstep;
;             const char* a2 = last ? nA : cA + ((Epi::HAS_MID && t + 2 >= nt1) ? dA2 : 0) + (size_t)(t + 2) * kstep; const char* b2 = last ? nB : cB + ((Epi::HAS_MID && t + 2 >= nt1) ? dB2 : 0) + (size_t)(t + 2) * kstep;
;             const char* a3 = a2 + kstep; const char* b3 = b2 + kstep;
;             PG8_LDB(B0, 0, 0); PG8_LDB(B1, 0, 1); PG8_SCHED; PG8_LDA(At, 0, 0); PG8_STAGE(PG8_SA(1, 1), a1 + hsA, voffA);
;             PG8_WAIT_V(8); PG8_WAIT_L(0); PG8_BAR; PG8_MMA(0, 0, At, B0); PG8_MMA(0, 1, At, B1); PG8_BAR; PG8_SCHED;
;             PG8_LDA(At, 0, 1); PG8_STAGE(PG8_SB(0, 0), b2, voffB); PG8_STAGE(PG8_SB(0, 1), b2 + hsB, voffB); PG8_STAGE(PG8_SA(0, 0), a2, voffA);
;             PG8_WAIT_V(8); PG8_WAIT_L(0); PG8_BAR; PG8_MMA(1, 0, At, B0); PG8_MMA(1, 1, At, B1); PG8_BAR; PG8_SCHED;
.LBB0_1083:
	s_add_i32 s33, s33, 2
	s_add_u32 s0, s52, s54
	s_addc_u32 s1, s53, s55
	s_add_u32 s0, s0, 0x100
	v_add_u32_e32 v153, s74, v171
	s_addc_u32 s1, s1, 0
	ds_read_b128 v[128:131], v153
	ds_read_b128 v[132:135], v153 offset:1024
	ds_read_b128 v[164:167], v153 offset:2048
	ds_read_b128 v[184:187], v153 offset:3072
	v_add_u32_e32 v153, s75, v171
	s_cmp_gt_u32 s33, 13
	ds_read_b128 v[188:191], v153
	ds_read_b128 v[192:195], v153 offset:1024
	ds_read_b128 v[196:199], v153 offset:2048
	ds_read_b128 v[200:203], v153 offset:3072
	s_cselect_b32 s17, 0x1ff800, 0
	s_add_u32 s17, s17, s54
	s_addc_u32 s24, 0, s55
	s_add_u32 s17, s22, s17
	s_addc_u32 s24, s23, s24
	s_cmpk_eq_i32 s54, 0xf00
	s_cselect_b32 s59, s6, s1
	s_cselect_b32 s58, s7, s0
	s_cselect_b32 s57, s16, s24
	s_cselect_b32 s56, s18, s17
	v_lshl_add_u64 v[168:169], v[158:159], 0, s[54:55]
	s_add_i32 m0, s61, 0xc000
	ds_read_b128 v[204:207], v173
	ds_read_b128 v[208:211], v173 offset:1024
	ds_read_b128 v[212:215], v173 offset:2048
	ds_read_b128 v[216:219], v173 offset:3072
	ds_read_b128 v[220:223], v173 offset:4096
	ds_read_b128 v[224:227], v173 offset:5120
	ds_read_b128 v[228:231], v173 offset:6144
	ds_read_b128 v[232:235], v173 offset:7168
	global_load_lds_dwordx4 v[168:169], off
	v_lshl_add_u64 v[168:169], v[162:163], 0, s[54:55]
	s_add_i32 m0, s61, 0xe000
	s_nop 0
	global_load_lds_dwordx4 v[168:169], off
	s_waitcnt vmcnt(8)
	s_waitcnt lgkmcnt(0)
	s_barrier
	s_setprio 1
	s_waitcnt lgkmcnt(0)
	v_mfma_f32_16x16x32_bf16 v[124:127], v[128:131], v[204:207], v[124:127]
	v_mfma_f32_16x16x32_bf16 v[120:123], v[164:167], v[204:207], v[120:123]
	v_mfma_f32_16x16x32_bf16 v[108:111], v[128:131], v[212:215], v[108:111]
	v_mfma_f32_16x16x32_bf16 v[104:107], v[164:167], v[212:215], v[104:107]
	v_mfma_f32_16x16x32_bf16 v[92:95], v[128:131], v[220:223], v[92:95]
	v_mfma_f32_16x16x32_bf16 v[88:91], v[164:167], v[220:223], v[88:91]
	v_mfma_f32_16x16x32_bf16 v[76:79], v[128:131], v[228:231], v[76:79]
	v_mfma_f32_16x16x32_bf16 v[72:75], v[164:167], v[228:231], v[72:75]
	v_mfma_f32_16x16x32_bf16 v[124:127], v[132:135], v[208:211], v[124:127]
	v_mfma_f32_16x16x32_bf16 v[120:123], v[184:187], v[208:211], v[120:123]
	v_mfma_f32_16x16x32_bf16 v[108:111], v[132:135], v[216:219], v[108:111]
	v_mfma_f32_16x16x32_bf16 v[104:107], v[184:187], v[216:219], v[104:107]
	v_mfma_f32_16x16x32_bf16 v[92:95], v[132:135], v[224:227], v[92:95]
	v_mfma_f32_16x16x32_bf16 v[88:91], v[184:187], v[224:227], v[88:91]
	v_mfma_f32_16x16x32_bf16 v[76:79], v[132:135], v[232:235], v[76:79]
	v_mfma_f32_16x16x32_bf16 v[72:75], v[184:187], v[232:235], v[72:75]
	s_setprio 0
	s_setprio 1
	v_mfma_f32_16x16x32_bf16 v[116:119], v[188:191], v[204:207], v[116:119]
	v_mfma_f32_16x16x32_bf16 v[112:115], v[196:199], v[204:207], v[112:115]
	v_mfma_f32_16x16x32_bf16 v[100:103], v[188:191], v[212:215], v[100:103]
	v_mfma_f32_16x16x32_bf16 v[96:99], v[196:199], v[212:215], v[96:99]
	v_mfma_f32_16x16x32_bf16 v[84:87], v[188:191], v[220:223], v[84:87]
	v_mfma_f32_16x16x32_bf16 v[80:83], v[196:199], v[220:223], v[80:83]
	v_mfma_f32_16x16x32_bf16 v[68:71], v[188:191], v[228:231], v[68:71]
	v_mfma_f32_16x16x32_bf16 v[64:67], v[196:199], v[228:231], v[64:67]
	v_mfma_f32_16x16x32_bf16 v[116:119], v[192:195], v[208:211], v[116:119]
	v_mfma_f32_16x16x32_bf16 v[112:115], v[200:203], v[208:211], v[112:115]
	v_mfma_f32_16x16x32_bf16 v[100:103], v[192:195], v[216:219], v[100:103]
	v_mfma_f32_16x16x32_bf16 v[96:99], v[200:203], v[216:219], v[96:99]
	v_mfma_f32_16x16x32_bf16 v[84:87], v[192:195], v[224:227], v[84:87]
	v_mfma_f32_16x16x32_bf16 v[80:83], v[200:203], v[224:227], v[80:83]
	v_mfma_f32_16x16x32_bf16 v[68:71], v[192:195], v[232:235], v[68:71]
	v_mfma_f32_16x16x32_bf16 v[64:67], v[200:203], v[232:235], v[64:67]
	s_setprio 3
	s_barrier
	s_add_i32 s0, s74, s60
	v_lshl_add_u64 v[168:169], s[56:57], 0, v[138:139]
	s_mov_b32 m0, s0
	ds_read_b128 v[204:207], v173 offset:16384
	ds_read_b128 v[208:211], v173 offset:17408
	ds_read_b128 v[212:215], v173 offset:18432
	ds_read_b128 v[216:219], v173 offset:19456
	ds_read_b128 v[220:223], v173 offset:20480
	ds_read_b128 v[224:227], v173 offset:21504
	ds_read_b128 v[228:231], v173 offset:22528
	ds_read_b128 v[232:235], v173 offset:23552
	global_load_lds_dwordx4 v[168:169], off
	s_add_i32 m0, s0, 0x2000
	s_add_u32 s0, s56, 0x40000
	v_lshl_add_u64 v[236:237], s[56:57], 0, v[142:143]
	s_addc_u32 s1, s57, 0
	s_add_i32 s17, s75, s60
	global_load_lds_dwordx4 v[236:237], off
	v_lshl_add_u64 v[238:239], s[0:1], 0, v[138:139]
	s_mov_b32 m0, s17
	v_lshl_add_u64 v[240:241], s[58:59], 0, v[140:141]
	global_load_lds_dwordx4 v[238:239], off
	v_lshl_add_u64 v[238:239], s[0:1], 0, v[142:143]
	s_add_i32 m0, s17, 0x2000
	s_nop 0
	global_load_lds_dwordx4 v[238:239], off
	v_lshl_add_u64 v[238:239], s[58:59], 0, v[136:137]
	s_mov_b32 m0, s61
	s_nop 0
	global_load_lds_dwordx4 v[238:239], off
	s_mov_b32 m0, s4
	s_nop 0
	global_load_lds_dwordx4 v[240:241], off
	s_waitcnt vmcnt(8)
	s_waitcnt lgkmcnt(0)
	s_barrier
; #define PG8_STAGE(bufoff, gbase, voff) do { _Pragma("unroll") for (int _i = 0; _i < 2; ++_i) \
;         __builtin_amdgcn_global_load_lds((const unsigned*)((const char*)(gbase) + (voff)[_i]), (LAS unsigned*)(lds + (bufoff) + ldsw + _i * 8192), 16, 0, 0); } while (0)
; #define PG8_LDA(dst, b, h) do { _Pragma("unroll") for (int m = 0; m < 4; ++m) _Pragma("unroll") for (int k = 0; k < 2; ++k) dst[m][k] = *(const LAS bf16x8*)(lds + PG8_SA(b, h) + aoff + m * 2048 + k * 1024); } while (0)
; #define PG8_LDB(dst, b, h) do { _Pragma("unroll") for (int n = 0; n < 2; ++n) _Pragma("unroll") for (int k = 0; k < 2; ++k) dst[n][k] = *(const LAS bf16x8*)(lds + PG8_SB(b, h) + boff + n * 2048 + k * 1024); } while (0)
; #define PG8_MMA(ai, bj, At, Bt) do { __builtin_amdgcn_s_setprio(1); _Pragma("unroll") for (int m = 0; m < 4; ++m) _Pragma("unroll") for (int n = 0; n < 2; ++n) _Pragma("unroll") for (int k = 0; k < 2; ++k) \
;         acc[ai][bj][m][n] = __builtin_amdgcn_mfma_f32_16x16x32_bf16(Bt[n][k], At[m][k], acc[ai][bj][m][n], 0, 0, 0); __builtin_amdgcn_s_setprio(0); } while (0)
; #define PG8_WAIT_V(n) asm volatile("s_waitcnt vmcnt(" #n ")" ::: "memory")
; #define PG8_WAIT_L(n) asm volatile("s_waitcnt lgkmcnt(" #n ")" ::: "memory")
; #define PG8_BAR __builtin_amdgcn_s_barrier()
; #define PG8_SCHED __builtin_amdgcn_sched_barrier(0)
; template <class Epi>
; __device__ __forceinline__ void gemm_phase(LAS unsigned char* lds, const Gemm g, const StaticOrder& S, const Epi& E) {
;     ...
;             PG8_WAIT_V(8); PG8_WAIT_L(0); PG8_BAR; PG8_MMA(1, 0, At, B0); PG8_MMA(1, 1, At, B1); PG8_BAR; PG8_SCHED;
;             PG8_LDB(B0, 1, 0); PG8_LDB(B1, 1, 1); PG8_SCHED; PG8_LDA(At, 1, 0); PG8_STAGE(PG8_SA(0, 1), a2 + hsA, voffA);
;             PG8_WAIT_V(8); PG8_WAIT_L(0); PG8_BAR; PG8_MMA(0, 0, At, B0); PG8_MMA(0, 1, At, B1); PG8_BAR; PG8_SCHED;
	s_setprio 1
	s_waitcnt lgkmcnt(0)
	v_mfma_f32_16x16x32_bf16 v[60:63], v[128:131], v[204:207], v[60:63]
	v_mfma_f32_16x16x32_bf16 v[56:59], v[164:167], v[204:207], v[56:59]
	v_mfma_f32_16x16x32_bf16 v[44:47], v[128:131], v[212:215], v[44:47]
	v_mfma_f32_16x16x32_bf16 v[40:43], v[164:167], v[212:215], v[40:43]
	v_mfma_f32_16x16x32_bf16 v[28:31], v[128:131], v[220:223], v[28:31]
	v_mfma_f32_16x16x32_bf16 v[24:27], v[164:167], v[220:223], v[24:27]
	v_mfma_f32_16x16x32_bf16 v[12:15], v[128:131], v[228:231], v[12:15]
	v_mfma_f32_16x16x32_bf16 v[8:11], v[164:167], v[228:231], v[8:11]
	v_mfma_f32_16x16x32_bf16 v[60:63], v[132:135], v[208:211], v[60:63]
	v_mfma_f32_16x16x32_bf16 v[56:59], v[184:187], v[208:211], v[56:59]
	v_mfma_f32_16x16x32_bf16 v[44:47], v[132:135], v[216:219], v[44:47]
	v_mfma_f32_16x16x32_bf16 v[40:43], v[184:187], v[216:219], v[40:43]
	v_mfma_f32_16x16x32_bf16 v[28:31], v[132:135], v[224:227], v[28:31]
	v_mfma_f32_16x16x32_bf16 v[24:27], v[184:187], v[224:227], v[24:27]
	v_mfma_f32_16x16x32_bf16 v[12:15], v[132:135], v[232:235], v[12:15]
	v_mfma_f32_16x16x32_bf16 v[8:11], v[184:187], v[232:235], v[8:11]
	s_setprio 0
	s_setprio 1
	v_mfma_f32_16x16x32_bf16 v[52:55], v[188:191], v[204:207], v[52:55]
	v_mfma_f32_16x16x32_bf16 v[48:51], v[196:199], v[204:207], v[48:51]
	v_mfma_f32_16x16x32_bf16 v[36:39], v[188:191], v[212:215], v[36:39]
	v_mfma_f32_16x16x32_bf16 v[32:35], v[196:199], v[212:215], v[32:35]
	v_mfma_f32_16x16x32_bf16 v[20:23], v[188:191], v[220:223], v[20:23]
	v_mfma_f32_16x16x32_bf16 v[16:19], v[196:199], v[220:223], v[16:19]
	v_mfma_f32_16x16x32_bf16 v[4:7], v[188:191], v[228:231], v[4:7]
	v_mfma_f32_16x16x32_bf16 v[0:3], v[196:199], v[228:231], v[0:3]
	v_mfma_f32_16x16x32_bf16 v[52:55], v[192:195], v[208:211], v[52:55]
	v_mfma_f32_16x16x32_bf16 v[48:51], v[200:203], v[208:211], v[48:51]
	v_mfma_f32_16x16x32_bf16 v[36:39], v[192:195], v[216:219], v[36:39]
	v_mfma_f32_16x16x32_bf16 v[32:35], v[200:203], v[216:219], v[32:35]
	v_mfma_f32_16x16x32_bf16 v[20:23], v[192:195], v[224:227], v[20:23]
	v_mfma_f32_16x16x32_bf16 v[16:19], v[200:203], v[224:227], v[16:19]
	v_mfma_f32_16x16x32_bf16 v[4:7], v[192:195], v[232:235], v[4:7]
	v_mfma_f32_16x16x32_bf16 v[0:3], v[200:203], v[232:235], v[0:3]
	s_setprio 3
	s_barrier
	s_add_i32 s17, 0, 0x18000
	v_add_u32_e32 v153, s17, v171
	s_add_i32 s24, 0, 0x1c000
	ds_read_b128 v[128:131], v153
	ds_read_b128 v[132:135], v153 offset:1024
	ds_read_b128 v[164:167], v153 offset:2048
	ds_read_b128 v[184:187], v153 offset:3072
	v_add_u32_e32 v153, s24, v171
	ds_read_b128 v[188:191], v153
	ds_read_b128 v[192:195], v153 offset:1024
	ds_read_b128 v[196:199], v153 offset:2048
	ds_read_b128 v[200:203], v153 offset:3072
	s_add_u32 s0, s58, 0x100000
	s_addc_u32 s1, s59, 0
	s_mov_b32 m0, s5
	v_lshl_add_u64 v[242:243], s[0:1], 0, v[136:137]
	ds_read_b128 v[204:207], v173 offset:32768
	ds_read_b128 v[208:211], v173 offset:33792
	ds_read_b128 v[212:215], v173 offset:34816
	ds_read_b128 v[216:219], v173 offset:35840
	ds_read_b128 v[220:223], v173 offset:36864
	ds_read_b128 v[224:227], v173 offset:37888
	ds_read_b128 v[228:231], v173 offset:38912
	ds_read_b128 v[232:235], v173 offset:39936
	global_load_lds_dwordx4 v[242:243], off
	v_lshl_add_u64 v[242:243], s[0:1], 0, v[140:141]
	s_mov_b32 m0, s62
	s_nop 0
	global_load_lds_dwordx4 v[242:243], off
	s_waitcnt vmcnt(8)
	s_waitcnt lgkmcnt(0)
	s_barrier
	s_setprio 1
	s_waitcnt lgkmcnt(0)
	v_mfma_f32_16x16x32_bf16 v[124:127], v[128:131], v[204:207], v[124:127]
	v_mfma_f32_16x16x32_bf16 v[120:123], v[164:167], v[204:207], v[120:123]
	v_mfma_f32_16x16x32_bf16 v[108:111], v[128:131], v[212:215], v[108:111]
	v_mfma_f32_16x16x32_bf16 v[104:107], v[164:167], v[212:215], v[104:107]
	v_mfma_f32_16x16x32_bf16 v[92:95], v[128:131], v[220:223], v[92:95]
	v_mfma_f32_16x16x32_bf16 v[88:91], v[164:167], v[220:223], v[88:91]
	v_mfma_f32_16x16x32_bf16 v[76:79], v[128:131], v[228:231], v[76:79]
	v_mfma_f32_16x16x32_bf16 v[72:75], v[164:167], v[228:231], v[72:75]
	v_mfma_f32_16x16x32_bf16 v[124:127], v[132:135], v[208:211], v[124:127]
	v_mfma_f32_16x16x32_bf16 v[120:123], v[184:187], v[208:211], v[120:123]
	v_mfma_f32_16x16x32_bf16 v[108:111], v[132:135], v[216:219], v[108:111]
	v_mfma_f32_16x16x32_bf16 v[104:107], v[184:187], v[216:219], v[104:107]
	v_mfma_f32_16x16x32_bf16 v[92:95], v[132:135], v[224:227], v[92:95]
	v_mfma_f32_16x16x32_bf16 v[88:91], v[184:187], v[224:227], v[88:91]
	v_mfma_f32_16x16x32_bf16 v[76:79], v[132:135], v[232:235], v[76:79]
	v_mfma_f32_16x16x32_bf16 v[72:75], v[184:187], v[232:235], v[72:75]
	s_setprio 0
	s_setprio 1
	v_mfma_f32_16x16x32_bf16 v[116:119], v[188:191], v[204:207], v[116:119]
	v_mfma_f32_16x16x32_bf16 v[112:115], v[196:199], v[204:207], v[112:115]
	v_mfma_f32_16x16x32_bf16 v[100:103], v[188:191], v[212:215], v[100:103]
	v_mfma_f32_16x16x32_bf16 v[96:99], v[196:199], v[212:215], v[96:99]
	v_mfma_f32_16x16x32_bf16 v[84:87], v[188:191], v[220:223], v[84:87]
	v_mfma_f32_16x16x32_bf16 v[80:83], v[196:199], v[220:223], v[80:83]
	v_mfma_f32_16x16x32_bf16 v[68:71], v[188:191], v[228:231], v[68:71]
	v_mfma_f32_16x16x32_bf16 v[64:67], v[196:199], v[228:231], v[64:67]
	v_mfma_f32_16x16x32_bf16 v[116:119], v[192:195], v[208:211], v[116:119]
	v_mfma_f32_16x16x32_bf16 v[112:115], v[200:203], v[208:211], v[112:115]
	v_mfma_f32_16x16x32_bf16 v[100:103], v[192:195], v[216:219], v[100:103]
	v_mfma_f32_16x16x32_bf16 v[96:99], v[200:203], v[216:219], v[96:99]
	v_mfma_f32_16x16x32_bf16 v[84:87], v[192:195], v[224:227], v[84:87]
	v_mfma_f32_16x16x32_bf16 v[80:83], v[200:203], v[224:227], v[80:83]
	v_mfma_f32_16x16x32_bf16 v[68:71], v[192:195], v[232:235], v[68:71]
	v_mfma_f32_16x16x32_bf16 v[64:67], v[200:203], v[232:235], v[64:67]
	s_setprio 3
	s_barrier
; #define PG8_STAGE(bufoff, gbase, voff) do { _Pragma("unroll") for (int _i = 0; _i < 2; ++_i) \
;         __builtin_amdgcn_global_load_lds((const unsigned*)((const char*)(gbase) + (voff)[_i]), (LAS unsigned*)(lds + (bufoff) + ldsw + _i * 8192), 16, 0, 0); } while (0)
; #define PG8_LDA(dst, b, h) do { _Pragma("unroll") for (int m = 0; m < 4; ++m) _Pragma("unroll") for (int k = 0; k < 2; ++k) dst[m][k] = *(const LAS bf16x8*)(lds + PG8_SA(b, h) + aoff + m * 2048 + k * 1024); } while (0)
; #define PG8_MMA(ai, bj, At, Bt) do { __builtin_amdgcn_s_setprio(1); _Pragma("unroll") for (int m = 0; m < 4; ++m) _Pragma("unroll") for (int n = 0; n < 2; ++n) _Pragma("unroll") for (int k = 0; k < 2; ++k) \
;         acc[ai][bj][m][n] = __builtin_amdgcn_mfma_f32_16x16x32_bf16(Bt[n][k], At[m][k], acc[ai][bj][m][n], 0, 0, 0); __builtin_amdgcn_s_setprio(0); } while (0)
; #define PG8_WAIT_V(n) asm volatile("s_waitcnt vmcnt(" #n ")" ::: "memory")
; #define PG8_WAIT_L(n) asm volatile("s_waitcnt lgkmcnt(" #n ")" ::: "memory")
; #define PG8_BAR __builtin_amdgcn_s_barrier()
; #define PG8_SCHED __builtin_amdgcn_sched_barrier(0)
; template <class Epi>
; __device__ __forceinline__ void gemm_phase(LAS unsigned char* lds, const Gemm g, const StaticOrder& S, const Epi& E) {
;     ...
;             PG8_LDA(At, 1, 1); PG8_STAGE(PG8_SB(1, 0), b3, voffB); PG8_STAGE(PG8_SB(1, 1), b3 + hsB, voffB); PG8_STAGE(PG8_SA(1, 0), a3, voffA);
;             PG8_WAIT_V(8); PG8_WAIT_L(0); PG8_BAR; PG8_MMA(1, 0, At, B0); PG8_MMA(1, 1, At, B1); PG8_BAR; PG8_SCHED;
;         }
	s_add_i32 s0, s17, s60
	v_lshl_add_u64 v[168:169], v[168:169], 0, s[10:11]
	s_mov_b32 m0, s0
	ds_read_b128 v[204:207], v173 offset:49152
	ds_read_b128 v[208:211], v173 offset:50176
	ds_read_b128 v[212:215], v173 offset:51200
	ds_read_b128 v[216:219], v173 offset:52224
	ds_read_b128 v[220:223], v173 offset:53248
	ds_read_b128 v[224:227], v173 offset:54272
	ds_read_b128 v[228:231], v173 offset:55296
	ds_read_b128 v[232:235], v173 offset:56320
	global_load_lds_dwordx4 v[168:169], off
	s_add_i32 m0, s0, 0x2000
	s_add_u32 s0, s56, 0x40080
	v_lshl_add_u64 v[168:169], v[236:237], 0, s[10:11]
	s_addc_u32 s1, s57, 0
	s_add_i32 s17, s24, s60
	global_load_lds_dwordx4 v[168:169], off
	v_lshl_add_u64 v[168:169], s[0:1], 0, v[138:139]
	s_mov_b32 m0, s17
	s_nop 0
	global_load_lds_dwordx4 v[168:169], off
	v_lshl_add_u64 v[168:169], s[0:1], 0, v[142:143]
	s_add_i32 m0, s17, 0x2000
	s_nop 0
	global_load_lds_dwordx4 v[168:169], off
	v_lshl_add_u64 v[168:169], v[238:239], 0, s[10:11]
	s_mov_b32 m0, s64
	s_nop 0
	global_load_lds_dwordx4 v[168:169], off
	v_lshl_add_u64 v[168:169], v[240:241], 0, s[10:11]
	s_mov_b32 m0, s65
	s_nop 0
	global_load_lds_dwordx4 v[168:169], off
	s_waitcnt vmcnt(8)
	s_waitcnt lgkmcnt(0)
	s_barrier
	s_setprio 1
	s_waitcnt lgkmcnt(0)
	v_mfma_f32_16x16x32_bf16 v[60:63], v[128:131], v[204:207], v[60:63]
	v_mfma_f32_16x16x32_bf16 v[56:59], v[164:167], v[204:207], v[56:59]
	v_mfma_f32_16x16x32_bf16 v[44:47], v[128:131], v[212:215], v[44:47]
	v_mfma_f32_16x16x32_bf16 v[40:43], v[164:167], v[212:215], v[40:43]
	v_mfma_f32_16x16x32_bf16 v[28:31], v[128:131], v[220:223], v[28:31]
	v_mfma_f32_16x16x32_bf16 v[24:27], v[164:167], v[220:223], v[24:27]
	v_mfma_f32_16x16x32_bf16 v[12:15], v[128:131], v[228:231], v[12:15]
	v_mfma_f32_16x16x32_bf16 v[8:11], v[164:167], v[228:231], v[8:11]
	v_mfma_f32_16x16x32_bf16 v[60:63], v[132:135], v[208:211], v[60:63]
	v_mfma_f32_16x16x32_bf16 v[56:59], v[184:187], v[208:211], v[56:59]
	v_mfma_f32_16x16x32_bf16 v[44:47], v[132:135], v[216:219], v[44:47]
	v_mfma_f32_16x16x32_bf16 v[40:43], v[184:187], v[216:219], v[40:43]
	v_mfma_f32_16x16x32_bf16 v[28:31], v[132:135], v[224:227], v[28:31]
	v_mfma_f32_16x16x32_bf16 v[24:27], v[184:187], v[224:227], v[24:27]
	v_mfma_f32_16x16x32_bf16 v[12:15], v[132:135], v[232:235], v[12:15]
	v_mfma_f32_16x16x32_bf16 v[8:11], v[184:187], v[232:235], v[8:11]
	s_setprio 0
	s_setprio 1
	v_mfma_f32_16x16x32_bf16 v[52:55], v[188:191], v[204:207], v[52:55]
	v_mfma_f32_16x16x32_bf16 v[48:51], v[196:199], v[204:207], v[48:51]
	v_mfma_f32_16x16x32_bf16 v[36:39], v[188:191], v[212:215], v[36:39]
	v_mfma_f32_16x16x32_bf16 v[32:35], v[196:199], v[212:215], v[32:35]
	v_mfma_f32_16x16x32_bf16 v[20:23], v[188:191], v[220:223], v[20:23]
	v_mfma_f32_16x16x32_bf16 v[16:19], v[196:199], v[220:223], v[16:19]
	v_mfma_f32_16x16x32_bf16 v[4:7], v[188:191], v[228:231], v[4:7]
	v_mfma_f32_16x16x32_bf16 v[0:3], v[196:199], v[228:231], v[0:3]
	v_mfma_f32_16x16x32_bf16 v[52:55], v[192:195], v[208:211], v[52:55]
	v_mfma_f32_16x16x32_bf16 v[48:51], v[200:203], v[208:211], v[48:51]
	v_mfma_f32_16x16x32_bf16 v[36:39], v[192:195], v[216:219], v[36:39]
	v_mfma_f32_16x16x32_bf16 v[32:35], v[200:203], v[216:219], v[32:35]
	v_mfma_f32_16x16x32_bf16 v[20:23], v[192:195], v[224:227], v[20:23]
	v_mfma_f32_16x16x32_bf16 v[16:19], v[200:203], v[224:227], v[16:19]
	v_mfma_f32_16x16x32_bf16 v[4:7], v[192:195], v[232:235], v[4:7]
	v_mfma_f32_16x16x32_bf16 v[0:3], v[200:203], v[232:235], v[0:3]
	s_setprio 3
	s_barrier
	s_add_u32 s54, s54, 0x100
	s_addc_u32 s55, 0, s55
	s_cmp_gt_u32 s33, 29
	s_cbranch_scc1 .LBB0_1086

; #define PG8_STAGE(bufoff, gbase, voff) do { _Pragma("unroll") for (int _i = 0; _i < 2; ++_i) \
;         __builtin_amdgcn_global_load_lds((const unsigned*)((const char*)(gbase) + (voff)[_i]), (LAS unsigned*)(lds + (bufoff) + ldsw + _i * 8192), 16, 0, 0); } while (0)
; #define PG8_LDA(dst, b, h) do { _Pragma("unroll") for (int m = 0; m < 4; ++m) _Pragma("unroll") for (int k = 0; k < 2; ++k) dst[m][k] = *(const LAS bf16x8*)(lds + PG8_SA(b, h) + aoff + m * 2048 + k * 1024); } while (0)
; #define PG8_LDB(dst, b, h) do { _Pragma("unroll") for (int n = 0; n < 2; ++n) _Pragma("unroll") for (int k = 0; k < 2; ++k) dst[n][k] = *(const LAS bf16x8*)(lds + PG8_SB(b, h) + boff + n * 2048 + k * 1024); } while (0)
; #define PG8_MMA(ai, bj, At, Bt) do { __builtin_amdgcn_s_setprio(1); _Pragma("unroll") for (int m = 0; m < 4; ++m) _Pragma("unroll") for (int n = 0; n < 2; ++n) _Pragma("unroll") for (int k = 0; k < 2; ++k) \
;         acc[ai][bj][m][n] = __builtin_amdgcn_mfma_f32_16x16x32_bf16(Bt[n][k], At[m][k], acc[ai][bj][m][n], 0, 0, 0); __builtin_amdgcn_s_setprio(0); } while (0)
; #define PG8_WAIT_V(n) asm volatile("s_waitcnt vmcnt(" #n ")" ::: "memory")
; #define PG8_WAIT_L(n) asm volatile("s_waitcnt lgkmcnt(" #n ")" ::: "memory")
; #define PG8_BAR __builtin_amdgcn_s_barrier()
; #define PG8_SCHED __builtin_amdgcn_sched_barrier(0)
; template <class Epi>
; __device__ __forceinline__ void gemm_phase(LAS unsigned char* lds, const Gemm g, const StaticOrder& S, const Epi& E) {
;     ...
;             PG8_LDB(B0, 0, 0); PG8_LDB(B1, 0, 1); PG8_SCHED; PG8_LDA(At, 0, 0); PG8_STAGE(PG8_SA(1, 1), a1 + hsA, voffA);
;             PG8_WAIT_V(8); PG8_WAIT_L(0); PG8_BAR; PG8_MMA(0, 0, At, B0); PG8_MMA(0, 1, At, B1); PG8_BAR; PG8_SCHED;
;             PG8_LDA(At, 0, 1); PG8_STAGE(PG8_SB(0, 0), b2, voffB); PG8_STAGE(PG8_SB(0, 1), b2 + hsB, voffB); PG8_STAGE(PG8_SA(0, 0), a2, voffA);
;             PG8_WAIT_V(8); PG8_WAIT_L(0); PG8_BAR; PG8_MMA(1, 0, At, B0); PG8_MMA(1, 1, At, B1); PG8_BAR; PG8_SCHED;
.LBB0_1234:
	ds_read_b128 v[144:147], v155
	ds_read_b128 v[148:151], v155 offset:1024
	ds_read_b128 v[162:165], v155 offset:2048
	ds_read_b128 v[166:169], v155 offset:3072
	ds_read_b128 v[170:173], v156
	ds_read_b128 v[174:177], v156 offset:1024
	ds_read_b128 v[184:187], v156 offset:2048
	ds_read_b128 v[188:191], v156 offset:3072
	s_add_u32 s39, s48, 0xfffc0080
	s_addc_u32 s41, s49, -1
	s_cmp_eq_u32 s35, 12
	s_cselect_b32 s53, s0, s41
	s_cselect_b32 s52, s1, s39
	s_cselect_b32 s51, s6, s34
	s_cselect_b32 s50, s7, s13
	v_lshl_add_u64 v[158:159], s[48:49], 0, v[136:137]
	s_add_i32 m0, s5, 0xc000
	ds_read_b128 v[192:195], v157
	ds_read_b128 v[196:199], v157 offset:1024
	ds_read_b128 v[200:203], v157 offset:2048
	ds_read_b128 v[204:207], v157 offset:3072
	ds_read_b128 v[208:211], v157 offset:4096
	ds_read_b128 v[212:215], v157 offset:5120
	ds_read_b128 v[216:219], v157 offset:6144
	ds_read_b128 v[220:223], v157 offset:7168
	global_load_lds_dwordx4 v[158:159], off
	v_lshl_add_u64 v[158:159], s[48:49], 0, v[138:139]
	s_add_i32 m0, s5, 0xe000
	s_nop 0
	global_load_lds_dwordx4 v[158:159], off
	s_waitcnt vmcnt(8)
	s_waitcnt lgkmcnt(0)
	s_barrier
	s_setprio 1
	s_waitcnt lgkmcnt(0)
	v_mfma_f32_16x16x32_bf16 v[124:127], v[144:147], v[192:195], v[124:127]
	v_mfma_f32_16x16x32_bf16 v[120:123], v[162:165], v[192:195], v[120:123]
	v_mfma_f32_16x16x32_bf16 v[108:111], v[144:147], v[200:203], v[108:111]
	v_mfma_f32_16x16x32_bf16 v[104:107], v[162:165], v[200:203], v[104:107]
	v_mfma_f32_16x16x32_bf16 v[92:95], v[144:147], v[208:211], v[92:95]
	v_mfma_f32_16x16x32_bf16 v[88:91], v[162:165], v[208:211], v[88:91]
	v_mfma_f32_16x16x32_bf16 v[76:79], v[144:147], v[216:219], v[76:79]
	v_mfma_f32_16x16x32_bf16 v[72:75], v[162:165], v[216:219], v[72:75]
	v_mfma_f32_16x16x32_bf16 v[124:127], v[148:151], v[196:199], v[124:127]
	v_mfma_f32_16x16x32_bf16 v[120:123], v[166:169], v[196:199], v[120:123]
	v_mfma_f32_16x16x32_bf16 v[108:111], v[148:151], v[204:207], v[108:111]
	v_mfma_f32_16x16x32_bf16 v[104:107], v[166:169], v[204:207], v[104:107]
	v_mfma_f32_16x16x32_bf16 v[92:95], v[148:151], v[212:215], v[92:95]
	v_mfma_f32_16x16x32_bf16 v[88:91], v[166:169], v[212:215], v[88:91]
	v_mfma_f32_16x16x32_bf16 v[76:79], v[148:151], v[220:223], v[76:79]
	v_mfma_f32_16x16x32_bf16 v[72:75], v[166:169], v[220:223], v[72:75]
	s_setprio 0
	s_setprio 1
	v_mfma_f32_16x16x32_bf16 v[116:119], v[170:173], v[192:195], v[116:119]
	v_mfma_f32_16x16x32_bf16 v[112:115], v[184:187], v[192:195], v[112:115]
	v_mfma_f32_16x16x32_bf16 v[100:103], v[170:173], v[200:203], v[100:103]
	v_mfma_f32_16x16x32_bf16 v[96:99], v[184:187], v[200:203], v[96:99]
	v_mfma_f32_16x16x32_bf16 v[84:87], v[170:173], v[208:211], v[84:87]
	v_mfma_f32_16x16x32_bf16 v[80:83], v[184:187], v[208:211], v[80:83]
	v_mfma_f32_16x16x32_bf16 v[68:71], v[170:173], v[216:219], v[68:71]
	v_mfma_f32_16x16x32_bf16 v[64:67], v[184:187], v[216:219], v[64:67]
	v_mfma_f32_16x16x32_bf16 v[116:119], v[174:177], v[196:199], v[116:119]
	v_mfma_f32_16x16x32_bf16 v[112:115], v[188:191], v[196:199], v[112:115]
	v_mfma_f32_16x16x32_bf16 v[100:103], v[174:177], v[204:207], v[100:103]
	v_mfma_f32_16x16x32_bf16 v[96:99], v[188:191], v[204:207], v[96:99]
	v_mfma_f32_16x16x32_bf16 v[84:87], v[174:177], v[212:215], v[84:87]
	v_mfma_f32_16x16x32_bf16 v[80:83], v[188:191], v[212:215], v[80:83]
	v_mfma_f32_16x16x32_bf16 v[68:71], v[174:177], v[220:223], v[68:71]
	v_mfma_f32_16x16x32_bf16 v[64:67], v[188:191], v[220:223], v[64:67]
	s_setprio 3
	s_barrier
	s_add_i32 s39, s31, s4
	v_lshl_add_u64 v[158:159], s[50:51], 0, v[130:131]
	s_mov_b32 m0, s39
	ds_read_b128 v[192:195], v157 offset:16384
	ds_read_b128 v[196:199], v157 offset:17408
	ds_read_b128 v[200:203], v157 offset:18432
	ds_read_b128 v[204:207], v157 offset:19456
	ds_read_b128 v[208:211], v157 offset:20480
	ds_read_b128 v[212:215], v157 offset:21504
	ds_read_b128 v[216:219], v157 offset:22528
	ds_read_b128 v[220:223], v157 offset:23552
	global_load_lds_dwordx4 v[158:159], off
	s_add_i32 m0, s39, 0x2000
	s_add_u32 s54, s50, 0x40000
	v_lshl_add_u64 v[224:225], s[50:51], 0, v[134:135]
	s_addc_u32 s55, s51, 0
	s_add_i32 s39, s33, s4
	global_load_lds_dwordx4 v[224:225], off
	v_lshl_add_u64 v[226:227], s[54:55], 0, v[130:131]
	s_mov_b32 m0, s39
	v_lshl_add_u64 v[228:229], s[52:53], 0, v[132:133]
	global_load_lds_dwordx4 v[226:227], off
	v_lshl_add_u64 v[226:227], s[54:55], 0, v[134:135]
	s_add_i32 m0, s39, 0x2000
	s_nop 0
	global_load_lds_dwordx4 v[226:227], off
	v_lshl_add_u64 v[226:227], s[52:53], 0, v[128:129]
	s_mov_b32 m0, s5
	s_nop 0
	global_load_lds_dwordx4 v[226:227], off
	s_mov_b32 m0, s16
	s_nop 0
	global_load_lds_dwordx4 v[228:229], off
	s_waitcnt vmcnt(8)
	s_waitcnt lgkmcnt(0)
	s_barrier
; #define PG8_STAGE(bufoff, gbase, voff) do { _Pragma("unroll") for (int _i = 0; _i < 2; ++_i) \
;         __builtin_amdgcn_global_load_lds((const unsigned*)((const char*)(gbase) + (voff)[_i]), (LAS unsigned*)(lds + (bufoff) + ldsw + _i * 8192), 16, 0, 0); } while (0)
; #define PG8_LDA(dst, b, h) do { _Pragma("unroll") for (int m = 0; m < 4; ++m) _Pragma("unroll") for (int k = 0; k < 2; ++k) dst[m][k] = *(const LAS bf16x8*)(lds + PG8_SA(b, h) + aoff + m * 2048 + k * 1024); } while (0)
; #define PG8_LDB(dst, b, h) do { _Pragma("unroll") for (int n = 0; n < 2; ++n) _Pragma("unroll") for (int k = 0; k < 2; ++k) dst[n][k] = *(const LAS bf16x8*)(lds + PG8_SB(b, h) + boff + n * 2048 + k * 1024); } while (0)
; #define PG8_MMA(ai, bj, At, Bt) do { __builtin_amdgcn_s_setprio(1); _Pragma("unroll") for (int m = 0; m < 4; ++m) _Pragma("unroll") for (int n = 0; n < 2; ++n) _Pragma("unroll") for (int k = 0; k < 2; ++k) \
;         acc[ai][bj][m][n] = __builtin_amdgcn_mfma_f32_16x16x32_bf16(Bt[n][k], At[m][k], acc[ai][bj][m][n], 0, 0, 0); __builtin_amdgcn_s_setprio(0); } while (0)
; #define PG8_WAIT_V(n) asm volatile("s_waitcnt vmcnt(" #n ")" ::: "memory")
; #define PG8_WAIT_L(n) asm volatile("s_waitcnt lgkmcnt(" #n ")" ::: "memory")
; #define PG8_BAR __builtin_amdgcn_s_barrier()
; #define PG8_SCHED __builtin_amdgcn_sched_barrier(0)
; template <class Epi>
; __device__ __forceinline__ void gemm_phase(LAS unsigned char* lds, const Gemm g, const StaticOrder& S, const Epi& E) {
;     ...
;             PG8_WAIT_V(8); PG8_WAIT_L(0); PG8_BAR; PG8_MMA(1, 0, At, B0); PG8_MMA(1, 1, At, B1); PG8_BAR; PG8_SCHED;
;             PG8_LDB(B0, 1, 0); PG8_LDB(B1, 1, 1); PG8_SCHED; PG8_LDA(At, 1, 0); PG8_STAGE(PG8_SA(0, 1), a2 + hsA, voffA);
;             PG8_WAIT_V(8); PG8_WAIT_L(0); PG8_BAR; PG8_MMA(0, 0, At, B0); PG8_MMA(0, 1, At, B1); PG8_BAR; PG8_SCHED;
	s_setprio 1
	s_waitcnt lgkmcnt(0)
	v_mfma_f32_16x16x32_bf16 v[60:63], v[144:147], v[192:195], v[60:63]
	v_mfma_f32_16x16x32_bf16 v[56:59], v[162:165], v[192:195], v[56:59]
	v_mfma_f32_16x16x32_bf16 v[44:47], v[144:147], v[200:203], v[44:47]
	v_mfma_f32_16x16x32_bf16 v[40:43], v[162:165], v[200:203], v[40:43]
	v_mfma_f32_16x16x32_bf16 v[28:31], v[144:147], v[208:211], v[28:31]
	v_mfma_f32_16x16x32_bf16 v[24:27], v[162:165], v[208:211], v[24:27]
	v_mfma_f32_16x16x32_bf16 v[12:15], v[144:147], v[216:219], v[12:15]
	v_mfma_f32_16x16x32_bf16 v[8:11], v[162:165], v[216:219], v[8:11]
	v_mfma_f32_16x16x32_bf16 v[60:63], v[148:151], v[196:199], v[60:63]
	v_mfma_f32_16x16x32_bf16 v[56:59], v[166:169], v[196:199], v[56:59]
	v_mfma_f32_16x16x32_bf16 v[44:47], v[148:151], v[204:207], v[44:47]
	v_mfma_f32_16x16x32_bf16 v[40:43], v[166:169], v[204:207], v[40:43]
	v_mfma_f32_16x16x32_bf16 v[28:31], v[148:151], v[212:215], v[28:31]
	v_mfma_f32_16x16x32_bf16 v[24:27], v[166:169], v[212:215], v[24:27]
	v_mfma_f32_16x16x32_bf16 v[12:15], v[148:151], v[220:223], v[12:15]
	v_mfma_f32_16x16x32_bf16 v[8:11], v[166:169], v[220:223], v[8:11]
	s_setprio 0
	s_setprio 1
	v_mfma_f32_16x16x32_bf16 v[52:55], v[170:173], v[192:195], v[52:55]
	v_mfma_f32_16x16x32_bf16 v[48:51], v[184:187], v[192:195], v[48:51]
	v_mfma_f32_16x16x32_bf16 v[36:39], v[170:173], v[200:203], v[36:39]
	v_mfma_f32_16x16x32_bf16 v[32:35], v[184:187], v[200:203], v[32:35]
	v_mfma_f32_16x16x32_bf16 v[20:23], v[170:173], v[208:211], v[20:23]
	v_mfma_f32_16x16x32_bf16 v[16:19], v[184:187], v[208:211], v[16:19]
	v_mfma_f32_16x16x32_bf16 v[4:7], v[170:173], v[216:219], v[4:7]
	v_mfma_f32_16x16x32_bf16 v[0:3], v[184:187], v[216:219], v[0:3]
	v_mfma_f32_16x16x32_bf16 v[52:55], v[174:177], v[196:199], v[52:55]
	v_mfma_f32_16x16x32_bf16 v[48:51], v[188:191], v[196:199], v[48:51]
	v_mfma_f32_16x16x32_bf16 v[36:39], v[174:177], v[204:207], v[36:39]
	v_mfma_f32_16x16x32_bf16 v[32:35], v[188:191], v[204:207], v[32:35]
	v_mfma_f32_16x16x32_bf16 v[20:23], v[174:177], v[212:215], v[20:23]
	v_mfma_f32_16x16x32_bf16 v[16:19], v[188:191], v[212:215], v[16:19]
	v_mfma_f32_16x16x32_bf16 v[4:7], v[174:177], v[220:223], v[4:7]
	v_mfma_f32_16x16x32_bf16 v[0:3], v[188:191], v[220:223], v[0:3]
	s_setprio 3
	s_barrier
	s_add_i32 s39, 0, 0x18000
	v_add_u32_e32 v160, s39, v153
	s_add_i32 s41, 0, 0x1c000
	ds_read_b128 v[144:147], v160
	ds_read_b128 v[148:151], v160 offset:1024
	ds_read_b128 v[162:165], v160 offset:2048
	ds_read_b128 v[166:169], v160 offset:3072
	v_add_u32_e32 v160, s41, v153
	ds_read_b128 v[170:173], v160
	ds_read_b128 v[174:177], v160 offset:1024
	ds_read_b128 v[184:187], v160 offset:2048
	ds_read_b128 v[188:191], v160 offset:3072
	s_add_u32 s52, s52, 0x40000
	s_addc_u32 s53, s53, 0
	s_mov_b32 m0, s17
	v_lshl_add_u64 v[230:231], s[52:53], 0, v[128:129]
	ds_read_b128 v[192:195], v157 offset:32768
	ds_read_b128 v[196:199], v157 offset:33792
	ds_read_b128 v[200:203], v157 offset:34816
	ds_read_b128 v[204:207], v157 offset:35840
	ds_read_b128 v[208:211], v157 offset:36864
	ds_read_b128 v[212:215], v157 offset:37888
	ds_read_b128 v[216:219], v157 offset:38912
	ds_read_b128 v[220:223], v157 offset:39936
	global_load_lds_dwordx4 v[230:231], off
	v_lshl_add_u64 v[230:231], s[52:53], 0, v[132:133]
	s_mov_b32 m0, s18
	s_nop 0
	global_load_lds_dwordx4 v[230:231], off
	s_waitcnt vmcnt(8)
	s_waitcnt lgkmcnt(0)
	s_barrier
	s_setprio 1
	s_waitcnt lgkmcnt(0)
	v_mfma_f32_16x16x32_bf16 v[124:127], v[144:147], v[192:195], v[124:127]
	v_mfma_f32_16x16x32_bf16 v[120:123], v[162:165], v[192:195], v[120:123]
	v_mfma_f32_16x16x32_bf16 v[108:111], v[144:147], v[200:203], v[108:111]
	v_mfma_f32_16x16x32_bf16 v[104:107], v[162:165], v[200:203], v[104:107]
	v_mfma_f32_16x16x32_bf16 v[92:95], v[144:147], v[208:211], v[92:95]
	v_mfma_f32_16x16x32_bf16 v[88:91], v[162:165], v[208:211], v[88:91]
	v_mfma_f32_16x16x32_bf16 v[76:79], v[144:147], v[216:219], v[76:79]
	v_mfma_f32_16x16x32_bf16 v[72:75], v[162:165], v[216:219], v[72:75]
	v_mfma_f32_16x16x32_bf16 v[124:127], v[148:151], v[196:199], v[124:127]
	v_mfma_f32_16x16x32_bf16 v[120:123], v[166:169], v[196:199], v[120:123]
	v_mfma_f32_16x16x32_bf16 v[108:111], v[148:151], v[204:207], v[108:111]
	v_mfma_f32_16x16x32_bf16 v[104:107], v[166:169], v[204:207], v[104:107]
	v_mfma_f32_16x16x32_bf16 v[92:95], v[148:151], v[212:215], v[92:95]
	v_mfma_f32_16x16x32_bf16 v[88:91], v[166:169], v[212:215], v[88:91]
	v_mfma_f32_16x16x32_bf16 v[76:79], v[148:151], v[220:223], v[76:79]
	v_mfma_f32_16x16x32_bf16 v[72:75], v[166:169], v[220:223], v[72:75]
	s_setprio 0
	s_setprio 1
	v_mfma_f32_16x16x32_bf16 v[116:119], v[170:173], v[192:195], v[116:119]
	v_mfma_f32_16x16x32_bf16 v[112:115], v[184:187], v[192:195], v[112:115]
	v_mfma_f32_16x16x32_bf16 v[100:103], v[170:173], v[200:203], v[100:103]
	v_mfma_f32_16x16x32_bf16 v[96:99], v[184:187], v[200:203], v[96:99]
	v_mfma_f32_16x16x32_bf16 v[84:87], v[170:173], v[208:211], v[84:87]
	v_mfma_f32_16x16x32_bf16 v[80:83], v[184:187], v[208:211], v[80:83]
	v_mfma_f32_16x16x32_bf16 v[68:71], v[170:173], v[216:219], v[68:71]
	v_mfma_f32_16x16x32_bf16 v[64:67], v[184:187], v[216:219], v[64:67]
	v_mfma_f32_16x16x32_bf16 v[116:119], v[174:177], v[196:199], v[116:119]
	v_mfma_f32_16x16x32_bf16 v[112:115], v[188:191], v[196:199], v[112:115]
	v_mfma_f32_16x16x32_bf16 v[100:103], v[174:177], v[204:207], v[100:103]
	v_mfma_f32_16x16x32_bf16 v[96:99], v[188:191], v[204:207], v[96:99]
	v_mfma_f32_16x16x32_bf16 v[84:87], v[174:177], v[212:215], v[84:87]
	v_mfma_f32_16x16x32_bf16 v[80:83], v[188:191], v[212:215], v[80:83]
	v_mfma_f32_16x16x32_bf16 v[68:71], v[174:177], v[220:223], v[68:71]
	v_mfma_f32_16x16x32_bf16 v[64:67], v[188:191], v[220:223], v[64:67]
	s_setprio 3
	s_barrier
; #define PG8_STAGE(bufoff, gbase, voff) do { _Pragma("unroll") for (int _i = 0; _i < 2; ++_i) \
;         __builtin_amdgcn_global_load_lds((const unsigned*)((const char*)(gbase) + (voff)[_i]), (LAS unsigned*)(lds + (bufoff) + ldsw + _i * 8192), 16, 0, 0); } while (0)
; #define PG8_LDA(dst, b, h) do { _Pragma("unroll") for (int m = 0; m < 4; ++m) _Pragma("unroll") for (int k = 0; k < 2; ++k) dst[m][k] = *(const LAS bf16x8*)(lds + PG8_SA(b, h) + aoff + m * 2048 + k * 1024); } while (0)
; #define PG8_MMA(ai, bj, At, Bt) do { __builtin_amdgcn_s_setprio(1); _Pragma("unroll") for (int m = 0; m < 4; ++m) _Pragma("unroll") for (int n = 0; n < 2; ++n) _Pragma("unroll") for (int k = 0; k < 2; ++k) \
;         acc[ai][bj][m][n] = __builtin_amdgcn_mfma_f32_16x16x32_bf16(Bt[n][k], At[m][k], acc[ai][bj][m][n], 0, 0, 0); __builtin_amdgcn_s_setprio(0); } while (0)
; #define PG8_WAIT_V(n) asm volatile("s_waitcnt vmcnt(" #n ")" ::: "memory")
; #define PG8_WAIT_L(n) asm volatile("s_waitcnt lgkmcnt(" #n ")" ::: "memory")
; #define PG8_BAR __builtin_amdgcn_s_barrier()
; #define PG8_SCHED __builtin_amdgcn_sched_barrier(0)
; template <class Epi>
; __device__ __forceinline__ void gemm_phase(LAS unsigned char* lds, const Gemm g, const StaticOrder& S, const Epi& E) {
;     ...
;             PG8_LDA(At, 1, 1); PG8_STAGE(PG8_SB(1, 0), b3, voffB); PG8_STAGE(PG8_SB(1, 1), b3 + hsB, voffB); PG8_STAGE(PG8_SA(1, 0), a3, voffA);
;             PG8_WAIT_V(8); PG8_WAIT_L(0); PG8_BAR; PG8_MMA(1, 0, At, B0); PG8_MMA(1, 1, At, B1); PG8_BAR; PG8_SCHED;
;         }
;         if (wr == 0) PG8_BAR;
	s_add_i32 s39, s39, s4
	v_lshl_add_u64 v[158:159], v[158:159], 0, s[24:25]
	s_mov_b32 m0, s39
	ds_read_b128 v[192:195], v157 offset:49152
	ds_read_b128 v[196:199], v157 offset:50176
	ds_read_b128 v[200:203], v157 offset:51200
	ds_read_b128 v[204:207], v157 offset:52224
	ds_read_b128 v[208:211], v157 offset:53248
	ds_read_b128 v[212:215], v157 offset:54272
	ds_read_b128 v[216:219], v157 offset:55296
	ds_read_b128 v[220:223], v157 offset:56320
	global_load_lds_dwordx4 v[158:159], off
	s_add_i32 m0, s39, 0x2000
	s_add_u32 s50, s50, 0x40080
	v_lshl_add_u64 v[158:159], v[224:225], 0, s[24:25]
	s_addc_u32 s51, s51, 0
	s_add_i32 s39, s41, s4
	global_load_lds_dwordx4 v[158:159], off
	v_lshl_add_u64 v[158:159], s[50:51], 0, v[130:131]
	s_mov_b32 m0, s39
	s_nop 0
	global_load_lds_dwordx4 v[158:159], off
	v_lshl_add_u64 v[158:159], s[50:51], 0, v[134:135]
	s_add_i32 m0, s39, 0x2000
	s_nop 0
	global_load_lds_dwordx4 v[158:159], off
	v_lshl_add_u64 v[158:159], v[226:227], 0, s[24:25]
	s_mov_b32 m0, s22
	s_nop 0
	global_load_lds_dwordx4 v[158:159], off
	v_lshl_add_u64 v[158:159], v[228:229], 0, s[24:25]
	s_mov_b32 m0, s23
	s_nop 0
	global_load_lds_dwordx4 v[158:159], off
	s_waitcnt vmcnt(8)
	s_waitcnt lgkmcnt(0)
	s_barrier
	s_setprio 1
	s_waitcnt lgkmcnt(0)
	v_mfma_f32_16x16x32_bf16 v[60:63], v[144:147], v[192:195], v[60:63]
	v_mfma_f32_16x16x32_bf16 v[56:59], v[162:165], v[192:195], v[56:59]
	v_mfma_f32_16x16x32_bf16 v[44:47], v[144:147], v[200:203], v[44:47]
	v_mfma_f32_16x16x32_bf16 v[40:43], v[162:165], v[200:203], v[40:43]
	v_mfma_f32_16x16x32_bf16 v[28:31], v[144:147], v[208:211], v[28:31]
	v_mfma_f32_16x16x32_bf16 v[24:27], v[162:165], v[208:211], v[24:27]
	v_mfma_f32_16x16x32_bf16 v[12:15], v[144:147], v[216:219], v[12:15]
	v_mfma_f32_16x16x32_bf16 v[8:11], v[162:165], v[216:219], v[8:11]
	v_mfma_f32_16x16x32_bf16 v[60:63], v[148:151], v[196:199], v[60:63]
	v_mfma_f32_16x16x32_bf16 v[56:59], v[166:169], v[196:199], v[56:59]
	v_mfma_f32_16x16x32_bf16 v[44:47], v[148:151], v[204:207], v[44:47]
	v_mfma_f32_16x16x32_bf16 v[40:43], v[166:169], v[204:207], v[40:43]
	v_mfma_f32_16x16x32_bf16 v[28:31], v[148:151], v[212:215], v[28:31]
	v_mfma_f32_16x16x32_bf16 v[24:27], v[166:169], v[212:215], v[24:27]
	v_mfma_f32_16x16x32_bf16 v[12:15], v[148:151], v[220:223], v[12:15]
	v_mfma_f32_16x16x32_bf16 v[8:11], v[166:169], v[220:223], v[8:11]
	s_setprio 0
	s_setprio 1
	v_mfma_f32_16x16x32_bf16 v[52:55], v[170:173], v[192:195], v[52:55]
	v_mfma_f32_16x16x32_bf16 v[48:51], v[184:187], v[192:195], v[48:51]
	v_mfma_f32_16x16x32_bf16 v[36:39], v[170:173], v[200:203], v[36:39]
	v_mfma_f32_16x16x32_bf16 v[32:35], v[184:187], v[200:203], v[32:35]
	v_mfma_f32_16x16x32_bf16 v[20:23], v[170:173], v[208:211], v[20:23]
	v_mfma_f32_16x16x32_bf16 v[16:19], v[184:187], v[208:211], v[16:19]
	v_mfma_f32_16x16x32_bf16 v[4:7], v[170:173], v[216:219], v[4:7]
	v_mfma_f32_16x16x32_bf16 v[0:3], v[184:187], v[216:219], v[0:3]
	v_mfma_f32_16x16x32_bf16 v[52:55], v[174:177], v[196:199], v[52:55]
	v_mfma_f32_16x16x32_bf16 v[48:51], v[188:191], v[196:199], v[48:51]
	v_mfma_f32_16x16x32_bf16 v[36:39], v[174:177], v[204:207], v[36:39]
	v_mfma_f32_16x16x32_bf16 v[32:35], v[188:191], v[204:207], v[32:35]
	v_mfma_f32_16x16x32_bf16 v[20:23], v[174:177], v[212:215], v[20:23]
	v_mfma_f32_16x16x32_bf16 v[16:19], v[188:191], v[212:215], v[16:19]
	v_mfma_f32_16x16x32_bf16 v[4:7], v[174:177], v[220:223], v[4:7]
	v_mfma_f32_16x16x32_bf16 v[0:3], v[188:191], v[220:223], v[0:3]
	s_setprio 3
	s_barrier
	s_add_i32 s35, s35, 2
	s_add_u32 s48, s48, 0x100
	s_addc_u32 s49, s49, 0
	s_add_u32 s13, s13, 0x100
	s_addc_u32 s34, s34, 0
	s_cmp_gt_u32 s35, 13
	s_cbranch_scc0 .LBB0_1234
	s_and_b64 vcc, exec, s[26:27]
	s_cbranch_vccz .LBB0_1237
	s_barrier

; #define PG8_STAGE(bufoff, gbase, voff) do { _Pragma("unroll") for (int _i = 0; _i < 2; ++_i) \
;         __builtin_amdgcn_global_load_lds((const unsigned*)((const char*)(gbase) + (voff)[_i]), (LAS unsigned*)(lds + (bufoff) + ldsw + _i * 8192), 16, 0, 0); } while (0)
; #define PG8_LDA(dst, b, h) do { _Pragma("unroll") for (int m = 0; m < 4; ++m) _Pragma("unroll") for (int k = 0; k < 2; ++k) dst[m][k] = *(const LAS bf16x8*)(lds + PG8_SA(b, h) + aoff + m * 2048 + k * 1024); } while (0)
; #define PG8_LDB(dst, b, h) do { _Pragma("unroll") for (int n = 0; n < 2; ++n) _Pragma("unroll") for (int k = 0; k < 2; ++k) dst[n][k] = *(const LAS bf16x8*)(lds + PG8_SB(b, h) + boff + n * 2048 + k * 1024); } while (0)
; #define PG8_MMA(ai, bj, At, Bt) do { __builtin_amdgcn_s_setprio(1); _Pragma("unroll") for (int m = 0; m < 4; ++m) _Pragma("unroll") for (int n = 0; n < 2; ++n) _Pragma("unroll") for (int k = 0; k < 2; ++k) \
;         acc[ai][bj][m][n] = __builtin_amdgcn_mfma_f32_16x16x32_bf16(Bt[n][k], At[m][k], acc[ai][bj][m][n], 0, 0, 0); __builtin_amdgcn_s_setprio(0); } while (0)
; #define PG8_WAIT_V(n) asm volatile("s_waitcnt vmcnt(" #n ")" ::: "memory")
; #define PG8_WAIT_L(n) asm volatile("s_waitcnt lgkmcnt(" #n ")" ::: "memory")
; #define PG8_BAR __builtin_amdgcn_s_barrier()
; #define PG8_SCHED __builtin_amdgcn_sched_barrier(0)
; template <class Epi>
; __device__ __forceinline__ void gemm_phase(LAS unsigned char* lds, const Gemm g, const StaticOrder& S, const Epi& E) {
;     ...
;             PG8_LDB(B0, 0, 0); PG8_LDB(B1, 0, 1); PG8_SCHED; PG8_LDA(At, 0, 0); PG8_STAGE(PG8_SA(1, 1), a1 + hsA, voffA);
;             PG8_WAIT_V(8); PG8_WAIT_L(0); PG8_BAR; PG8_MMA(0, 0, At, B0); PG8_MMA(0, 1, At, B1); PG8_BAR; PG8_SCHED;
;             PG8_LDA(At, 0, 1); PG8_STAGE(PG8_SB(0, 0), b2, voffB); PG8_STAGE(PG8_SB(0, 1), b2 + hsB, voffB); PG8_STAGE(PG8_SA(0, 0), a2, voffA);
;             PG8_WAIT_V(8); PG8_WAIT_L(0); PG8_BAR; PG8_MMA(1, 0, At, B0); PG8_MMA(1, 1, At, B1); PG8_BAR; PG8_SCHED;
.LBB0_1350:
	ds_read_b128 v[144:147], v155
	ds_read_b128 v[148:151], v155 offset:1024
	ds_read_b128 v[162:165], v155 offset:2048
	ds_read_b128 v[166:169], v155 offset:3072
	ds_read_b128 v[170:173], v156
	ds_read_b128 v[174:177], v156 offset:1024
	ds_read_b128 v[184:187], v156 offset:2048
	ds_read_b128 v[188:191], v156 offset:3072
	s_add_u32 s40, s38, 0xfffc0080
	s_addc_u32 s41, s39, -1
	s_cmp_eq_u32 s48, 12
	s_cselect_b32 s43, s25, s41
	s_cselect_b32 s42, s44, s40
	s_cselect_b32 s41, s15, s47
	s_cselect_b32 s40, s45, s46
	v_lshl_add_u64 v[224:225], s[38:39], 0, v[136:137]
	s_add_i32 m0, s17, 0xc000
	ds_read_b128 v[192:195], v157
	ds_read_b128 v[196:199], v157 offset:1024
	ds_read_b128 v[200:203], v157 offset:2048
	ds_read_b128 v[204:207], v157 offset:3072
	ds_read_b128 v[208:211], v157 offset:4096
	ds_read_b128 v[212:215], v157 offset:5120
	ds_read_b128 v[216:219], v157 offset:6144
	ds_read_b128 v[220:223], v157 offset:7168
	global_load_lds_dwordx4 v[224:225], off
	v_lshl_add_u64 v[224:225], s[38:39], 0, v[138:139]
	s_add_i32 m0, s17, 0xe000
	s_nop 0
	global_load_lds_dwordx4 v[224:225], off
	s_waitcnt vmcnt(8)
	s_waitcnt lgkmcnt(0)
	s_barrier
	s_setprio 1
	s_waitcnt lgkmcnt(0)
	v_mfma_f32_16x16x32_bf16 v[124:127], v[144:147], v[192:195], v[124:127]
	v_mfma_f32_16x16x32_bf16 v[120:123], v[162:165], v[192:195], v[120:123]
	v_mfma_f32_16x16x32_bf16 v[108:111], v[144:147], v[200:203], v[108:111]
	v_mfma_f32_16x16x32_bf16 v[104:107], v[162:165], v[200:203], v[104:107]
	v_mfma_f32_16x16x32_bf16 v[92:95], v[144:147], v[208:211], v[92:95]
	v_mfma_f32_16x16x32_bf16 v[88:91], v[162:165], v[208:211], v[88:91]
	v_mfma_f32_16x16x32_bf16 v[76:79], v[144:147], v[216:219], v[76:79]
	v_mfma_f32_16x16x32_bf16 v[72:75], v[162:165], v[216:219], v[72:75]
	v_mfma_f32_16x16x32_bf16 v[124:127], v[148:151], v[196:199], v[124:127]
	v_mfma_f32_16x16x32_bf16 v[120:123], v[166:169], v[196:199], v[120:123]
	v_mfma_f32_16x16x32_bf16 v[108:111], v[148:151], v[204:207], v[108:111]
	v_mfma_f32_16x16x32_bf16 v[104:107], v[166:169], v[204:207], v[104:107]
	v_mfma_f32_16x16x32_bf16 v[92:95], v[148:151], v[212:215], v[92:95]
	v_mfma_f32_16x16x32_bf16 v[88:91], v[166:169], v[212:215], v[88:91]
	v_mfma_f32_16x16x32_bf16 v[76:79], v[148:151], v[220:223], v[76:79]
	v_mfma_f32_16x16x32_bf16 v[72:75], v[166:169], v[220:223], v[72:75]
	s_setprio 0
	s_setprio 1
	v_mfma_f32_16x16x32_bf16 v[116:119], v[170:173], v[192:195], v[116:119]
	v_mfma_f32_16x16x32_bf16 v[112:115], v[184:187], v[192:195], v[112:115]
	v_mfma_f32_16x16x32_bf16 v[100:103], v[170:173], v[200:203], v[100:103]
	v_mfma_f32_16x16x32_bf16 v[96:99], v[184:187], v[200:203], v[96:99]
	v_mfma_f32_16x16x32_bf16 v[84:87], v[170:173], v[208:211], v[84:87]
	v_mfma_f32_16x16x32_bf16 v[80:83], v[184:187], v[208:211], v[80:83]
	v_mfma_f32_16x16x32_bf16 v[68:71], v[170:173], v[216:219], v[68:71]
	v_mfma_f32_16x16x32_bf16 v[64:67], v[184:187], v[216:219], v[64:67]
	v_mfma_f32_16x16x32_bf16 v[116:119], v[174:177], v[196:199], v[116:119]
	v_mfma_f32_16x16x32_bf16 v[112:115], v[188:191], v[196:199], v[112:115]
	v_mfma_f32_16x16x32_bf16 v[100:103], v[174:177], v[204:207], v[100:103]
	v_mfma_f32_16x16x32_bf16 v[96:99], v[188:191], v[204:207], v[96:99]
	v_mfma_f32_16x16x32_bf16 v[84:87], v[174:177], v[212:215], v[84:87]
	v_mfma_f32_16x16x32_bf16 v[80:83], v[188:191], v[212:215], v[80:83]
	v_mfma_f32_16x16x32_bf16 v[68:71], v[174:177], v[220:223], v[68:71]
	v_mfma_f32_16x16x32_bf16 v[64:67], v[188:191], v[220:223], v[64:67]
	s_setprio 3
	s_barrier
	s_add_i32 s49, s30, s4
	v_lshl_add_u64 v[224:225], s[40:41], 0, v[132:133]
	s_mov_b32 m0, s49
	ds_read_b128 v[192:195], v157 offset:16384
	ds_read_b128 v[196:199], v157 offset:17408
	ds_read_b128 v[200:203], v157 offset:18432
	ds_read_b128 v[204:207], v157 offset:19456
	ds_read_b128 v[208:211], v157 offset:20480
	ds_read_b128 v[212:215], v157 offset:21504
	ds_read_b128 v[216:219], v157 offset:22528
	ds_read_b128 v[220:223], v157 offset:23552
	global_load_lds_dwordx4 v[224:225], off
	s_add_i32 m0, s49, 0x2000
	s_add_u32 s50, s40, 0x40000
	v_lshl_add_u64 v[226:227], s[40:41], 0, v[128:129]
	s_addc_u32 s51, s41, 0
	s_add_i32 s49, s31, s4
	global_load_lds_dwordx4 v[226:227], off
	v_lshl_add_u64 v[228:229], s[50:51], 0, v[132:133]
	s_mov_b32 m0, s49
	v_lshl_add_u64 v[230:231], s[42:43], 0, v[130:131]
	global_load_lds_dwordx4 v[228:229], off
	v_lshl_add_u64 v[228:229], s[50:51], 0, v[128:129]
	s_add_i32 m0, s49, 0x2000
	s_nop 0
	global_load_lds_dwordx4 v[228:229], off
	v_lshl_add_u64 v[228:229], s[42:43], 0, v[134:135]
	s_mov_b32 m0, s17
	s_nop 0
	global_load_lds_dwordx4 v[228:229], off
	s_mov_b32 m0, s18
	s_nop 0
	global_load_lds_dwordx4 v[230:231], off
	s_waitcnt vmcnt(8)
	s_waitcnt lgkmcnt(0)
	s_barrier
; #define PG8_STAGE(bufoff, gbase, voff) do { _Pragma("unroll") for (int _i = 0; _i < 2; ++_i) \
;         __builtin_amdgcn_global_load_lds((const unsigned*)((const char*)(gbase) + (voff)[_i]), (LAS unsigned*)(lds + (bufoff) + ldsw + _i * 8192), 16, 0, 0); } while (0)
; #define PG8_LDA(dst, b, h) do { _Pragma("unroll") for (int m = 0; m < 4; ++m) _Pragma("unroll") for (int k = 0; k < 2; ++k) dst[m][k] = *(const LAS bf16x8*)(lds + PG8_SA(b, h) + aoff + m * 2048 + k * 1024); } while (0)
; #define PG8_LDB(dst, b, h) do { _Pragma("unroll") for (int n = 0; n < 2; ++n) _Pragma("unroll") for (int k = 0; k < 2; ++k) dst[n][k] = *(const LAS bf16x8*)(lds + PG8_SB(b, h) + boff + n * 2048 + k * 1024); } while (0)
; #define PG8_MMA(ai, bj, At, Bt) do { __builtin_amdgcn_s_setprio(1); _Pragma("unroll") for (int m = 0; m < 4; ++m) _Pragma("unroll") for (int n = 0; n < 2; ++n) _Pragma("unroll") for (int k = 0; k < 2; ++k) \
;         acc[ai][bj][m][n] = __builtin_amdgcn_mfma_f32_16x16x32_bf16(Bt[n][k], At[m][k], acc[ai][bj][m][n], 0, 0, 0); __builtin_amdgcn_s_setprio(0); } while (0)
; #define PG8_WAIT_V(n) asm volatile("s_waitcnt vmcnt(" #n ")" ::: "memory")
; #define PG8_WAIT_L(n) asm volatile("s_waitcnt lgkmcnt(" #n ")" ::: "memory")
; #define PG8_BAR __builtin_amdgcn_s_barrier()
; #define PG8_SCHED __builtin_amdgcn_sched_barrier(0)
; template <class Epi>
; __device__ __forceinline__ void gemm_phase(LAS unsigned char* lds, const Gemm g, const StaticOrder& S, const Epi& E) {
;     ...
;             PG8_WAIT_V(8); PG8_WAIT_L(0); PG8_BAR; PG8_MMA(1, 0, At, B0); PG8_MMA(1, 1, At, B1); PG8_BAR; PG8_SCHED;
;             PG8_LDB(B0, 1, 0); PG8_LDB(B1, 1, 1); PG8_SCHED; PG8_LDA(At, 1, 0); PG8_STAGE(PG8_SA(0, 1), a2 + hsA, voffA);
;             PG8_WAIT_V(8); PG8_WAIT_L(0); PG8_BAR; PG8_MMA(0, 0, At, B0); PG8_MMA(0, 1, At, B1); PG8_BAR; PG8_SCHED;
	s_setprio 1
	s_waitcnt lgkmcnt(0)
	v_mfma_f32_16x16x32_bf16 v[60:63], v[144:147], v[192:195], v[60:63]
	v_mfma_f32_16x16x32_bf16 v[56:59], v[162:165], v[192:195], v[56:59]
	v_mfma_f32_16x16x32_bf16 v[44:47], v[144:147], v[200:203], v[44:47]
	v_mfma_f32_16x16x32_bf16 v[40:43], v[162:165], v[200:203], v[40:43]
	v_mfma_f32_16x16x32_bf16 v[28:31], v[144:147], v[208:211], v[28:31]
	v_mfma_f32_16x16x32_bf16 v[24:27], v[162:165], v[208:211], v[24:27]
	v_mfma_f32_16x16x32_bf16 v[12:15], v[144:147], v[216:219], v[12:15]
	v_mfma_f32_16x16x32_bf16 v[8:11], v[162:165], v[216:219], v[8:11]
	v_mfma_f32_16x16x32_bf16 v[60:63], v[148:151], v[196:199], v[60:63]
	v_mfma_f32_16x16x32_bf16 v[56:59], v[166:169], v[196:199], v[56:59]
	v_mfma_f32_16x16x32_bf16 v[44:47], v[148:151], v[204:207], v[44:47]
	v_mfma_f32_16x16x32_bf16 v[40:43], v[166:169], v[204:207], v[40:43]
	v_mfma_f32_16x16x32_bf16 v[28:31], v[148:151], v[212:215], v[28:31]
	v_mfma_f32_16x16x32_bf16 v[24:27], v[166:169], v[212:215], v[24:27]
	v_mfma_f32_16x16x32_bf16 v[12:15], v[148:151], v[220:223], v[12:15]
	v_mfma_f32_16x16x32_bf16 v[8:11], v[166:169], v[220:223], v[8:11]
	s_setprio 0
	s_setprio 1
	v_mfma_f32_16x16x32_bf16 v[52:55], v[170:173], v[192:195], v[52:55]
	v_mfma_f32_16x16x32_bf16 v[48:51], v[184:187], v[192:195], v[48:51]
	v_mfma_f32_16x16x32_bf16 v[36:39], v[170:173], v[200:203], v[36:39]
	v_mfma_f32_16x16x32_bf16 v[32:35], v[184:187], v[200:203], v[32:35]
	v_mfma_f32_16x16x32_bf16 v[20:23], v[170:173], v[208:211], v[20:23]
	v_mfma_f32_16x16x32_bf16 v[16:19], v[184:187], v[208:211], v[16:19]
	v_mfma_f32_16x16x32_bf16 v[4:7], v[170:173], v[216:219], v[4:7]
	v_mfma_f32_16x16x32_bf16 v[0:3], v[184:187], v[216:219], v[0:3]
	v_mfma_f32_16x16x32_bf16 v[52:55], v[174:177], v[196:199], v[52:55]
	v_mfma_f32_16x16x32_bf16 v[48:51], v[188:191], v[196:199], v[48:51]
	v_mfma_f32_16x16x32_bf16 v[36:39], v[174:177], v[204:207], v[36:39]
	v_mfma_f32_16x16x32_bf16 v[32:35], v[188:191], v[204:207], v[32:35]
	v_mfma_f32_16x16x32_bf16 v[20:23], v[174:177], v[212:215], v[20:23]
	v_mfma_f32_16x16x32_bf16 v[16:19], v[188:191], v[212:215], v[16:19]
	v_mfma_f32_16x16x32_bf16 v[4:7], v[174:177], v[220:223], v[4:7]
	v_mfma_f32_16x16x32_bf16 v[0:3], v[188:191], v[220:223], v[0:3]
	s_setprio 3
	s_barrier
	s_add_i32 s49, 0, 0x18000
	v_add_u32_e32 v159, s49, v153
	s_add_i32 s50, 0, 0x1c000
	ds_read_b128 v[144:147], v159
	ds_read_b128 v[148:151], v159 offset:1024
	ds_read_b128 v[162:165], v159 offset:2048
	ds_read_b128 v[166:169], v159 offset:3072
	v_add_u32_e32 v159, s50, v153
	ds_read_b128 v[170:173], v159
	ds_read_b128 v[174:177], v159 offset:1024
	ds_read_b128 v[184:187], v159 offset:2048
	ds_read_b128 v[188:191], v159 offset:3072
	s_add_u32 s42, s42, 0x40000
	s_addc_u32 s43, s43, 0
	s_mov_b32 m0, s19
	v_lshl_add_u64 v[232:233], s[42:43], 0, v[134:135]
	ds_read_b128 v[192:195], v157 offset:32768
	ds_read_b128 v[196:199], v157 offset:33792
	ds_read_b128 v[200:203], v157 offset:34816
	ds_read_b128 v[204:207], v157 offset:35840
	ds_read_b128 v[208:211], v157 offset:36864
	ds_read_b128 v[212:215], v157 offset:37888
	ds_read_b128 v[216:219], v157 offset:38912
	ds_read_b128 v[220:223], v157 offset:39936
	global_load_lds_dwordx4 v[232:233], off
	v_lshl_add_u64 v[232:233], s[42:43], 0, v[130:131]
	s_mov_b32 m0, s22
	s_nop 0
	global_load_lds_dwordx4 v[232:233], off
	s_waitcnt vmcnt(8)
	s_waitcnt lgkmcnt(0)
	s_barrier
	s_setprio 1
	s_waitcnt lgkmcnt(0)
	v_mfma_f32_16x16x32_bf16 v[124:127], v[144:147], v[192:195], v[124:127]
	v_mfma_f32_16x16x32_bf16 v[120:123], v[162:165], v[192:195], v[120:123]
	v_mfma_f32_16x16x32_bf16 v[108:111], v[144:147], v[200:203], v[108:111]
	v_mfma_f32_16x16x32_bf16 v[104:107], v[162:165], v[200:203], v[104:107]
	v_mfma_f32_16x16x32_bf16 v[92:95], v[144:147], v[208:211], v[92:95]
	v_mfma_f32_16x16x32_bf16 v[88:91], v[162:165], v[208:211], v[88:91]
	v_mfma_f32_16x16x32_bf16 v[76:79], v[144:147], v[216:219], v[76:79]
	v_mfma_f32_16x16x32_bf16 v[72:75], v[162:165], v[216:219], v[72:75]
	v_mfma_f32_16x16x32_bf16 v[124:127], v[148:151], v[196:199], v[124:127]
	v_mfma_f32_16x16x32_bf16 v[120:123], v[166:169], v[196:199], v[120:123]
	v_mfma_f32_16x16x32_bf16 v[108:111], v[148:151], v[204:207], v[108:111]
	v_mfma_f32_16x16x32_bf16 v[104:107], v[166:169], v[204:207], v[104:107]
	v_mfma_f32_16x16x32_bf16 v[92:95], v[148:151], v[212:215], v[92:95]
	v_mfma_f32_16x16x32_bf16 v[88:91], v[166:169], v[212:215], v[88:91]
	v_mfma_f32_16x16x32_bf16 v[76:79], v[148:151], v[220:223], v[76:79]
	v_mfma_f32_16x16x32_bf16 v[72:75], v[166:169], v[220:223], v[72:75]
	s_setprio 0
	s_setprio 1
	v_mfma_f32_16x16x32_bf16 v[116:119], v[170:173], v[192:195], v[116:119]
	v_mfma_f32_16x16x32_bf16 v[112:115], v[184:187], v[192:195], v[112:115]
	v_mfma_f32_16x16x32_bf16 v[100:103], v[170:173], v[200:203], v[100:103]
	v_mfma_f32_16x16x32_bf16 v[96:99], v[184:187], v[200:203], v[96:99]
	v_mfma_f32_16x16x32_bf16 v[84:87], v[170:173], v[208:211], v[84:87]
	v_mfma_f32_16x16x32_bf16 v[80:83], v[184:187], v[208:211], v[80:83]
	v_mfma_f32_16x16x32_bf16 v[68:71], v[170:173], v[216:219], v[68:71]
	v_mfma_f32_16x16x32_bf16 v[64:67], v[184:187], v[216:219], v[64:67]
	v_mfma_f32_16x16x32_bf16 v[116:119], v[174:177], v[196:199], v[116:119]
	v_mfma_f32_16x16x32_bf16 v[112:115], v[188:191], v[196:199], v[112:115]
	v_mfma_f32_16x16x32_bf16 v[100:103], v[174:177], v[204:207], v[100:103]
	v_mfma_f32_16x16x32_bf16 v[96:99], v[188:191], v[204:207], v[96:99]
	v_mfma_f32_16x16x32_bf16 v[84:87], v[174:177], v[212:215], v[84:87]
	v_mfma_f32_16x16x32_bf16 v[80:83], v[188:191], v[212:215], v[80:83]
	v_mfma_f32_16x16x32_bf16 v[68:71], v[174:177], v[220:223], v[68:71]
	v_mfma_f32_16x16x32_bf16 v[64:67], v[188:191], v[220:223], v[64:67]
	s_setprio 3
	s_barrier
; #define PG8_STAGE(bufoff, gbase, voff) do { _Pragma("unroll") for (int _i = 0; _i < 2; ++_i) \
;         __builtin_amdgcn_global_load_lds((const unsigned*)((const char*)(gbase) + (voff)[_i]), (LAS unsigned*)(lds + (bufoff) + ldsw + _i * 8192), 16, 0, 0); } while (0)
; #define PG8_LDA(dst, b, h) do { _Pragma("unroll") for (int m = 0; m < 4; ++m) _Pragma("unroll") for (int k = 0; k < 2; ++k) dst[m][k] = *(const LAS bf16x8*)(lds + PG8_SA(b, h) + aoff + m * 2048 + k * 1024); } while (0)
; #define PG8_MMA(ai, bj, At, Bt) do { __builtin_amdgcn_s_setprio(1); _Pragma("unroll") for (int m = 0; m < 4; ++m) _Pragma("unroll") for (int n = 0; n < 2; ++n) _Pragma("unroll") for (int k = 0; k < 2; ++k) \
;         acc[ai][bj][m][n] = __builtin_amdgcn_mfma_f32_16x16x32_bf16(Bt[n][k], At[m][k], acc[ai][bj][m][n], 0, 0, 0); __builtin_amdgcn_s_setprio(0); } while (0)
; #define PG8_WAIT_V(n) asm volatile("s_waitcnt vmcnt(" #n ")" ::: "memory")
; #define PG8_WAIT_L(n) asm volatile("s_waitcnt lgkmcnt(" #n ")" ::: "memory")
; #define PG8_BAR __builtin_amdgcn_s_barrier()
; #define PG8_SCHED __builtin_amdgcn_sched_barrier(0)
; template <class Epi>
; __device__ __forceinline__ void gemm_phase(LAS unsigned char* lds, const Gemm g, const StaticOrder& S, const Epi& E) {
;     ...
;             PG8_LDA(At, 1, 1); PG8_STAGE(PG8_SB(1, 0), b3, voffB); PG8_STAGE(PG8_SB(1, 1), b3 + hsB, voffB); PG8_STAGE(PG8_SA(1, 0), a3, voffA);
;             PG8_WAIT_V(8); PG8_WAIT_L(0); PG8_BAR; PG8_MMA(1, 0, At, B0); PG8_MMA(1, 1, At, B1); PG8_BAR; PG8_SCHED;
;         }
;         if (wr == 0) PG8_BAR;
	s_add_i32 s42, s49, s4
	v_lshl_add_u64 v[224:225], v[224:225], 0, s[10:11]
	s_mov_b32 m0, s42
	ds_read_b128 v[192:195], v157 offset:49152
	ds_read_b128 v[196:199], v157 offset:50176
	ds_read_b128 v[200:203], v157 offset:51200
	ds_read_b128 v[204:207], v157 offset:52224
	ds_read_b128 v[208:211], v157 offset:53248
	ds_read_b128 v[212:215], v157 offset:54272
	ds_read_b128 v[216:219], v157 offset:55296
	ds_read_b128 v[220:223], v157 offset:56320
	global_load_lds_dwordx4 v[224:225], off
	s_add_i32 m0, s42, 0x2000
	s_add_u32 s40, s40, 0x40080
	v_lshl_add_u64 v[224:225], v[226:227], 0, s[10:11]
	s_addc_u32 s41, s41, 0
	s_add_i32 s42, s50, s4
	global_load_lds_dwordx4 v[224:225], off
	v_lshl_add_u64 v[224:225], s[40:41], 0, v[132:133]
	s_mov_b32 m0, s42
	s_nop 0
	global_load_lds_dwordx4 v[224:225], off
	v_lshl_add_u64 v[224:225], s[40:41], 0, v[128:129]
	s_add_i32 m0, s42, 0x2000
	s_nop 0
	global_load_lds_dwordx4 v[224:225], off
	v_lshl_add_u64 v[224:225], v[228:229], 0, s[10:11]
	s_mov_b32 m0, s0
	s_nop 0
	global_load_lds_dwordx4 v[224:225], off
	v_lshl_add_u64 v[224:225], v[230:231], 0, s[10:11]
	s_mov_b32 m0, s1
	s_nop 0
	global_load_lds_dwordx4 v[224:225], off
	s_waitcnt vmcnt(8)
	s_waitcnt lgkmcnt(0)
	s_barrier
	s_setprio 1
	s_waitcnt lgkmcnt(0)
	v_mfma_f32_16x16x32_bf16 v[60:63], v[144:147], v[192:195], v[60:63]
	v_mfma_f32_16x16x32_bf16 v[56:59], v[162:165], v[192:195], v[56:59]
	v_mfma_f32_16x16x32_bf16 v[44:47], v[144:147], v[200:203], v[44:47]
	v_mfma_f32_16x16x32_bf16 v[40:43], v[162:165], v[200:203], v[40:43]
	v_mfma_f32_16x16x32_bf16 v[28:31], v[144:147], v[208:211], v[28:31]
	v_mfma_f32_16x16x32_bf16 v[24:27], v[162:165], v[208:211], v[24:27]
	v_mfma_f32_16x16x32_bf16 v[12:15], v[144:147], v[216:219], v[12:15]
	v_mfma_f32_16x16x32_bf16 v[8:11], v[162:165], v[216:219], v[8:11]
	v_mfma_f32_16x16x32_bf16 v[60:63], v[148:151], v[196:199], v[60:63]
	v_mfma_f32_16x16x32_bf16 v[56:59], v[166:169], v[196:199], v[56:59]
	v_mfma_f32_16x16x32_bf16 v[44:47], v[148:151], v[204:207], v[44:47]
	v_mfma_f32_16x16x32_bf16 v[40:43], v[166:169], v[204:207], v[40:43]
	v_mfma_f32_16x16x32_bf16 v[28:31], v[148:151], v[212:215], v[28:31]
	v_mfma_f32_16x16x32_bf16 v[24:27], v[166:169], v[212:215], v[24:27]
	v_mfma_f32_16x16x32_bf16 v[12:15], v[148:151], v[220:223], v[12:15]
	v_mfma_f32_16x16x32_bf16 v[8:11], v[166:169], v[220:223], v[8:11]
	s_setprio 0
	s_setprio 1
	v_mfma_f32_16x16x32_bf16 v[52:55], v[170:173], v[192:195], v[52:55]
	v_mfma_f32_16x16x32_bf16 v[48:51], v[184:187], v[192:195], v[48:51]
	v_mfma_f32_16x16x32_bf16 v[36:39], v[170:173], v[200:203], v[36:39]
	v_mfma_f32_16x16x32_bf16 v[32:35], v[184:187], v[200:203], v[32:35]
	v_mfma_f32_16x16x32_bf16 v[20:23], v[170:173], v[208:211], v[20:23]
	v_mfma_f32_16x16x32_bf16 v[16:19], v[184:187], v[208:211], v[16:19]
	v_mfma_f32_16x16x32_bf16 v[4:7], v[170:173], v[216:219], v[4:7]
	v_mfma_f32_16x16x32_bf16 v[0:3], v[184:187], v[216:219], v[0:3]
	v_mfma_f32_16x16x32_bf16 v[52:55], v[174:177], v[196:199], v[52:55]
	v_mfma_f32_16x16x32_bf16 v[48:51], v[188:191], v[196:199], v[48:51]
	v_mfma_f32_16x16x32_bf16 v[36:39], v[174:177], v[204:207], v[36:39]
	v_mfma_f32_16x16x32_bf16 v[32:35], v[188:191], v[204:207], v[32:35]
	v_mfma_f32_16x16x32_bf16 v[20:23], v[174:177], v[212:215], v[20:23]
	v_mfma_f32_16x16x32_bf16 v[16:19], v[188:191], v[212:215], v[16:19]
	v_mfma_f32_16x16x32_bf16 v[4:7], v[174:177], v[220:223], v[4:7]
	v_mfma_f32_16x16x32_bf16 v[0:3], v[188:191], v[220:223], v[0:3]
	s_setprio 3
	s_barrier
	s_add_i32 s48, s48, 2
	s_add_u32 s38, s38, 0x100
	s_addc_u32 s39, s39, 0
	s_add_u32 s46, s46, 0x100
	s_addc_u32 s47, s47, 0
	s_cmp_gt_u32 s48, 13
	s_cbranch_scc0 .LBB0_1350
	s_and_b64 vcc, exec, s[12:13]
	s_cbranch_vccz .LBB0_1353
	s_barrier

; #define PG8_STAGE(bufoff, gbase, voff) do { _Pragma("unroll") for (int _i = 0; _i < 2; ++_i) \
;         __builtin_amdgcn_global_load_lds((const unsigned*)((const char*)(gbase) + (voff)[_i]), (LAS unsigned*)(lds + (bufoff) + ldsw + _i * 8192), 16, 0, 0); } while (0)
; #define PG8_LDA(dst, b, h) do { _Pragma("unroll") for (int m = 0; m < 4; ++m) _Pragma("unroll") for (int k = 0; k < 2; ++k) dst[m][k] = *(const LAS bf16x8*)(lds + PG8_SA(b, h) + aoff + m * 2048 + k * 1024); } while (0)
; #define PG8_LDB(dst, b, h) do { _Pragma("unroll") for (int n = 0; n < 2; ++n) _Pragma("unroll") for (int k = 0; k < 2; ++k) dst[n][k] = *(const LAS bf16x8*)(lds + PG8_SB(b, h) + boff + n * 2048 + k * 1024); } while (0)
; #define PG8_MMA(ai, bj, At, Bt) do { __builtin_amdgcn_s_setprio(1); _Pragma("unroll") for (int m = 0; m < 4; ++m) _Pragma("unroll") for (int n = 0; n < 2; ++n) _Pragma("unroll") for (int k = 0; k < 2; ++k) \
;         acc[ai][bj][m][n] = __builtin_amdgcn_mfma_f32_16x16x32_bf16(Bt[n][k], At[m][k], acc[ai][bj][m][n], 0, 0, 0); __builtin_amdgcn_s_setprio(0); } while (0)
; #define PG8_WAIT_V(n) asm volatile("s_waitcnt vmcnt(" #n ")" ::: "memory")
; #define PG8_WAIT_L(n) asm volatile("s_waitcnt lgkmcnt(" #n ")" ::: "memory")
; #define PG8_BAR __builtin_amdgcn_s_barrier()
; #define PG8_SCHED __builtin_amdgcn_sched_barrier(0)
; template <class Epi>
; __device__ __forceinline__ void gemm_phase(LAS unsigned char* lds, const Gemm g, const StaticOrder& S, const Epi& E) {
;     ...
;             PG8_LDB(B0, 0, 0); PG8_LDB(B1, 0, 1); PG8_SCHED; PG8_LDA(At, 0, 0); PG8_STAGE(PG8_SA(1, 1), a1 + hsA, voffA);
;             PG8_WAIT_V(8); PG8_WAIT_L(0); PG8_BAR; PG8_MMA(0, 0, At, B0); PG8_MMA(0, 1, At, B1); PG8_BAR; PG8_SCHED;
;             PG8_LDA(At, 0, 1); PG8_STAGE(PG8_SB(0, 0), b2, voffB); PG8_STAGE(PG8_SB(0, 1), b2 + hsB, voffB); PG8_STAGE(PG8_SA(0, 0), a2, voffA);
;             PG8_WAIT_V(8); PG8_WAIT_L(0); PG8_BAR; PG8_MMA(1, 0, At, B0); PG8_MMA(1, 1, At, B1); PG8_BAR; PG8_SCHED;
.LBB0_1433:
	ds_read_b128 v[144:147], v202
	ds_read_b128 v[148:151], v202 offset:1024
	ds_read_b128 v[152:155], v202 offset:2048
	ds_read_b128 v[156:159], v202 offset:3072
	ds_read_b128 v[160:163], v203
	ds_read_b128 v[164:167], v203 offset:1024
	ds_read_b128 v[168:171], v203 offset:2048
	ds_read_b128 v[172:175], v203 offset:3072
	s_add_u32 s34, s26, 0x100
	s_addc_u32 s35, s27, 0
	s_cmp_eq_u32 s51, 40
	s_cselect_b32 s39, s1, s35
	s_cselect_b32 s38, s0, s34
	s_cselect_b32 s37, s23, s50
	s_cselect_b32 s36, s22, s25
	v_lshl_add_u64 v[176:177], s[26:27], 0, v[136:137]
	s_add_i32 m0, s17, 0xc000
	ds_read_b128 v[216:219], v204
	ds_read_b128 v[220:223], v204 offset:1024
	ds_read_b128 v[224:227], v204 offset:2048
	ds_read_b128 v[228:231], v204 offset:3072
	ds_read_b128 v[232:235], v204 offset:4096
	ds_read_b128 v[236:239], v204 offset:5120
	ds_read_b128 v[240:243], v204 offset:6144
	ds_read_b128 v[244:247], v204 offset:7168
	global_load_lds_dwordx4 v[176:177], off
	v_lshl_add_u64 v[176:177], s[26:27], 0, v[138:139]
	s_add_i32 m0, s17, 0xe000
	s_nop 0
	global_load_lds_dwordx4 v[176:177], off
	s_waitcnt vmcnt(8)
	s_waitcnt lgkmcnt(0)
	s_barrier
	s_setprio 1
	s_waitcnt lgkmcnt(0)
	v_mfma_f32_16x16x32_bf16 v[124:127], v[144:147], v[216:219], v[124:127]
	v_mfma_f32_16x16x32_bf16 v[120:123], v[152:155], v[216:219], v[120:123]
	v_mfma_f32_16x16x32_bf16 v[108:111], v[144:147], v[224:227], v[108:111]
	v_mfma_f32_16x16x32_bf16 v[104:107], v[152:155], v[224:227], v[104:107]
	v_mfma_f32_16x16x32_bf16 v[92:95], v[144:147], v[232:235], v[92:95]
	v_mfma_f32_16x16x32_bf16 v[88:91], v[152:155], v[232:235], v[88:91]
	v_mfma_f32_16x16x32_bf16 v[76:79], v[144:147], v[240:243], v[76:79]
	v_mfma_f32_16x16x32_bf16 v[72:75], v[152:155], v[240:243], v[72:75]
	v_mfma_f32_16x16x32_bf16 v[124:127], v[148:151], v[220:223], v[124:127]
	v_mfma_f32_16x16x32_bf16 v[120:123], v[156:159], v[220:223], v[120:123]
	v_mfma_f32_16x16x32_bf16 v[108:111], v[148:151], v[228:231], v[108:111]
	v_mfma_f32_16x16x32_bf16 v[104:107], v[156:159], v[228:231], v[104:107]
	v_mfma_f32_16x16x32_bf16 v[92:95], v[148:151], v[236:239], v[92:95]
	v_mfma_f32_16x16x32_bf16 v[88:91], v[156:159], v[236:239], v[88:91]
	v_mfma_f32_16x16x32_bf16 v[76:79], v[148:151], v[244:247], v[76:79]
	v_mfma_f32_16x16x32_bf16 v[72:75], v[156:159], v[244:247], v[72:75]
	s_setprio 0
	s_setprio 1
	v_mfma_f32_16x16x32_bf16 v[116:119], v[160:163], v[216:219], v[116:119]
	v_mfma_f32_16x16x32_bf16 v[112:115], v[168:171], v[216:219], v[112:115]
	v_mfma_f32_16x16x32_bf16 v[100:103], v[160:163], v[224:227], v[100:103]
	v_mfma_f32_16x16x32_bf16 v[96:99], v[168:171], v[224:227], v[96:99]
	v_mfma_f32_16x16x32_bf16 v[84:87], v[160:163], v[232:235], v[84:87]
	v_mfma_f32_16x16x32_bf16 v[80:83], v[168:171], v[232:235], v[80:83]
	v_mfma_f32_16x16x32_bf16 v[68:71], v[160:163], v[240:243], v[68:71]
	v_mfma_f32_16x16x32_bf16 v[64:67], v[168:171], v[240:243], v[64:67]
	v_mfma_f32_16x16x32_bf16 v[116:119], v[164:167], v[220:223], v[116:119]
	v_mfma_f32_16x16x32_bf16 v[112:115], v[172:175], v[220:223], v[112:115]
	v_mfma_f32_16x16x32_bf16 v[100:103], v[164:167], v[228:231], v[100:103]
	v_mfma_f32_16x16x32_bf16 v[96:99], v[172:175], v[228:231], v[96:99]
	v_mfma_f32_16x16x32_bf16 v[84:87], v[164:167], v[236:239], v[84:87]
	v_mfma_f32_16x16x32_bf16 v[80:83], v[172:175], v[236:239], v[80:83]
	v_mfma_f32_16x16x32_bf16 v[68:71], v[164:167], v[244:247], v[68:71]
	v_mfma_f32_16x16x32_bf16 v[64:67], v[172:175], v[244:247], v[64:67]
	s_setprio 3
	s_barrier
	s_add_i32 s26, s45, s16
	v_lshl_add_u64 v[176:177], s[36:37], 0, v[130:131]
	s_mov_b32 m0, s26
	ds_read_b128 v[216:219], v204 offset:16384
	ds_read_b128 v[220:223], v204 offset:17408
	ds_read_b128 v[224:227], v204 offset:18432
	ds_read_b128 v[228:231], v204 offset:19456
	ds_read_b128 v[232:235], v204 offset:20480
	ds_read_b128 v[236:239], v204 offset:21504
	ds_read_b128 v[240:243], v204 offset:22528
	ds_read_b128 v[244:247], v204 offset:23552
	global_load_lds_dwordx4 v[176:177], off
	s_add_i32 m0, s26, 0x2000
	s_add_u32 s26, s36, 0xb0000
	v_lshl_add_u64 v[248:249], s[36:37], 0, v[134:135]
	s_addc_u32 s27, s37, 0
	s_add_i32 s52, s46, s16
	global_load_lds_dwordx4 v[248:249], off
	v_lshl_add_u64 v[250:251], s[26:27], 0, v[130:131]
	s_mov_b32 m0, s52
	v_lshl_add_u64 v[252:253], s[38:39], 0, v[132:133]
	global_load_lds_dwordx4 v[250:251], off
	v_lshl_add_u64 v[250:251], s[26:27], 0, v[134:135]
	s_add_i32 m0, s52, 0x2000
	s_nop 0
	global_load_lds_dwordx4 v[250:251], off
	v_lshl_add_u64 v[250:251], s[38:39], 0, v[128:129]
	s_mov_b32 m0, s17
	s_nop 0
	global_load_lds_dwordx4 v[250:251], off
	s_mov_b32 m0, s28
	s_nop 0
	global_load_lds_dwordx4 v[252:253], off
	s_waitcnt vmcnt(8)
	s_waitcnt lgkmcnt(0)
	s_barrier
; #define PG8_STAGE(bufoff, gbase, voff) do { _Pragma("unroll") for (int _i = 0; _i < 2; ++_i) \
;         __builtin_amdgcn_global_load_lds((const unsigned*)((const char*)(gbase) + (voff)[_i]), (LAS unsigned*)(lds + (bufoff) + ldsw + _i * 8192), 16, 0, 0); } while (0)
; #define PG8_LDA(dst, b, h) do { _Pragma("unroll") for (int m = 0; m < 4; ++m) _Pragma("unroll") for (int k = 0; k < 2; ++k) dst[m][k] = *(const LAS bf16x8*)(lds + PG8_SA(b, h) + aoff + m * 2048 + k * 1024); } while (0)
; #define PG8_LDB(dst, b, h) do { _Pragma("unroll") for (int n = 0; n < 2; ++n) _Pragma("unroll") for (int k = 0; k < 2; ++k) dst[n][k] = *(const LAS bf16x8*)(lds + PG8_SB(b, h) + boff + n * 2048 + k * 1024); } while (0)
; #define PG8_MMA(ai, bj, At, Bt) do { __builtin_amdgcn_s_setprio(1); _Pragma("unroll") for (int m = 0; m < 4; ++m) _Pragma("unroll") for (int n = 0; n < 2; ++n) _Pragma("unroll") for (int k = 0; k < 2; ++k) \
;         acc[ai][bj][m][n] = __builtin_amdgcn_mfma_f32_16x16x32_bf16(Bt[n][k], At[m][k], acc[ai][bj][m][n], 0, 0, 0); __builtin_amdgcn_s_setprio(0); } while (0)
; #define PG8_WAIT_V(n) asm volatile("s_waitcnt vmcnt(" #n ")" ::: "memory")
; #define PG8_WAIT_L(n) asm volatile("s_waitcnt lgkmcnt(" #n ")" ::: "memory")
; #define PG8_BAR __builtin_amdgcn_s_barrier()
; #define PG8_SCHED __builtin_amdgcn_sched_barrier(0)
; template <class Epi>
; __device__ __forceinline__ void gemm_phase(LAS unsigned char* lds, const Gemm g, const StaticOrder& S, const Epi& E) {
;     ...
;             PG8_WAIT_V(8); PG8_WAIT_L(0); PG8_BAR; PG8_MMA(1, 0, At, B0); PG8_MMA(1, 1, At, B1); PG8_BAR; PG8_SCHED;
;             PG8_LDB(B0, 1, 0); PG8_LDB(B1, 1, 1); PG8_SCHED; PG8_LDA(At, 1, 0); PG8_STAGE(PG8_SA(0, 1), a2 + hsA, voffA);
;             PG8_WAIT_V(8); PG8_WAIT_L(0); PG8_BAR; PG8_MMA(0, 0, At, B0); PG8_MMA(0, 1, At, B1); PG8_BAR; PG8_SCHED;
	s_setprio 1
	s_waitcnt lgkmcnt(0)
	v_mfma_f32_16x16x32_bf16 v[60:63], v[144:147], v[216:219], v[60:63]
	v_mfma_f32_16x16x32_bf16 v[56:59], v[152:155], v[216:219], v[56:59]
	v_mfma_f32_16x16x32_bf16 v[44:47], v[144:147], v[224:227], v[44:47]
	v_mfma_f32_16x16x32_bf16 v[40:43], v[152:155], v[224:227], v[40:43]
	v_mfma_f32_16x16x32_bf16 v[28:31], v[144:147], v[232:235], v[28:31]
	v_mfma_f32_16x16x32_bf16 v[24:27], v[152:155], v[232:235], v[24:27]
	v_mfma_f32_16x16x32_bf16 v[12:15], v[144:147], v[240:243], v[12:15]
	v_mfma_f32_16x16x32_bf16 v[8:11], v[152:155], v[240:243], v[8:11]
	v_mfma_f32_16x16x32_bf16 v[60:63], v[148:151], v[220:223], v[60:63]
	v_mfma_f32_16x16x32_bf16 v[56:59], v[156:159], v[220:223], v[56:59]
	v_mfma_f32_16x16x32_bf16 v[44:47], v[148:151], v[228:231], v[44:47]
	v_mfma_f32_16x16x32_bf16 v[40:43], v[156:159], v[228:231], v[40:43]
	v_mfma_f32_16x16x32_bf16 v[28:31], v[148:151], v[236:239], v[28:31]
	v_mfma_f32_16x16x32_bf16 v[24:27], v[156:159], v[236:239], v[24:27]
	v_mfma_f32_16x16x32_bf16 v[12:15], v[148:151], v[244:247], v[12:15]
	v_mfma_f32_16x16x32_bf16 v[8:11], v[156:159], v[244:247], v[8:11]
	s_setprio 0
	s_setprio 1
	v_mfma_f32_16x16x32_bf16 v[52:55], v[160:163], v[216:219], v[52:55]
	v_mfma_f32_16x16x32_bf16 v[48:51], v[168:171], v[216:219], v[48:51]
	v_mfma_f32_16x16x32_bf16 v[36:39], v[160:163], v[224:227], v[36:39]
	v_mfma_f32_16x16x32_bf16 v[32:35], v[168:171], v[224:227], v[32:35]
	v_mfma_f32_16x16x32_bf16 v[20:23], v[160:163], v[232:235], v[20:23]
	v_mfma_f32_16x16x32_bf16 v[16:19], v[168:171], v[232:235], v[16:19]
	v_mfma_f32_16x16x32_bf16 v[4:7], v[160:163], v[240:243], v[4:7]
	v_mfma_f32_16x16x32_bf16 v[0:3], v[168:171], v[240:243], v[0:3]
	v_mfma_f32_16x16x32_bf16 v[52:55], v[164:167], v[220:223], v[52:55]
	v_mfma_f32_16x16x32_bf16 v[48:51], v[172:175], v[220:223], v[48:51]
	v_mfma_f32_16x16x32_bf16 v[36:39], v[164:167], v[228:231], v[36:39]
	v_mfma_f32_16x16x32_bf16 v[32:35], v[172:175], v[228:231], v[32:35]
	v_mfma_f32_16x16x32_bf16 v[20:23], v[164:167], v[236:239], v[20:23]
	v_mfma_f32_16x16x32_bf16 v[16:19], v[172:175], v[236:239], v[16:19]
	v_mfma_f32_16x16x32_bf16 v[4:7], v[164:167], v[244:247], v[4:7]
	v_mfma_f32_16x16x32_bf16 v[0:3], v[172:175], v[244:247], v[0:3]
	s_setprio 3
	s_barrier
	s_add_i32 s52, 0, 0x18000
	s_add_i32 s53, 0, 0x1c000
	v_add_u32_e32 v156, s52, v184
	v_add_u32_e32 v172, s53, v184
	ds_read_b128 v[144:147], v156
	ds_read_b128 v[148:151], v156 offset:1024
	ds_read_b128 v[152:155], v156 offset:2048
	ds_read_b128 v[156:159], v156 offset:3072
	ds_read_b128 v[160:163], v172
	ds_read_b128 v[164:167], v172 offset:1024
	ds_read_b128 v[168:171], v172 offset:2048
	ds_read_b128 v[172:175], v172 offset:3072
	s_add_u32 s26, s38, 0xb0000
	s_addc_u32 s27, s39, 0
	s_mov_b32 m0, s29
	v_lshl_add_u64 v[178:179], s[26:27], 0, v[128:129]
	ds_read_b128 v[216:219], v204 offset:32768
	ds_read_b128 v[220:223], v204 offset:33792
	ds_read_b128 v[224:227], v204 offset:34816
	ds_read_b128 v[228:231], v204 offset:35840
	ds_read_b128 v[232:235], v204 offset:36864
	ds_read_b128 v[236:239], v204 offset:37888
	ds_read_b128 v[240:243], v204 offset:38912
	ds_read_b128 v[244:247], v204 offset:39936
	global_load_lds_dwordx4 v[178:179], off
	v_lshl_add_u64 v[178:179], s[26:27], 0, v[132:133]
	s_mov_b32 m0, s30
	s_nop 0
	global_load_lds_dwordx4 v[178:179], off
	s_waitcnt vmcnt(8)
	s_waitcnt lgkmcnt(0)
	s_barrier
	s_setprio 1
	s_waitcnt lgkmcnt(0)
	v_mfma_f32_16x16x32_bf16 v[124:127], v[144:147], v[216:219], v[124:127]
	v_mfma_f32_16x16x32_bf16 v[120:123], v[152:155], v[216:219], v[120:123]
	v_mfma_f32_16x16x32_bf16 v[108:111], v[144:147], v[224:227], v[108:111]
	v_mfma_f32_16x16x32_bf16 v[104:107], v[152:155], v[224:227], v[104:107]
	v_mfma_f32_16x16x32_bf16 v[92:95], v[144:147], v[232:235], v[92:95]
	v_mfma_f32_16x16x32_bf16 v[88:91], v[152:155], v[232:235], v[88:91]
	v_mfma_f32_16x16x32_bf16 v[76:79], v[144:147], v[240:243], v[76:79]
	v_mfma_f32_16x16x32_bf16 v[72:75], v[152:155], v[240:243], v[72:75]
	v_mfma_f32_16x16x32_bf16 v[124:127], v[148:151], v[220:223], v[124:127]
	v_mfma_f32_16x16x32_bf16 v[120:123], v[156:159], v[220:223], v[120:123]
	v_mfma_f32_16x16x32_bf16 v[108:111], v[148:151], v[228:231], v[108:111]
	v_mfma_f32_16x16x32_bf16 v[104:107], v[156:159], v[228:231], v[104:107]
	v_mfma_f32_16x16x32_bf16 v[92:95], v[148:151], v[236:239], v[92:95]
	v_mfma_f32_16x16x32_bf16 v[88:91], v[156:159], v[236:239], v[88:91]
	v_mfma_f32_16x16x32_bf16 v[76:79], v[148:151], v[244:247], v[76:79]
	v_mfma_f32_16x16x32_bf16 v[72:75], v[156:159], v[244:247], v[72:75]
	s_setprio 0
	s_setprio 1
	v_mfma_f32_16x16x32_bf16 v[116:119], v[160:163], v[216:219], v[116:119]
	v_mfma_f32_16x16x32_bf16 v[112:115], v[168:171], v[216:219], v[112:115]
	v_mfma_f32_16x16x32_bf16 v[100:103], v[160:163], v[224:227], v[100:103]
	v_mfma_f32_16x16x32_bf16 v[96:99], v[168:171], v[224:227], v[96:99]
	v_mfma_f32_16x16x32_bf16 v[84:87], v[160:163], v[232:235], v[84:87]
	v_mfma_f32_16x16x32_bf16 v[80:83], v[168:171], v[232:235], v[80:83]
	v_mfma_f32_16x16x32_bf16 v[68:71], v[160:163], v[240:243], v[68:71]
	v_mfma_f32_16x16x32_bf16 v[64:67], v[168:171], v[240:243], v[64:67]
	v_mfma_f32_16x16x32_bf16 v[116:119], v[164:167], v[220:223], v[116:119]
	v_mfma_f32_16x16x32_bf16 v[112:115], v[172:175], v[220:223], v[112:115]
	v_mfma_f32_16x16x32_bf16 v[100:103], v[164:167], v[228:231], v[100:103]
	v_mfma_f32_16x16x32_bf16 v[96:99], v[172:175], v[228:231], v[96:99]
	v_mfma_f32_16x16x32_bf16 v[84:87], v[164:167], v[236:239], v[84:87]
	v_mfma_f32_16x16x32_bf16 v[80:83], v[172:175], v[236:239], v[80:83]
	v_mfma_f32_16x16x32_bf16 v[68:71], v[164:167], v[244:247], v[68:71]
	v_mfma_f32_16x16x32_bf16 v[64:67], v[172:175], v[244:247], v[64:67]
	s_setprio 3
	s_barrier
; #define PG8_STAGE(bufoff, gbase, voff) do { _Pragma("unroll") for (int _i = 0; _i < 2; ++_i) \
;         __builtin_amdgcn_global_load_lds((const unsigned*)((const char*)(gbase) + (voff)[_i]), (LAS unsigned*)(lds + (bufoff) + ldsw + _i * 8192), 16, 0, 0); } while (0)
; #define PG8_LDA(dst, b, h) do { _Pragma("unroll") for (int m = 0; m < 4; ++m) _Pragma("unroll") for (int k = 0; k < 2; ++k) dst[m][k] = *(const LAS bf16x8*)(lds + PG8_SA(b, h) + aoff + m * 2048 + k * 1024); } while (0)
; #define PG8_MMA(ai, bj, At, Bt) do { __builtin_amdgcn_s_setprio(1); _Pragma("unroll") for (int m = 0; m < 4; ++m) _Pragma("unroll") for (int n = 0; n < 2; ++n) _Pragma("unroll") for (int k = 0; k < 2; ++k) \
;         acc[ai][bj][m][n] = __builtin_amdgcn_mfma_f32_16x16x32_bf16(Bt[n][k], At[m][k], acc[ai][bj][m][n], 0, 0, 0); __builtin_amdgcn_s_setprio(0); } while (0)
; #define PG8_WAIT_V(n) asm volatile("s_waitcnt vmcnt(" #n ")" ::: "memory")
; #define PG8_WAIT_L(n) asm volatile("s_waitcnt lgkmcnt(" #n ")" ::: "memory")
; #define PG8_BAR __builtin_amdgcn_s_barrier()
; #define PG8_SCHED __builtin_amdgcn_sched_barrier(0)
; template <class Epi>
; __device__ __forceinline__ void gemm_phase(LAS unsigned char* lds, const Gemm g, const StaticOrder& S, const Epi& E) {
;     ...
;             PG8_LDA(At, 1, 1); PG8_STAGE(PG8_SB(1, 0), b3, voffB); PG8_STAGE(PG8_SB(1, 1), b3 + hsB, voffB); PG8_STAGE(PG8_SA(1, 0), a3, voffA);
;             PG8_WAIT_V(8); PG8_WAIT_L(0); PG8_BAR; PG8_MMA(1, 0, At, B0); PG8_MMA(1, 1, At, B1); PG8_BAR; PG8_SCHED;
;         }
;         if (wr == 0) PG8_BAR;
	s_add_i32 s26, s52, s16
	v_lshl_add_u64 v[176:177], v[176:177], 0, s[14:15]
	s_mov_b32 m0, s26
	ds_read_b128 v[216:219], v204 offset:49152
	ds_read_b128 v[220:223], v204 offset:50176
	ds_read_b128 v[224:227], v204 offset:51200
	ds_read_b128 v[228:231], v204 offset:52224
	ds_read_b128 v[232:235], v204 offset:53248
	ds_read_b128 v[236:239], v204 offset:54272
	ds_read_b128 v[240:243], v204 offset:55296
	ds_read_b128 v[244:247], v204 offset:56320
	global_load_lds_dwordx4 v[176:177], off
	s_add_i32 m0, s26, 0x2000
	s_add_u32 s26, s36, 0xb0080
	v_lshl_add_u64 v[176:177], v[248:249], 0, s[14:15]
	s_addc_u32 s27, s37, 0
	s_add_i32 s36, s53, s16
	global_load_lds_dwordx4 v[176:177], off
	v_lshl_add_u64 v[176:177], s[26:27], 0, v[130:131]
	s_mov_b32 m0, s36
	s_nop 0
	global_load_lds_dwordx4 v[176:177], off
	v_lshl_add_u64 v[176:177], s[26:27], 0, v[134:135]
	s_add_i32 m0, s36, 0x2000
	s_nop 0
	global_load_lds_dwordx4 v[176:177], off
	v_lshl_add_u64 v[176:177], v[250:251], 0, s[14:15]
	s_mov_b32 m0, s41
	s_nop 0
	global_load_lds_dwordx4 v[176:177], off
	v_lshl_add_u64 v[176:177], v[252:253], 0, s[14:15]
	s_mov_b32 m0, s42
	s_nop 0
	global_load_lds_dwordx4 v[176:177], off
	s_waitcnt vmcnt(8)
	s_waitcnt lgkmcnt(0)
	s_barrier
	s_setprio 1
	s_waitcnt lgkmcnt(0)
	v_mfma_f32_16x16x32_bf16 v[60:63], v[144:147], v[216:219], v[60:63]
	v_mfma_f32_16x16x32_bf16 v[56:59], v[152:155], v[216:219], v[56:59]
	v_mfma_f32_16x16x32_bf16 v[44:47], v[144:147], v[224:227], v[44:47]
	v_mfma_f32_16x16x32_bf16 v[40:43], v[152:155], v[224:227], v[40:43]
	v_mfma_f32_16x16x32_bf16 v[28:31], v[144:147], v[232:235], v[28:31]
	v_mfma_f32_16x16x32_bf16 v[24:27], v[152:155], v[232:235], v[24:27]
	v_mfma_f32_16x16x32_bf16 v[12:15], v[144:147], v[240:243], v[12:15]
	v_mfma_f32_16x16x32_bf16 v[8:11], v[152:155], v[240:243], v[8:11]
	v_mfma_f32_16x16x32_bf16 v[60:63], v[148:151], v[220:223], v[60:63]
	v_mfma_f32_16x16x32_bf16 v[56:59], v[156:159], v[220:223], v[56:59]
	v_mfma_f32_16x16x32_bf16 v[44:47], v[148:151], v[228:231], v[44:47]
	v_mfma_f32_16x16x32_bf16 v[40:43], v[156:159], v[228:231], v[40:43]
	v_mfma_f32_16x16x32_bf16 v[28:31], v[148:151], v[236:239], v[28:31]
	v_mfma_f32_16x16x32_bf16 v[24:27], v[156:159], v[236:239], v[24:27]
	v_mfma_f32_16x16x32_bf16 v[12:15], v[148:151], v[244:247], v[12:15]
	v_mfma_f32_16x16x32_bf16 v[8:11], v[156:159], v[244:247], v[8:11]
	s_setprio 0
	s_setprio 1
	v_mfma_f32_16x16x32_bf16 v[52:55], v[160:163], v[216:219], v[52:55]
	v_mfma_f32_16x16x32_bf16 v[48:51], v[168:171], v[216:219], v[48:51]
	v_mfma_f32_16x16x32_bf16 v[36:39], v[160:163], v[224:227], v[36:39]
	v_mfma_f32_16x16x32_bf16 v[32:35], v[168:171], v[224:227], v[32:35]
	v_mfma_f32_16x16x32_bf16 v[20:23], v[160:163], v[232:235], v[20:23]
	v_mfma_f32_16x16x32_bf16 v[16:19], v[168:171], v[232:235], v[16:19]
	v_mfma_f32_16x16x32_bf16 v[4:7], v[160:163], v[240:243], v[4:7]
	v_mfma_f32_16x16x32_bf16 v[0:3], v[168:171], v[240:243], v[0:3]
	v_mfma_f32_16x16x32_bf16 v[52:55], v[164:167], v[220:223], v[52:55]
	v_mfma_f32_16x16x32_bf16 v[48:51], v[172:175], v[220:223], v[48:51]
	v_mfma_f32_16x16x32_bf16 v[36:39], v[164:167], v[228:231], v[36:39]
	v_mfma_f32_16x16x32_bf16 v[32:35], v[172:175], v[228:231], v[32:35]
	v_mfma_f32_16x16x32_bf16 v[20:23], v[164:167], v[236:239], v[20:23]
	v_mfma_f32_16x16x32_bf16 v[16:19], v[172:175], v[236:239], v[16:19]
	v_mfma_f32_16x16x32_bf16 v[4:7], v[164:167], v[244:247], v[4:7]
	v_mfma_f32_16x16x32_bf16 v[0:3], v[172:175], v[244:247], v[0:3]
	s_setprio 3
	s_barrier
	s_add_i32 s51, s51, 2
	s_add_u32 s25, s25, 0x100
	s_addc_u32 s50, s50, 0
	s_cmp_gt_u32 s51, 41
	s_mov_b64 s[26:27], s[34:35]
	s_cbranch_scc0 .LBB0_1433
	s_and_b64 vcc, exec, s[18:19]
	s_cbranch_vccz .LBB0_1436
	s_barrier
